# adaLN silu staging: ten loads issued together instead of one dependent load per iteration; s5 ktab loop: rows preloaded with 32 dwordx4 loads and loop unrolled from registers
# speedup vs baseline: 1.0490x; 1.0084x over previous
.LBB0_456:
	v_readlane_b32 s0, v254, 0
	s_cmpk_lt_i32 s0, 0xc0
	s_cbranch_scc1 .LBB0_664
	v_readlane_b32 s4, v255, 6
	s_cmp_lt_u32 s4, 2
	s_cselect_b64 s[0:1], -1, 0
	v_readlane_b32 s42, v254, 0
	s_cmp_gt_u32 s4, 1
	s_mov_b64 s[4:5], -1
	s_cbranch_scc0 .LBB0_480
	v_mov_b32_e32 v46, v156
	s_movk_i32 s4, 0x13ff
	s_nop 0
	v_cmp_lt_i32_e32 vcc, s4, v46
	v_lshlrev_b32_e32 v47, 2, v46
	s_load_dwordx2 s[24:25], s[72:73], 0x10
	s_load_dwordx2 s[28:29], s[72:73], 0x30
	s_waitcnt vmcnt(0) lgkmcnt(0)
	global_load_dword v20, v47, s[28:29]
	global_load_dword v21, v47, s[28:29] offset:2048
	global_load_dword v22, v47, s[24:25]
	global_load_dword v23, v47, s[24:25] offset:2048
	s_add_u32 s24, s24, 0x1000
	s_addc_u32 s25, s25, 0
	global_load_dword v24, v47, s[24:25]
	global_load_dword v25, v47, s[24:25] offset:2048
	s_add_u32 s24, s24, 0x1000
	s_addc_u32 s25, s25, 0
	global_load_dword v26, v47, s[24:25]
	global_load_dword v27, v47, s[24:25] offset:2048
	s_add_u32 s24, s24, 0x1000
	s_addc_u32 s25, s25, 0
	global_load_dword v28, v47, s[24:25]
	global_load_dword v29, v47, s[24:25] offset:2048
	v_add_u32_e32 v2, 0, v47
	s_waitcnt vmcnt(9)
	v_mul_f32_e32 v1, 0xbfb8aa3b, v20
	v_exp_f32_e32 v1, v1
	s_nop 0
	v_add_f32_e32 v1, 1.0, v1
	v_div_scale_f32 v4, vcc, v1, v1, v20
	v_rcp_f32_e32 v5, v4
	s_nop 0
	v_fma_f32 v6, -v4, v5, 1.0
	v_fmac_f32_e32 v5, v6, v5
	v_div_scale_f32 v6, vcc, v20, v1, v20
	v_mul_f32_e32 v7, v6, v5
	v_fma_f32 v8, -v4, v7, v6
	v_fmac_f32_e32 v7, v8, v5
	v_fma_f32 v4, -v4, v7, v6
	v_div_fmas_f32 v4, v4, v5, v7
	v_div_fixup_f32 v0, v4, v1, v20
	ds_write_b32 v2, v0 offset:0
	s_waitcnt vmcnt(8)
	v_mul_f32_e32 v1, 0xbfb8aa3b, v21
	v_exp_f32_e32 v1, v1
	s_nop 0
	v_add_f32_e32 v1, 1.0, v1
	v_div_scale_f32 v4, vcc, v1, v1, v21
	v_rcp_f32_e32 v5, v4
	s_nop 0
	v_fma_f32 v6, -v4, v5, 1.0
	v_fmac_f32_e32 v5, v6, v5
	v_div_scale_f32 v6, vcc, v21, v1, v21
	v_mul_f32_e32 v7, v6, v5
	v_fma_f32 v8, -v4, v7, v6
	v_fmac_f32_e32 v7, v8, v5
	v_fma_f32 v4, -v4, v7, v6
	v_div_fmas_f32 v4, v4, v5, v7
	v_div_fixup_f32 v0, v4, v1, v21
	ds_write_b32 v2, v0 offset:2048
	s_waitcnt vmcnt(7)
	v_mul_f32_e32 v1, 0xbfb8aa3b, v22
	v_exp_f32_e32 v1, v1
	s_nop 0
	v_add_f32_e32 v1, 1.0, v1
	v_div_scale_f32 v4, vcc, v1, v1, v22
	v_rcp_f32_e32 v5, v4
	s_nop 0
	v_fma_f32 v6, -v4, v5, 1.0
	v_fmac_f32_e32 v5, v6, v5
	v_div_scale_f32 v6, vcc, v22, v1, v22
	v_mul_f32_e32 v7, v6, v5
	v_fma_f32 v8, -v4, v7, v6
	v_fmac_f32_e32 v7, v8, v5
	v_fma_f32 v4, -v4, v7, v6
	v_div_fmas_f32 v4, v4, v5, v7
	v_div_fixup_f32 v0, v4, v1, v22
	ds_write_b32 v2, v0 offset:4096
	s_waitcnt vmcnt(6)
	v_mul_f32_e32 v1, 0xbfb8aa3b, v23
	v_exp_f32_e32 v1, v1
	s_nop 0
	v_add_f32_e32 v1, 1.0, v1
	v_div_scale_f32 v4, vcc, v1, v1, v23
	v_rcp_f32_e32 v5, v4
	s_nop 0
	v_fma_f32 v6, -v4, v5, 1.0
	v_fmac_f32_e32 v5, v6, v5
	v_div_scale_f32 v6, vcc, v23, v1, v23
	v_mul_f32_e32 v7, v6, v5
	v_fma_f32 v8, -v4, v7, v6
	v_fmac_f32_e32 v7, v8, v5
	v_fma_f32 v4, -v4, v7, v6
	v_div_fmas_f32 v4, v4, v5, v7
	v_div_fixup_f32 v0, v4, v1, v23
	ds_write_b32 v2, v0 offset:6144
	s_waitcnt vmcnt(5)
	v_mul_f32_e32 v1, 0xbfb8aa3b, v24
	v_exp_f32_e32 v1, v1
	s_nop 0
	v_add_f32_e32 v1, 1.0, v1
	v_div_scale_f32 v4, vcc, v1, v1, v24
	v_rcp_f32_e32 v5, v4
	s_nop 0
	v_fma_f32 v6, -v4, v5, 1.0
	v_fmac_f32_e32 v5, v6, v5
	v_div_scale_f32 v6, vcc, v24, v1, v24
	v_mul_f32_e32 v7, v6, v5
	v_fma_f32 v8, -v4, v7, v6
	v_fmac_f32_e32 v7, v8, v5
	v_fma_f32 v4, -v4, v7, v6
	v_div_fmas_f32 v4, v4, v5, v7
	v_div_fixup_f32 v0, v4, v1, v24
	ds_write_b32 v2, v0 offset:8192
	s_waitcnt vmcnt(4)
	v_mul_f32_e32 v1, 0xbfb8aa3b, v25
	v_exp_f32_e32 v1, v1
	s_nop 0
	v_add_f32_e32 v1, 1.0, v1
	v_div_scale_f32 v4, vcc, v1, v1, v25
	v_rcp_f32_e32 v5, v4
	s_nop 0
	v_fma_f32 v6, -v4, v5, 1.0
	v_fmac_f32_e32 v5, v6, v5
	v_div_scale_f32 v6, vcc, v25, v1, v25
	v_mul_f32_e32 v7, v6, v5
	v_fma_f32 v8, -v4, v7, v6
	v_fmac_f32_e32 v7, v8, v5
	v_fma_f32 v4, -v4, v7, v6
	v_div_fmas_f32 v4, v4, v5, v7
	v_div_fixup_f32 v0, v4, v1, v25
	ds_write_b32 v2, v0 offset:10240
	s_waitcnt vmcnt(3)
	v_mul_f32_e32 v1, 0xbfb8aa3b, v26
	v_exp_f32_e32 v1, v1
	s_nop 0
	v_add_f32_e32 v1, 1.0, v1
	v_div_scale_f32 v4, vcc, v1, v1, v26
	v_rcp_f32_e32 v5, v4
	s_nop 0
	v_fma_f32 v6, -v4, v5, 1.0
	v_fmac_f32_e32 v5, v6, v5
	v_div_scale_f32 v6, vcc, v26, v1, v26
	v_mul_f32_e32 v7, v6, v5
	v_fma_f32 v8, -v4, v7, v6
	v_fmac_f32_e32 v7, v8, v5
	v_fma_f32 v4, -v4, v7, v6
	v_div_fmas_f32 v4, v4, v5, v7
	v_div_fixup_f32 v0, v4, v1, v26
	ds_write_b32 v2, v0 offset:12288
	s_waitcnt vmcnt(2)
	v_mul_f32_e32 v1, 0xbfb8aa3b, v27
	v_exp_f32_e32 v1, v1
	s_nop 0
	v_add_f32_e32 v1, 1.0, v1
	v_div_scale_f32 v4, vcc, v1, v1, v27
	v_rcp_f32_e32 v5, v4
	s_nop 0
	v_fma_f32 v6, -v4, v5, 1.0
	v_fmac_f32_e32 v5, v6, v5
	v_div_scale_f32 v6, vcc, v27, v1, v27
	v_mul_f32_e32 v7, v6, v5
	v_fma_f32 v8, -v4, v7, v6
	v_fmac_f32_e32 v7, v8, v5
	v_fma_f32 v4, -v4, v7, v6
	v_div_fmas_f32 v4, v4, v5, v7
	v_div_fixup_f32 v0, v4, v1, v27
	ds_write_b32 v2, v0 offset:14336
	s_waitcnt vmcnt(1)
	v_mul_f32_e32 v1, 0xbfb8aa3b, v28
	v_exp_f32_e32 v1, v1
	s_nop 0
	v_add_f32_e32 v1, 1.0, v1
	v_div_scale_f32 v4, vcc, v1, v1, v28
	v_rcp_f32_e32 v5, v4
	s_nop 0
	v_fma_f32 v6, -v4, v5, 1.0
	v_fmac_f32_e32 v5, v6, v5
	v_div_scale_f32 v6, vcc, v28, v1, v28
	v_mul_f32_e32 v7, v6, v5
	v_fma_f32 v8, -v4, v7, v6
	v_fmac_f32_e32 v7, v8, v5
	v_fma_f32 v4, -v4, v7, v6
	v_div_fmas_f32 v4, v4, v5, v7
	v_div_fixup_f32 v0, v4, v1, v28
	ds_write_b32 v2, v0 offset:16384
	s_waitcnt vmcnt(0)
	v_mul_f32_e32 v1, 0xbfb8aa3b, v29
	v_exp_f32_e32 v1, v1
	s_nop 0
	v_add_f32_e32 v1, 1.0, v1
	v_div_scale_f32 v4, vcc, v1, v1, v29
	v_rcp_f32_e32 v5, v4
	s_nop 0
	v_fma_f32 v6, -v4, v5, 1.0
	v_fmac_f32_e32 v5, v6, v5
	v_div_scale_f32 v6, vcc, v29, v1, v29
	v_mul_f32_e32 v7, v6, v5
	v_fma_f32 v8, -v4, v7, v6
	v_fmac_f32_e32 v7, v8, v5
	v_fma_f32 v4, -v4, v7, v6
	v_div_fmas_f32 v4, v4, v5, v7
	v_div_fixup_f32 v0, v4, v1, v29
	ds_write_b32 v2, v0 offset:18432
.LBB0_468:
	s_add_i32 s4, s42, 0x80
	s_mul_hi_i32 s5, s4, 0x2aaaaaab
	s_lshr_b32 s24, s5, 31
	s_ashr_i32 s30, s5, 4
	s_add_i32 s30, s30, s24
	s_mul_i32 s5, s30, 0x60
	s_sub_i32 s4, s4, s5
	v_ashrrev_i32_e32 v48, 4, v46
	s_lshl_b32 s4, s4, 6
	s_movk_i32 s24, 0x400
	s_waitcnt vmcnt(0)
	v_mov_b32_e32 v3, 0
	s_ashr_i32 s5, s4, 31
	v_cmp_gt_i32_e32 vcc, s24, v48
	v_mov_b32_e32 v2, v3
	v_mov_b32_e32 v1, v3
	v_mov_b32_e32 v0, v3
	v_mov_b32_e32 v7, v3
	v_mov_b32_e32 v6, v3
	v_mov_b32_e32 v5, v3
	v_mov_b32_e32 v4, v3
	v_mov_b32_e32 v11, v3
	v_mov_b32_e32 v10, v3
	v_mov_b32_e32 v9, v3
	v_mov_b32_e32 v8, v3
	v_mov_b32_e32 v15, v3
	v_mov_b32_e32 v14, v3
	v_mov_b32_e32 v13, v3
	v_mov_b32_e32 v12, v3
	v_mov_b32_e32 v19, v3
	v_mov_b32_e32 v18, v3
	v_mov_b32_e32 v17, v3
	v_mov_b32_e32 v16, v3
	s_waitcnt vmcnt(0) lgkmcnt(0)
	s_barrier
	s_and_saveexec_b64 s[24:25], vcc
	s_cbranch_execz .LBB0_472
	s_load_dwordx2 s[28:29], s[72:73], 0x38
	s_movk_i32 s31, 0x6000
	v_mad_i64_i32 v[0:1], s[40:41], v48, s31, 0
	v_mad_i64_i32 v[0:1], s[40:41], s30, v167, v[0:1]
	s_lshl_b64 s[40:41], s[4:5], 2
	v_and_b32_e32 v2, 15, v46
	s_waitcnt lgkmcnt(0)
	s_add_u32 s28, s28, s40
	v_lshl_or_b32 v0, v2, 4, v0
	s_addc_u32 s29, s29, s41
	v_lshl_add_u64 v[0:1], s[28:29], 0, v[0:1]
	s_mov_b64 s[28:29], 0x540000
	v_mov_b32_e32 v16, 0
	v_add_u32_e32 v49, 0xffffff00, v48
	v_lshl_add_u32 v50, v48, 2, 0
	v_lshl_add_u64 v[44:45], v[0:1], 0, s[28:29]
	s_mov_b64 s[28:29], 0
	v_mov_b32_e32 v17, v16
	v_mov_b32_e32 v18, v16
	v_mov_b32_e32 v19, v16
	v_mov_b32_e32 v12, v16
	v_mov_b32_e32 v13, v16
	v_mov_b32_e32 v14, v16
	v_mov_b32_e32 v15, v16
	v_mov_b32_e32 v8, v16
	v_mov_b32_e32 v9, v16
	v_mov_b32_e32 v10, v16
	v_mov_b32_e32 v11, v16
	v_mov_b32_e32 v4, v16
	v_mov_b32_e32 v5, v16
	v_mov_b32_e32 v6, v16
	v_mov_b32_e32 v7, v16
	v_mov_b32_e32 v0, v16
	v_mov_b32_e32 v1, v16
	v_mov_b32_e32 v2, v16
	v_mov_b32_e32 v3, v16

.LBB0_485:
	v_mov_b32_e32 v46, v156
	s_movk_i32 s28, 0x13ff
	s_nop 0
	v_cmp_lt_i32_e32 vcc, s28, v46
	v_lshlrev_b32_e32 v47, 2, v46
	s_load_dwordx2 s[30:31], s[72:73], 0x10
	s_load_dwordx2 s[40:41], s[72:73], 0x30
	s_waitcnt vmcnt(0) lgkmcnt(0)
	global_load_dword v20, v47, s[40:41]
	global_load_dword v21, v47, s[40:41] offset:2048
	global_load_dword v22, v47, s[30:31]
	global_load_dword v23, v47, s[30:31] offset:2048
	s_add_u32 s30, s30, 0x1000
	s_addc_u32 s31, s31, 0
	global_load_dword v24, v47, s[30:31]
	global_load_dword v25, v47, s[30:31] offset:2048
	s_add_u32 s30, s30, 0x1000
	s_addc_u32 s31, s31, 0
	global_load_dword v26, v47, s[30:31]
	global_load_dword v27, v47, s[30:31] offset:2048
	s_add_u32 s30, s30, 0x1000
	s_addc_u32 s31, s31, 0
	global_load_dword v28, v47, s[30:31]
	global_load_dword v29, v47, s[30:31] offset:2048
	v_add_u32_e32 v2, 0, v47
	s_waitcnt vmcnt(9)
	v_mul_f32_e32 v1, 0xbfb8aa3b, v20
	v_exp_f32_e32 v1, v1
	s_nop 0
	v_add_f32_e32 v1, 1.0, v1
	v_div_scale_f32 v4, vcc, v1, v1, v20
	v_rcp_f32_e32 v5, v4
	s_nop 0
	v_fma_f32 v6, -v4, v5, 1.0
	v_fmac_f32_e32 v5, v6, v5
	v_div_scale_f32 v6, vcc, v20, v1, v20
	v_mul_f32_e32 v7, v6, v5
	v_fma_f32 v8, -v4, v7, v6
	v_fmac_f32_e32 v7, v8, v5
	v_fma_f32 v4, -v4, v7, v6
	v_div_fmas_f32 v4, v4, v5, v7
	v_div_fixup_f32 v0, v4, v1, v20
	ds_write_b32 v2, v0 offset:0
	s_waitcnt vmcnt(8)
	v_mul_f32_e32 v1, 0xbfb8aa3b, v21
	v_exp_f32_e32 v1, v1
	s_nop 0
	v_add_f32_e32 v1, 1.0, v1
	v_div_scale_f32 v4, vcc, v1, v1, v21
	v_rcp_f32_e32 v5, v4
	s_nop 0
	v_fma_f32 v6, -v4, v5, 1.0
	v_fmac_f32_e32 v5, v6, v5
	v_div_scale_f32 v6, vcc, v21, v1, v21
	v_mul_f32_e32 v7, v6, v5
	v_fma_f32 v8, -v4, v7, v6
	v_fmac_f32_e32 v7, v8, v5
	v_fma_f32 v4, -v4, v7, v6
	v_div_fmas_f32 v4, v4, v5, v7
	v_div_fixup_f32 v0, v4, v1, v21
	ds_write_b32 v2, v0 offset:2048
	s_waitcnt vmcnt(7)
	v_mul_f32_e32 v1, 0xbfb8aa3b, v22
	v_exp_f32_e32 v1, v1
	s_nop 0
	v_add_f32_e32 v1, 1.0, v1
	v_div_scale_f32 v4, vcc, v1, v1, v22
	v_rcp_f32_e32 v5, v4
	s_nop 0
	v_fma_f32 v6, -v4, v5, 1.0
	v_fmac_f32_e32 v5, v6, v5
	v_div_scale_f32 v6, vcc, v22, v1, v22
	v_mul_f32_e32 v7, v6, v5
	v_fma_f32 v8, -v4, v7, v6
	v_fmac_f32_e32 v7, v8, v5
	v_fma_f32 v4, -v4, v7, v6
	v_div_fmas_f32 v4, v4, v5, v7
	v_div_fixup_f32 v0, v4, v1, v22
	ds_write_b32 v2, v0 offset:4096
	s_waitcnt vmcnt(6)
	v_mul_f32_e32 v1, 0xbfb8aa3b, v23
	v_exp_f32_e32 v1, v1
	s_nop 0
	v_add_f32_e32 v1, 1.0, v1
	v_div_scale_f32 v4, vcc, v1, v1, v23
	v_rcp_f32_e32 v5, v4
	s_nop 0
	v_fma_f32 v6, -v4, v5, 1.0
	v_fmac_f32_e32 v5, v6, v5
	v_div_scale_f32 v6, vcc, v23, v1, v23
	v_mul_f32_e32 v7, v6, v5
	v_fma_f32 v8, -v4, v7, v6
	v_fmac_f32_e32 v7, v8, v5
	v_fma_f32 v4, -v4, v7, v6
	v_div_fmas_f32 v4, v4, v5, v7
	v_div_fixup_f32 v0, v4, v1, v23
	ds_write_b32 v2, v0 offset:6144
	s_waitcnt vmcnt(5)
	v_mul_f32_e32 v1, 0xbfb8aa3b, v24
	v_exp_f32_e32 v1, v1
	s_nop 0
	v_add_f32_e32 v1, 1.0, v1
	v_div_scale_f32 v4, vcc, v1, v1, v24
	v_rcp_f32_e32 v5, v4
	s_nop 0
	v_fma_f32 v6, -v4, v5, 1.0
	v_fmac_f32_e32 v5, v6, v5
	v_div_scale_f32 v6, vcc, v24, v1, v24
	v_mul_f32_e32 v7, v6, v5
	v_fma_f32 v8, -v4, v7, v6
	v_fmac_f32_e32 v7, v8, v5
	v_fma_f32 v4, -v4, v7, v6
	v_div_fmas_f32 v4, v4, v5, v7
	v_div_fixup_f32 v0, v4, v1, v24
	ds_write_b32 v2, v0 offset:8192
	s_waitcnt vmcnt(4)
	v_mul_f32_e32 v1, 0xbfb8aa3b, v25
	v_exp_f32_e32 v1, v1
	s_nop 0
	v_add_f32_e32 v1, 1.0, v1
	v_div_scale_f32 v4, vcc, v1, v1, v25
	v_rcp_f32_e32 v5, v4
	s_nop 0
	v_fma_f32 v6, -v4, v5, 1.0
	v_fmac_f32_e32 v5, v6, v5
	v_div_scale_f32 v6, vcc, v25, v1, v25
	v_mul_f32_e32 v7, v6, v5
	v_fma_f32 v8, -v4, v7, v6
	v_fmac_f32_e32 v7, v8, v5
	v_fma_f32 v4, -v4, v7, v6
	v_div_fmas_f32 v4, v4, v5, v7
	v_div_fixup_f32 v0, v4, v1, v25
	ds_write_b32 v2, v0 offset:10240
	s_waitcnt vmcnt(3)
	v_mul_f32_e32 v1, 0xbfb8aa3b, v26
	v_exp_f32_e32 v1, v1
	s_nop 0
	v_add_f32_e32 v1, 1.0, v1
	v_div_scale_f32 v4, vcc, v1, v1, v26
	v_rcp_f32_e32 v5, v4
	s_nop 0
	v_fma_f32 v6, -v4, v5, 1.0
	v_fmac_f32_e32 v5, v6, v5
	v_div_scale_f32 v6, vcc, v26, v1, v26
	v_mul_f32_e32 v7, v6, v5
	v_fma_f32 v8, -v4, v7, v6
	v_fmac_f32_e32 v7, v8, v5
	v_fma_f32 v4, -v4, v7, v6
	v_div_fmas_f32 v4, v4, v5, v7
	v_div_fixup_f32 v0, v4, v1, v26
	ds_write_b32 v2, v0 offset:12288
	s_waitcnt vmcnt(2)
	v_mul_f32_e32 v1, 0xbfb8aa3b, v27
	v_exp_f32_e32 v1, v1
	s_nop 0
	v_add_f32_e32 v1, 1.0, v1
	v_div_scale_f32 v4, vcc, v1, v1, v27
	v_rcp_f32_e32 v5, v4
	s_nop 0
	v_fma_f32 v6, -v4, v5, 1.0
	v_fmac_f32_e32 v5, v6, v5
	v_div_scale_f32 v6, vcc, v27, v1, v27
	v_mul_f32_e32 v7, v6, v5
	v_fma_f32 v8, -v4, v7, v6
	v_fmac_f32_e32 v7, v8, v5
	v_fma_f32 v4, -v4, v7, v6
	v_div_fmas_f32 v4, v4, v5, v7
	v_div_fixup_f32 v0, v4, v1, v27
	ds_write_b32 v2, v0 offset:14336
	s_waitcnt vmcnt(1)
	v_mul_f32_e32 v1, 0xbfb8aa3b, v28
	v_exp_f32_e32 v1, v1
	s_nop 0
	v_add_f32_e32 v1, 1.0, v1
	v_div_scale_f32 v4, vcc, v1, v1, v28
	v_rcp_f32_e32 v5, v4
	s_nop 0
	v_fma_f32 v6, -v4, v5, 1.0
	v_fmac_f32_e32 v5, v6, v5
	v_div_scale_f32 v6, vcc, v28, v1, v28
	v_mul_f32_e32 v7, v6, v5
	v_fma_f32 v8, -v4, v7, v6
	v_fmac_f32_e32 v7, v8, v5
	v_fma_f32 v4, -v4, v7, v6
	v_div_fmas_f32 v4, v4, v5, v7
	v_div_fixup_f32 v0, v4, v1, v28
	ds_write_b32 v2, v0 offset:16384
	s_waitcnt vmcnt(0)
	v_mul_f32_e32 v1, 0xbfb8aa3b, v29
	v_exp_f32_e32 v1, v1
	s_nop 0
	v_add_f32_e32 v1, 1.0, v1
	v_div_scale_f32 v4, vcc, v1, v1, v29
	v_rcp_f32_e32 v5, v4
	s_nop 0
	v_fma_f32 v6, -v4, v5, 1.0
	v_fmac_f32_e32 v5, v6, v5
	v_div_scale_f32 v6, vcc, v29, v1, v29
	v_mul_f32_e32 v7, v6, v5
	v_fma_f32 v8, -v4, v7, v6
	v_fmac_f32_e32 v7, v8, v5
	v_fma_f32 v4, -v4, v7, v6
	v_div_fmas_f32 v4, v4, v5, v7
	v_div_fixup_f32 v0, v4, v1, v29
	ds_write_b32 v2, v0 offset:18432
.LBB0_495:
	s_add_i32 s28, s43, 0xc0
	s_mul_hi_i32 s29, s28, 0x2aaaaaab
	s_lshr_b32 s30, s29, 31
	s_ashr_i32 s44, s29, 4
	s_add_i32 s44, s44, s30
	s_mul_i32 s29, s44, 0x60
	s_sub_i32 s28, s28, s29
	v_ashrrev_i32_e32 v48, 4, v46
	s_lshl_b32 s28, s28, 6
	s_movk_i32 s30, 0x400
	s_waitcnt vmcnt(0)
	v_mov_b32_e32 v3, 0
	s_ashr_i32 s29, s28, 31
	v_cmp_gt_i32_e32 vcc, s30, v48
	v_mov_b32_e32 v2, v3
	v_mov_b32_e32 v1, v3
	v_mov_b32_e32 v0, v3
	v_mov_b32_e32 v7, v3
	v_mov_b32_e32 v6, v3
	v_mov_b32_e32 v5, v3
	v_mov_b32_e32 v4, v3
	v_mov_b32_e32 v11, v3
	v_mov_b32_e32 v10, v3
	v_mov_b32_e32 v9, v3
	v_mov_b32_e32 v8, v3
	v_mov_b32_e32 v15, v3
	v_mov_b32_e32 v14, v3
	v_mov_b32_e32 v13, v3
	v_mov_b32_e32 v12, v3
	v_mov_b32_e32 v19, v3
	v_mov_b32_e32 v18, v3
	v_mov_b32_e32 v17, v3
	v_mov_b32_e32 v16, v3
	s_waitcnt vmcnt(0) lgkmcnt(0)
	s_barrier
	s_and_saveexec_b64 s[30:31], vcc
	s_cbranch_execz .LBB0_499
	s_load_dwordx2 s[40:41], s[72:73], 0x38
	s_movk_i32 s45, 0x6000
	v_mad_i64_i32 v[0:1], s[46:47], v48, s45, 0
	v_mad_i64_i32 v[0:1], s[46:47], s44, v167, v[0:1]
	s_lshl_b64 s[46:47], s[28:29], 2
	v_and_b32_e32 v2, 15, v46
	s_waitcnt lgkmcnt(0)
	s_add_u32 s40, s40, s46
	v_lshl_or_b32 v0, v2, 4, v0
	s_addc_u32 s41, s41, s47
	v_lshl_add_u64 v[0:1], s[40:41], 0, v[0:1]
	s_mov_b64 s[40:41], 0x540000
	v_mov_b32_e32 v16, 0
	v_add_u32_e32 v49, 0xffffff00, v48
	v_lshl_add_u32 v50, v48, 2, 0
	v_lshl_add_u64 v[44:45], v[0:1], 0, s[40:41]
	s_mov_b64 s[40:41], 0
	v_mov_b32_e32 v17, v16
	v_mov_b32_e32 v18, v16
	v_mov_b32_e32 v19, v16
	v_mov_b32_e32 v12, v16
	v_mov_b32_e32 v13, v16
	v_mov_b32_e32 v14, v16
	v_mov_b32_e32 v15, v16
	v_mov_b32_e32 v8, v16
	v_mov_b32_e32 v9, v16
	v_mov_b32_e32 v10, v16
	v_mov_b32_e32 v11, v16
	v_mov_b32_e32 v4, v16
	v_mov_b32_e32 v5, v16
	v_mov_b32_e32 v6, v16
	v_mov_b32_e32 v7, v16
	v_mov_b32_e32 v0, v16
	v_mov_b32_e32 v1, v16
	v_mov_b32_e32 v2, v16
	v_mov_b32_e32 v3, v16

.LBB0_1170:
	v_mov_b32_e32 v47, v156
	s_movk_i32 s0, 0x13ff
	s_nop 0
	v_cmp_lt_i32_e32 vcc, s0, v47
	v_lshlrev_b32_e32 v48, 2, v47
	s_load_dwordx2 s[4:5], s[72:73], 0x10
	s_load_dwordx2 s[24:25], s[72:73], 0x30
	s_waitcnt vmcnt(0) lgkmcnt(0)
	global_load_dword v20, v48, s[24:25]
	global_load_dword v21, v48, s[24:25] offset:2048
	global_load_dword v22, v48, s[4:5]
	global_load_dword v23, v48, s[4:5] offset:2048
	s_add_u32 s4, s4, 0x1000
	s_addc_u32 s5, s5, 0
	global_load_dword v24, v48, s[4:5]
	global_load_dword v25, v48, s[4:5] offset:2048
	s_add_u32 s4, s4, 0x1000
	s_addc_u32 s5, s5, 0
	global_load_dword v26, v48, s[4:5]
	global_load_dword v27, v48, s[4:5] offset:2048
	s_add_u32 s4, s4, 0x1000
	s_addc_u32 s5, s5, 0
	global_load_dword v28, v48, s[4:5]
	global_load_dword v29, v48, s[4:5] offset:2048
	v_add_u32_e32 v2, 0, v48
	s_waitcnt vmcnt(9)
	v_mul_f32_e32 v1, 0xbfb8aa3b, v20
	v_exp_f32_e32 v1, v1
	s_nop 0
	v_add_f32_e32 v1, 1.0, v1
	v_div_scale_f32 v4, vcc, v1, v1, v20
	v_rcp_f32_e32 v5, v4
	s_nop 0
	v_fma_f32 v6, -v4, v5, 1.0
	v_fmac_f32_e32 v5, v6, v5
	v_div_scale_f32 v6, vcc, v20, v1, v20
	v_mul_f32_e32 v7, v6, v5
	v_fma_f32 v8, -v4, v7, v6
	v_fmac_f32_e32 v7, v8, v5
	v_fma_f32 v4, -v4, v7, v6
	v_div_fmas_f32 v4, v4, v5, v7
	v_div_fixup_f32 v0, v4, v1, v20
	ds_write_b32 v2, v0 offset:0
	s_waitcnt vmcnt(8)
	v_mul_f32_e32 v1, 0xbfb8aa3b, v21
	v_exp_f32_e32 v1, v1
	s_nop 0
	v_add_f32_e32 v1, 1.0, v1
	v_div_scale_f32 v4, vcc, v1, v1, v21
	v_rcp_f32_e32 v5, v4
	s_nop 0
	v_fma_f32 v6, -v4, v5, 1.0
	v_fmac_f32_e32 v5, v6, v5
	v_div_scale_f32 v6, vcc, v21, v1, v21
	v_mul_f32_e32 v7, v6, v5
	v_fma_f32 v8, -v4, v7, v6
	v_fmac_f32_e32 v7, v8, v5
	v_fma_f32 v4, -v4, v7, v6
	v_div_fmas_f32 v4, v4, v5, v7
	v_div_fixup_f32 v0, v4, v1, v21
	ds_write_b32 v2, v0 offset:2048
	s_waitcnt vmcnt(7)
	v_mul_f32_e32 v1, 0xbfb8aa3b, v22
	v_exp_f32_e32 v1, v1
	s_nop 0
	v_add_f32_e32 v1, 1.0, v1
	v_div_scale_f32 v4, vcc, v1, v1, v22
	v_rcp_f32_e32 v5, v4
	s_nop 0
	v_fma_f32 v6, -v4, v5, 1.0
	v_fmac_f32_e32 v5, v6, v5
	v_div_scale_f32 v6, vcc, v22, v1, v22
	v_mul_f32_e32 v7, v6, v5
	v_fma_f32 v8, -v4, v7, v6
	v_fmac_f32_e32 v7, v8, v5
	v_fma_f32 v4, -v4, v7, v6
	v_div_fmas_f32 v4, v4, v5, v7
	v_div_fixup_f32 v0, v4, v1, v22
	ds_write_b32 v2, v0 offset:4096
	s_waitcnt vmcnt(6)
	v_mul_f32_e32 v1, 0xbfb8aa3b, v23
	v_exp_f32_e32 v1, v1
	s_nop 0
	v_add_f32_e32 v1, 1.0, v1
	v_div_scale_f32 v4, vcc, v1, v1, v23
	v_rcp_f32_e32 v5, v4
	s_nop 0
	v_fma_f32 v6, -v4, v5, 1.0
	v_fmac_f32_e32 v5, v6, v5
	v_div_scale_f32 v6, vcc, v23, v1, v23
	v_mul_f32_e32 v7, v6, v5
	v_fma_f32 v8, -v4, v7, v6
	v_fmac_f32_e32 v7, v8, v5
	v_fma_f32 v4, -v4, v7, v6
	v_div_fmas_f32 v4, v4, v5, v7
	v_div_fixup_f32 v0, v4, v1, v23
	ds_write_b32 v2, v0 offset:6144
	s_waitcnt vmcnt(5)
	v_mul_f32_e32 v1, 0xbfb8aa3b, v24
	v_exp_f32_e32 v1, v1
	s_nop 0
	v_add_f32_e32 v1, 1.0, v1
	v_div_scale_f32 v4, vcc, v1, v1, v24
	v_rcp_f32_e32 v5, v4
	s_nop 0
	v_fma_f32 v6, -v4, v5, 1.0
	v_fmac_f32_e32 v5, v6, v5
	v_div_scale_f32 v6, vcc, v24, v1, v24
	v_mul_f32_e32 v7, v6, v5
	v_fma_f32 v8, -v4, v7, v6
	v_fmac_f32_e32 v7, v8, v5
	v_fma_f32 v4, -v4, v7, v6
	v_div_fmas_f32 v4, v4, v5, v7
	v_div_fixup_f32 v0, v4, v1, v24
	ds_write_b32 v2, v0 offset:8192
	s_waitcnt vmcnt(4)
	v_mul_f32_e32 v1, 0xbfb8aa3b, v25
	v_exp_f32_e32 v1, v1
	s_nop 0
	v_add_f32_e32 v1, 1.0, v1
	v_div_scale_f32 v4, vcc, v1, v1, v25
	v_rcp_f32_e32 v5, v4
	s_nop 0
	v_fma_f32 v6, -v4, v5, 1.0
	v_fmac_f32_e32 v5, v6, v5
	v_div_scale_f32 v6, vcc, v25, v1, v25
	v_mul_f32_e32 v7, v6, v5
	v_fma_f32 v8, -v4, v7, v6
	v_fmac_f32_e32 v7, v8, v5
	v_fma_f32 v4, -v4, v7, v6
	v_div_fmas_f32 v4, v4, v5, v7
	v_div_fixup_f32 v0, v4, v1, v25
	ds_write_b32 v2, v0 offset:10240
	s_waitcnt vmcnt(3)
	v_mul_f32_e32 v1, 0xbfb8aa3b, v26
	v_exp_f32_e32 v1, v1
	s_nop 0
	v_add_f32_e32 v1, 1.0, v1
	v_div_scale_f32 v4, vcc, v1, v1, v26
	v_rcp_f32_e32 v5, v4
	s_nop 0
	v_fma_f32 v6, -v4, v5, 1.0
	v_fmac_f32_e32 v5, v6, v5
	v_div_scale_f32 v6, vcc, v26, v1, v26
	v_mul_f32_e32 v7, v6, v5
	v_fma_f32 v8, -v4, v7, v6
	v_fmac_f32_e32 v7, v8, v5
	v_fma_f32 v4, -v4, v7, v6
	v_div_fmas_f32 v4, v4, v5, v7
	v_div_fixup_f32 v0, v4, v1, v26
	ds_write_b32 v2, v0 offset:12288
	s_waitcnt vmcnt(2)
	v_mul_f32_e32 v1, 0xbfb8aa3b, v27
	v_exp_f32_e32 v1, v1
	s_nop 0
	v_add_f32_e32 v1, 1.0, v1
	v_div_scale_f32 v4, vcc, v1, v1, v27
	v_rcp_f32_e32 v5, v4
	s_nop 0
	v_fma_f32 v6, -v4, v5, 1.0
	v_fmac_f32_e32 v5, v6, v5
	v_div_scale_f32 v6, vcc, v27, v1, v27
	v_mul_f32_e32 v7, v6, v5
	v_fma_f32 v8, -v4, v7, v6
	v_fmac_f32_e32 v7, v8, v5
	v_fma_f32 v4, -v4, v7, v6
	v_div_fmas_f32 v4, v4, v5, v7
	v_div_fixup_f32 v0, v4, v1, v27
	ds_write_b32 v2, v0 offset:14336
	s_waitcnt vmcnt(1)
	v_mul_f32_e32 v1, 0xbfb8aa3b, v28
	v_exp_f32_e32 v1, v1
	s_nop 0
	v_add_f32_e32 v1, 1.0, v1
	v_div_scale_f32 v4, vcc, v1, v1, v28
	v_rcp_f32_e32 v5, v4
	s_nop 0
	v_fma_f32 v6, -v4, v5, 1.0
	v_fmac_f32_e32 v5, v6, v5
	v_div_scale_f32 v6, vcc, v28, v1, v28
	v_mul_f32_e32 v7, v6, v5
	v_fma_f32 v8, -v4, v7, v6
	v_fmac_f32_e32 v7, v8, v5
	v_fma_f32 v4, -v4, v7, v6
	v_div_fmas_f32 v4, v4, v5, v7
	v_div_fixup_f32 v0, v4, v1, v28
	ds_write_b32 v2, v0 offset:16384
	s_waitcnt vmcnt(0)
	v_mul_f32_e32 v1, 0xbfb8aa3b, v29
	v_exp_f32_e32 v1, v1
	s_nop 0
	v_add_f32_e32 v1, 1.0, v1
	v_div_scale_f32 v4, vcc, v1, v1, v29
	v_rcp_f32_e32 v5, v4
	s_nop 0
	v_fma_f32 v6, -v4, v5, 1.0
	v_fmac_f32_e32 v5, v6, v5
	v_div_scale_f32 v6, vcc, v29, v1, v29
	v_mul_f32_e32 v7, v6, v5
	v_fma_f32 v8, -v4, v7, v6
	v_fmac_f32_e32 v7, v8, v5
	v_fma_f32 v4, -v4, v7, v6
	v_div_fmas_f32 v4, v4, v5, v7
	v_div_fixup_f32 v0, v4, v1, v29
	ds_write_b32 v2, v0 offset:18432
.LBB0_1180:
	s_mul_hi_i32 s0, s28, 0x2aaaaaab
	s_lshr_b32 s1, s0, 31
	s_ashr_i32 s24, s0, 4
	s_add_i32 s24, s24, s1
	s_mul_i32 s0, s24, 0x60
	s_sub_i32 s0, s28, s0
	v_ashrrev_i32_e32 v49, 4, v47
	s_lshl_b32 s0, s0, 6
	s_movk_i32 s4, 0x400
	s_waitcnt vmcnt(0)
	v_mov_b32_e32 v3, 0
	s_ashr_i32 s1, s0, 31
	v_cmp_gt_i32_e32 vcc, s4, v49
	v_mov_b32_e32 v2, v3
	v_mov_b32_e32 v1, v3
	v_mov_b32_e32 v0, v3
	v_mov_b32_e32 v7, v3
	v_mov_b32_e32 v6, v3
	v_mov_b32_e32 v5, v3
	v_mov_b32_e32 v4, v3
	v_mov_b32_e32 v11, v3
	v_mov_b32_e32 v10, v3
	v_mov_b32_e32 v9, v3
	v_mov_b32_e32 v8, v3
	v_mov_b32_e32 v15, v3
	v_mov_b32_e32 v14, v3
	v_mov_b32_e32 v13, v3
	v_mov_b32_e32 v12, v3
	v_mov_b32_e32 v19, v3
	v_mov_b32_e32 v18, v3
	v_mov_b32_e32 v17, v3
	v_mov_b32_e32 v16, v3
	s_waitcnt lgkmcnt(0)
	s_barrier
	s_and_saveexec_b64 s[30:31], vcc
	s_cbranch_execz .LBB0_1184
	s_load_dwordx2 s[4:5], s[72:73], 0x38
	s_movk_i32 s25, 0x6000
	v_mad_i64_i32 v[0:1], s[40:41], v49, s25, 0
	v_mad_i64_i32 v[0:1], s[40:41], s24, v167, v[0:1]
	s_lshl_b64 s[40:41], s[0:1], 2
	v_and_b32_e32 v2, 15, v47
	s_waitcnt lgkmcnt(0)
	s_add_u32 s4, s4, s40
	v_lshl_or_b32 v0, v2, 4, v0
	s_addc_u32 s5, s5, s41
	v_lshl_add_u64 v[0:1], s[4:5], 0, v[0:1]
	s_mov_b64 s[4:5], 0x540000
	v_mov_b32_e32 v16, 0
	v_add_u32_e32 v50, 0xffffff00, v49
	v_lshl_add_u32 v51, v49, 2, 0
	v_lshl_add_u64 v[44:45], v[0:1], 0, s[4:5]
	s_mov_b64 s[40:41], 0
	v_mov_b32_e32 v17, v16
	v_mov_b32_e32 v18, v16
	v_mov_b32_e32 v19, v16
	v_mov_b32_e32 v12, v16
	v_mov_b32_e32 v13, v16
	v_mov_b32_e32 v14, v16
	v_mov_b32_e32 v15, v16
	v_mov_b32_e32 v8, v16
	v_mov_b32_e32 v9, v16
	v_mov_b32_e32 v10, v16
	v_mov_b32_e32 v11, v16
	v_mov_b32_e32 v4, v16
	v_mov_b32_e32 v5, v16
	v_mov_b32_e32 v6, v16
	v_mov_b32_e32 v7, v16
	v_mov_b32_e32 v0, v16
	v_mov_b32_e32 v1, v16
	v_mov_b32_e32 v2, v16
	v_mov_b32_e32 v3, v16

.LBB0_1344:
	s_mul_hi_u32 s0, s31, 0xaaaaaaab
	s_lshr_b32 s4, s0, 6
	s_mul_i32 s0, s4, 0x60
	s_sub_i32 s0, s31, s0
	v_ashrrev_i32_e32 v49, 4, v47
	s_lshl_b32 s84, s0, 6
	s_movk_i32 s0, 0x400
	s_waitcnt vmcnt(0)
	v_mov_b32_e32 v3, 0
	v_cmp_gt_i32_e32 vcc, s0, v49
	v_mov_b32_e32 v2, v3
	v_mov_b32_e32 v1, v3
	v_mov_b32_e32 v0, v3
	v_mov_b32_e32 v7, v3
	v_mov_b32_e32 v6, v3
	v_mov_b32_e32 v5, v3
	v_mov_b32_e32 v4, v3
	v_mov_b32_e32 v11, v3
	v_mov_b32_e32 v10, v3
	v_mov_b32_e32 v9, v3
	v_mov_b32_e32 v8, v3
	v_mov_b32_e32 v15, v3
	v_mov_b32_e32 v14, v3
	v_mov_b32_e32 v13, v3
	v_mov_b32_e32 v12, v3
	v_mov_b32_e32 v19, v3
	v_mov_b32_e32 v18, v3
	v_mov_b32_e32 v17, v3
	v_mov_b32_e32 v16, v3
	s_waitcnt lgkmcnt(0)
	s_barrier
	s_and_saveexec_b64 s[0:1], vcc
	s_cbranch_execz .LBB0_1348
	s_load_dwordx2 s[24:25], s[72:73], 0x38
	s_movk_i32 s5, 0x6000
	v_mad_i64_i32 v[0:1], s[28:29], v49, s5, 0
	v_mad_u64_u32 v[0:1], s[28:29], s4, v167, v[0:1]
	s_lshl_b64 s[28:29], s[84:85], 2
	v_and_b32_e32 v2, 15, v47
	s_waitcnt lgkmcnt(0)
	s_add_u32 s24, s24, s28
	v_lshl_or_b32 v0, v2, 4, v0
	s_addc_u32 s25, s25, s29
	v_lshl_add_u64 v[0:1], s[24:25], 0, v[0:1]
	s_mov_b64 s[24:25], 0x540000
	v_mov_b32_e32 v16, 0
	v_add_u32_e32 v50, 0xffffff00, v49
	v_lshl_add_u32 v51, v49, 2, 0
	v_lshl_add_u64 v[44:45], v[0:1], 0, s[24:25]
	s_mov_b64 s[28:29], 0
	v_mov_b32_e32 v17, v16
	v_mov_b32_e32 v18, v16
	v_mov_b32_e32 v19, v16
	v_mov_b32_e32 v12, v16
	v_mov_b32_e32 v13, v16
	v_mov_b32_e32 v14, v16
	v_mov_b32_e32 v15, v16
	v_mov_b32_e32 v8, v16
	v_mov_b32_e32 v9, v16
	v_mov_b32_e32 v10, v16
	v_mov_b32_e32 v11, v16
	v_mov_b32_e32 v4, v16
	v_mov_b32_e32 v5, v16
	v_mov_b32_e32 v6, v16
	v_mov_b32_e32 v7, v16
	v_mov_b32_e32 v0, v16
	v_mov_b32_e32 v1, v16
	v_mov_b32_e32 v2, v16
	v_mov_b32_e32 v3, v16

.LBB0_1400:
	s_or_b64 exec, exec, s[0:1]
	s_waitcnt vmcnt(0)
	v_ashrrev_i32_e32 v2, 8, v32
	s_lshl_b32 s63, s28, 1
	s_waitcnt lgkmcnt(0)
	s_barrier
	s_load_dwordx4 s[56:59], s[72:73], 0x88
	v_add_u32_e32 v0, s63, v2
	v_lshl_or_b32 v0, v0, 6, s33
	v_ashrrev_i32_e32 v1, 31, v0
	v_and_b32_e32 v33, 15, v32
	v_lshlrev_b64 v[0:1], 12, v[0:1]
	v_lshl_or_b32 v0, v33, 8, v0
	v_bfe_u32 v34, v32, 4, 4
	s_waitcnt lgkmcnt(0)
	v_lshl_add_u64 v[24:25], s[56:57], 0, v[0:1]
	v_lshl_add_u64 v[26:27], s[58:59], 0, v[0:1]
	v_mul_i32_i24_e32 v0, 0x2200, v2
	v_lshl_or_b32 v0, v34, 3, v0
	v_readlane_b32 s0, v254, 57
	v_add_u32_e32 v36, 0, v0
	v_mov_b32_e32 v0, 0
	v_lshl_add_u32 v35, v2, 13, s0
	s_mov_b64 s[0:1], 0
	v_mov_b32_e32 v1, v0
	v_mov_b32_e32 v2, v0
	v_mov_b32_e32 v3, v0
	v_mov_b32_e32 v4, v0
	v_mov_b32_e32 v5, v0
	v_mov_b32_e32 v6, v0
	v_mov_b32_e32 v7, v0
	v_mov_b32_e32 v8, v0
	v_mov_b32_e32 v9, v0
	v_mov_b32_e32 v10, v0
	v_mov_b32_e32 v11, v0
	v_mov_b32_e32 v12, v0
	v_mov_b32_e32 v13, v0
	v_mov_b32_e32 v14, v0
	v_mov_b32_e32 v15, v0
	global_load_dwordx4 v[84:87], v[24:25], off offset:0
	global_load_dwordx4 v[176:179], v[26:27], off offset:0
	global_load_dwordx4 v[88:91], v[24:25], off offset:16
	global_load_dwordx4 v[180:183], v[26:27], off offset:16
	global_load_dwordx4 v[92:95], v[24:25], off offset:32
	global_load_dwordx4 v[184:187], v[26:27], off offset:32
	global_load_dwordx4 v[96:99], v[24:25], off offset:48
	global_load_dwordx4 v[188:191], v[26:27], off offset:48
	global_load_dwordx4 v[100:103], v[24:25], off offset:64
	global_load_dwordx4 v[192:195], v[26:27], off offset:64
	global_load_dwordx4 v[104:107], v[24:25], off offset:80
	global_load_dwordx4 v[196:199], v[26:27], off offset:80
	global_load_dwordx4 v[108:111], v[24:25], off offset:96
	global_load_dwordx4 v[200:203], v[26:27], off offset:96
	global_load_dwordx4 v[112:115], v[24:25], off offset:112
	global_load_dwordx4 v[204:207], v[26:27], off offset:112
	global_load_dwordx4 v[116:119], v[24:25], off offset:128
	global_load_dwordx4 v[208:211], v[26:27], off offset:128
	global_load_dwordx4 v[120:123], v[24:25], off offset:144
	global_load_dwordx4 v[212:215], v[26:27], off offset:144
	global_load_dwordx4 v[124:127], v[24:25], off offset:160
	global_load_dwordx4 v[216:219], v[26:27], off offset:160
	global_load_dwordx4 v[128:131], v[24:25], off offset:176
	global_load_dwordx4 v[220:223], v[26:27], off offset:176
	global_load_dwordx4 v[132:135], v[24:25], off offset:192
	global_load_dwordx4 v[224:227], v[26:27], off offset:192
	global_load_dwordx4 v[136:139], v[24:25], off offset:208
	global_load_dwordx4 v[228:231], v[26:27], off offset:208
	global_load_dwordx4 v[140:143], v[24:25], off offset:224
	global_load_dwordx4 v[232:235], v[26:27], off offset:224
	global_load_dwordx4 v[148:151], v[24:25], off offset:240
	global_load_dwordx4 v[236:239], v[26:27], off offset:240
	v_lshl_add_u64 v[16:17], v[24:25], 0, s[0:1]
	v_lshl_add_u64 v[18:19], v[26:27], 0, s[0:1]
	s_waitcnt vmcnt(30)
	v_mov_b32_e32 v72, v84
	v_mov_b32_e32 v73, v85
	v_mov_b32_e32 v74, v176
	v_mov_b32_e32 v75, v177
	ds_read2_b64 v[28:31], v36 offset1:17
	ds_read_b128 v[38:41], v35
	ds_read_b128 v[42:45], v35 offset:16
	ds_read_b128 v[48:51], v35 offset:32
	ds_read_b128 v[52:55], v35 offset:48
	ds_read_b128 v[56:59], v35 offset:64
	ds_read_b128 v[60:63], v35 offset:80
	ds_read_b128 v[64:67], v35 offset:96
	ds_read_b128 v[68:71], v35 offset:112
	ds_read_b128 v[16:19], v35 offset:128
	ds_read_b128 v[20:23], v35 offset:192
	s_add_u32 s0, s0, 8
	s_addc_u32 s1, s1, 0
	v_add_u32_e32 v36, 0x110, v36
	s_cmpk_eq_i32 s0, 0x100
	v_mov_b32_e32 v76, v72
	v_mov_b32_e32 v77, v74
	s_waitcnt lgkmcnt(10)
	v_mul_f32_e32 v78, v74, v29
	v_mov_b32_e32 v80, v74
	v_mov_b32_e32 v81, v72
	v_mul_f32_e32 v72, v72, v29
	v_pk_fma_f32 v[76:77], v[76:77], v[28:29], v[78:79] op_sel_hi:[1,1,0] neg_lo:[0,0,1] neg_hi:[0,0,1]
	v_pk_fma_f32 v[78:79], v[80:81], v[28:29], v[72:73] op_sel_hi:[1,1,0]
	v_mov_b32_e32 v74, v73
	v_mul_f32_e32 v28, v75, v31
	s_waitcnt lgkmcnt(4)
	v_pk_mul_f32 v[60:61], v[78:79], v[60:61] op_sel_hi:[0,1]
	v_pk_mul_f32 v[62:63], v[78:79], v[62:63] op_sel_hi:[0,1]
	s_waitcnt lgkmcnt(2)
	v_pk_mul_f32 v[68:69], v[78:79], v[68:69] op_sel_hi:[0,1]
	v_pk_mul_f32 v[70:71], v[78:79], v[70:71] op_sel_hi:[0,1]
	v_mov_b32_e32 v72, v75
	v_pk_fma_f32 v[28:29], v[74:75], v[30:31], v[28:29] op_sel_hi:[1,1,0] neg_lo:[0,0,1] neg_hi:[0,0,1]
	v_mul_f32_e32 v74, v73, v31
	v_pk_mul_f32 v[80:81], v[56:57], v[78:79] op_sel_hi:[1,0]
	v_pk_mul_f32 v[82:83], v[58:59], v[78:79] op_sel_hi:[1,0]
	v_pk_mul_f32 v[64:65], v[78:79], v[64:65] op_sel_hi:[0,1]
	v_pk_mul_f32 v[66:67], v[78:79], v[66:67] op_sel_hi:[0,1]
	ds_read_b128 v[56:59], v35 offset:208
	v_pk_fma_f32 v[62:63], v[44:45], v[76:77], v[62:63] op_sel_hi:[1,0,1] neg_lo:[0,0,1] neg_hi:[0,0,1]
	v_pk_fma_f32 v[60:61], v[42:43], v[76:77], v[60:61] op_sel_hi:[1,0,1] neg_lo:[0,0,1] neg_hi:[0,0,1]
	ds_read_b128 v[42:45], v35 offset:224
	v_pk_fma_f32 v[70:71], v[76:77], v[54:55], v[70:71] op_sel_hi:[0,1,1] neg_lo:[0,0,1] neg_hi:[0,0,1]
	v_pk_fma_f32 v[68:69], v[76:77], v[52:53], v[68:69] op_sel_hi:[0,1,1] neg_lo:[0,0,1] neg_hi:[0,0,1]
	ds_read_b128 v[52:55], v35 offset:240
	v_pk_fma_f32 v[30:31], v[72:73], v[30:31], v[74:75] op_sel_hi:[1,1,0]
	ds_read_b128 v[72:75], v35 offset:144
	v_pk_fma_f32 v[78:79], v[40:41], v[76:77], v[82:83] op_sel_hi:[1,0,1] neg_lo:[0,0,1] neg_hi:[0,0,1]
	v_pk_fma_f32 v[80:81], v[38:39], v[76:77], v[80:81] op_sel_hi:[1,0,1] neg_lo:[0,0,1] neg_hi:[0,0,1]
	ds_read_b128 v[38:41], v35 offset:160
	v_pk_fma_f32 v[66:67], v[76:77], v[50:51], v[66:67] op_sel_hi:[0,1,1] neg_lo:[0,0,1] neg_hi:[0,0,1]
	v_pk_fma_f32 v[64:65], v[76:77], v[48:49], v[64:65] op_sel_hi:[0,1,1] neg_lo:[0,0,1] neg_hi:[0,0,1]
	ds_read_b128 v[48:51], v35 offset:176
	s_waitcnt lgkmcnt(6)
	v_pk_mul_f32 v[22:23], v[22:23], v[30:31] op_sel_hi:[1,0]
	v_pk_mul_f32 v[20:21], v[20:21], v[30:31] op_sel_hi:[1,0]
	s_waitcnt lgkmcnt(5)
	v_pk_mul_f32 v[58:59], v[30:31], v[58:59] op_sel_hi:[0,1]
	v_pk_mul_f32 v[56:57], v[30:31], v[56:57] op_sel_hi:[0,1]
	s_waitcnt lgkmcnt(4)
	v_pk_mul_f32 v[44:45], v[30:31], v[44:45] op_sel_hi:[0,1]
	v_pk_mul_f32 v[42:43], v[30:31], v[42:43] op_sel_hi:[0,1]
	s_waitcnt lgkmcnt(3)
	v_pk_mul_f32 v[54:55], v[30:31], v[54:55] op_sel_hi:[0,1]
	v_pk_mul_f32 v[30:31], v[30:31], v[52:53] op_sel_hi:[0,1]
	v_pk_fma_f32 v[16:17], v[16:17], v[28:29], v[20:21] op_sel_hi:[1,0,1] neg_lo:[0,0,1] neg_hi:[0,0,1]
	v_pk_fma_f32 v[18:19], v[18:19], v[28:29], v[22:23] op_sel_hi:[1,0,1] neg_lo:[0,0,1] neg_hi:[0,0,1]
	s_waitcnt lgkmcnt(2)
	v_pk_fma_f32 v[20:21], v[72:73], v[28:29], v[56:57] op_sel_hi:[1,0,1] neg_lo:[0,0,1] neg_hi:[0,0,1]
	v_pk_fma_f32 v[22:23], v[74:75], v[28:29], v[58:59] op_sel_hi:[1,0,1] neg_lo:[0,0,1] neg_hi:[0,0,1]
	s_waitcnt lgkmcnt(1)
	v_pk_fma_f32 v[38:39], v[28:29], v[38:39], v[42:43] op_sel_hi:[0,1,1] neg_lo:[0,0,1] neg_hi:[0,0,1]
	v_pk_fma_f32 v[40:41], v[28:29], v[40:41], v[44:45] op_sel_hi:[0,1,1] neg_lo:[0,0,1] neg_hi:[0,0,1]
	s_waitcnt lgkmcnt(0)
	v_pk_fma_f32 v[30:31], v[28:29], v[48:49], v[30:31] op_sel_hi:[0,1,1] neg_lo:[0,0,1] neg_hi:[0,0,1]
	v_pk_fma_f32 v[28:29], v[28:29], v[50:51], v[54:55] op_sel_hi:[0,1,1] neg_lo:[0,0,1] neg_hi:[0,0,1]
	v_pk_add_f32 v[12:13], v[12:13], v[80:81]
	v_pk_add_f32 v[14:15], v[14:15], v[78:79]
	v_pk_add_f32 v[8:9], v[8:9], v[60:61]
	v_pk_add_f32 v[10:11], v[10:11], v[62:63]
	v_pk_add_f32 v[4:5], v[4:5], v[64:65]
	v_pk_add_f32 v[6:7], v[6:7], v[66:67]
	v_pk_add_f32 v[0:1], v[0:1], v[68:69]
	v_pk_add_f32 v[2:3], v[2:3], v[70:71]
	v_add_u32_e32 v35, 0x100, v35
	v_pk_add_f32 v[14:15], v[14:15], v[18:19]
	v_pk_add_f32 v[12:13], v[12:13], v[16:17]
	v_pk_add_f32 v[10:11], v[10:11], v[22:23]
	v_pk_add_f32 v[8:9], v[8:9], v[20:21]
	v_pk_add_f32 v[6:7], v[6:7], v[40:41]
	v_pk_add_f32 v[4:5], v[4:5], v[38:39]
	v_pk_add_f32 v[2:3], v[2:3], v[28:29]
	v_pk_add_f32 v[0:1], v[0:1], v[30:31]
	v_lshl_add_u64 v[16:17], v[24:25], 0, s[0:1]
	v_lshl_add_u64 v[18:19], v[26:27], 0, s[0:1]
	s_waitcnt vmcnt(30)
	v_mov_b32_e32 v72, v86
	v_mov_b32_e32 v73, v87
	v_mov_b32_e32 v74, v178
	v_mov_b32_e32 v75, v179
	ds_read2_b64 v[28:31], v36 offset1:17
	ds_read_b128 v[38:41], v35
	ds_read_b128 v[42:45], v35 offset:16
	ds_read_b128 v[48:51], v35 offset:32
	ds_read_b128 v[52:55], v35 offset:48
	ds_read_b128 v[56:59], v35 offset:64
	ds_read_b128 v[60:63], v35 offset:80
	ds_read_b128 v[64:67], v35 offset:96
	ds_read_b128 v[68:71], v35 offset:112
	ds_read_b128 v[16:19], v35 offset:128
	ds_read_b128 v[20:23], v35 offset:192
	s_add_u32 s0, s0, 8
	s_addc_u32 s1, s1, 0
	v_add_u32_e32 v36, 0x110, v36
	s_cmpk_eq_i32 s0, 0x100
	v_mov_b32_e32 v76, v72
	v_mov_b32_e32 v77, v74
	s_waitcnt lgkmcnt(10)
	v_mul_f32_e32 v78, v74, v29
	v_mov_b32_e32 v80, v74
	v_mov_b32_e32 v81, v72
	v_mul_f32_e32 v72, v72, v29
	v_pk_fma_f32 v[76:77], v[76:77], v[28:29], v[78:79] op_sel_hi:[1,1,0] neg_lo:[0,0,1] neg_hi:[0,0,1]
	v_pk_fma_f32 v[78:79], v[80:81], v[28:29], v[72:73] op_sel_hi:[1,1,0]
	v_mov_b32_e32 v74, v73
	v_mul_f32_e32 v28, v75, v31
	s_waitcnt lgkmcnt(4)
	v_pk_mul_f32 v[60:61], v[78:79], v[60:61] op_sel_hi:[0,1]
	v_pk_mul_f32 v[62:63], v[78:79], v[62:63] op_sel_hi:[0,1]
	s_waitcnt lgkmcnt(2)
	v_pk_mul_f32 v[68:69], v[78:79], v[68:69] op_sel_hi:[0,1]
	v_pk_mul_f32 v[70:71], v[78:79], v[70:71] op_sel_hi:[0,1]
	v_mov_b32_e32 v72, v75
	v_pk_fma_f32 v[28:29], v[74:75], v[30:31], v[28:29] op_sel_hi:[1,1,0] neg_lo:[0,0,1] neg_hi:[0,0,1]
	v_mul_f32_e32 v74, v73, v31
	v_pk_mul_f32 v[80:81], v[56:57], v[78:79] op_sel_hi:[1,0]
	v_pk_mul_f32 v[82:83], v[58:59], v[78:79] op_sel_hi:[1,0]
	v_pk_mul_f32 v[64:65], v[78:79], v[64:65] op_sel_hi:[0,1]
	v_pk_mul_f32 v[66:67], v[78:79], v[66:67] op_sel_hi:[0,1]
	ds_read_b128 v[56:59], v35 offset:208
	v_pk_fma_f32 v[62:63], v[44:45], v[76:77], v[62:63] op_sel_hi:[1,0,1] neg_lo:[0,0,1] neg_hi:[0,0,1]
	v_pk_fma_f32 v[60:61], v[42:43], v[76:77], v[60:61] op_sel_hi:[1,0,1] neg_lo:[0,0,1] neg_hi:[0,0,1]
	ds_read_b128 v[42:45], v35 offset:224
	v_pk_fma_f32 v[70:71], v[76:77], v[54:55], v[70:71] op_sel_hi:[0,1,1] neg_lo:[0,0,1] neg_hi:[0,0,1]
	v_pk_fma_f32 v[68:69], v[76:77], v[52:53], v[68:69] op_sel_hi:[0,1,1] neg_lo:[0,0,1] neg_hi:[0,0,1]
	ds_read_b128 v[52:55], v35 offset:240
	v_pk_fma_f32 v[30:31], v[72:73], v[30:31], v[74:75] op_sel_hi:[1,1,0]
	ds_read_b128 v[72:75], v35 offset:144
	v_pk_fma_f32 v[78:79], v[40:41], v[76:77], v[82:83] op_sel_hi:[1,0,1] neg_lo:[0,0,1] neg_hi:[0,0,1]
	v_pk_fma_f32 v[80:81], v[38:39], v[76:77], v[80:81] op_sel_hi:[1,0,1] neg_lo:[0,0,1] neg_hi:[0,0,1]
	ds_read_b128 v[38:41], v35 offset:160
	v_pk_fma_f32 v[66:67], v[76:77], v[50:51], v[66:67] op_sel_hi:[0,1,1] neg_lo:[0,0,1] neg_hi:[0,0,1]
	v_pk_fma_f32 v[64:65], v[76:77], v[48:49], v[64:65] op_sel_hi:[0,1,1] neg_lo:[0,0,1] neg_hi:[0,0,1]
	ds_read_b128 v[48:51], v35 offset:176
	s_waitcnt lgkmcnt(6)
	v_pk_mul_f32 v[22:23], v[22:23], v[30:31] op_sel_hi:[1,0]
	v_pk_mul_f32 v[20:21], v[20:21], v[30:31] op_sel_hi:[1,0]
	s_waitcnt lgkmcnt(5)
	v_pk_mul_f32 v[58:59], v[30:31], v[58:59] op_sel_hi:[0,1]
	v_pk_mul_f32 v[56:57], v[30:31], v[56:57] op_sel_hi:[0,1]
	s_waitcnt lgkmcnt(4)
	v_pk_mul_f32 v[44:45], v[30:31], v[44:45] op_sel_hi:[0,1]
	v_pk_mul_f32 v[42:43], v[30:31], v[42:43] op_sel_hi:[0,1]
	s_waitcnt lgkmcnt(3)
	v_pk_mul_f32 v[54:55], v[30:31], v[54:55] op_sel_hi:[0,1]
	v_pk_mul_f32 v[30:31], v[30:31], v[52:53] op_sel_hi:[0,1]
	v_pk_fma_f32 v[16:17], v[16:17], v[28:29], v[20:21] op_sel_hi:[1,0,1] neg_lo:[0,0,1] neg_hi:[0,0,1]
	v_pk_fma_f32 v[18:19], v[18:19], v[28:29], v[22:23] op_sel_hi:[1,0,1] neg_lo:[0,0,1] neg_hi:[0,0,1]
	s_waitcnt lgkmcnt(2)
	v_pk_fma_f32 v[20:21], v[72:73], v[28:29], v[56:57] op_sel_hi:[1,0,1] neg_lo:[0,0,1] neg_hi:[0,0,1]
	v_pk_fma_f32 v[22:23], v[74:75], v[28:29], v[58:59] op_sel_hi:[1,0,1] neg_lo:[0,0,1] neg_hi:[0,0,1]
	s_waitcnt lgkmcnt(1)
	v_pk_fma_f32 v[38:39], v[28:29], v[38:39], v[42:43] op_sel_hi:[0,1,1] neg_lo:[0,0,1] neg_hi:[0,0,1]
	v_pk_fma_f32 v[40:41], v[28:29], v[40:41], v[44:45] op_sel_hi:[0,1,1] neg_lo:[0,0,1] neg_hi:[0,0,1]
	s_waitcnt lgkmcnt(0)
	v_pk_fma_f32 v[30:31], v[28:29], v[48:49], v[30:31] op_sel_hi:[0,1,1] neg_lo:[0,0,1] neg_hi:[0,0,1]
	v_pk_fma_f32 v[28:29], v[28:29], v[50:51], v[54:55] op_sel_hi:[0,1,1] neg_lo:[0,0,1] neg_hi:[0,0,1]
	v_pk_add_f32 v[12:13], v[12:13], v[80:81]
	v_pk_add_f32 v[14:15], v[14:15], v[78:79]
	v_pk_add_f32 v[8:9], v[8:9], v[60:61]
	v_pk_add_f32 v[10:11], v[10:11], v[62:63]
	v_pk_add_f32 v[4:5], v[4:5], v[64:65]
	v_pk_add_f32 v[6:7], v[6:7], v[66:67]
	v_pk_add_f32 v[0:1], v[0:1], v[68:69]
	v_pk_add_f32 v[2:3], v[2:3], v[70:71]
	v_add_u32_e32 v35, 0x100, v35
	v_pk_add_f32 v[14:15], v[14:15], v[18:19]
	v_pk_add_f32 v[12:13], v[12:13], v[16:17]
	v_pk_add_f32 v[10:11], v[10:11], v[22:23]
	v_pk_add_f32 v[8:9], v[8:9], v[20:21]
	v_pk_add_f32 v[6:7], v[6:7], v[40:41]
	v_pk_add_f32 v[4:5], v[4:5], v[38:39]
	v_pk_add_f32 v[2:3], v[2:3], v[28:29]
	v_pk_add_f32 v[0:1], v[0:1], v[30:31]
	v_lshl_add_u64 v[16:17], v[24:25], 0, s[0:1]
	v_lshl_add_u64 v[18:19], v[26:27], 0, s[0:1]
	s_waitcnt vmcnt(28)
	v_mov_b32_e32 v72, v88
	v_mov_b32_e32 v73, v89
	v_mov_b32_e32 v74, v180
	v_mov_b32_e32 v75, v181
	ds_read2_b64 v[28:31], v36 offset1:17
	ds_read_b128 v[38:41], v35
	ds_read_b128 v[42:45], v35 offset:16
	ds_read_b128 v[48:51], v35 offset:32
	ds_read_b128 v[52:55], v35 offset:48
	ds_read_b128 v[56:59], v35 offset:64
	ds_read_b128 v[60:63], v35 offset:80
	ds_read_b128 v[64:67], v35 offset:96
	ds_read_b128 v[68:71], v35 offset:112
	ds_read_b128 v[16:19], v35 offset:128
	ds_read_b128 v[20:23], v35 offset:192
	s_add_u32 s0, s0, 8
	s_addc_u32 s1, s1, 0
	v_add_u32_e32 v36, 0x110, v36
	s_cmpk_eq_i32 s0, 0x100
	v_mov_b32_e32 v76, v72
	v_mov_b32_e32 v77, v74
	s_waitcnt lgkmcnt(10)
	v_mul_f32_e32 v78, v74, v29
	v_mov_b32_e32 v80, v74
	v_mov_b32_e32 v81, v72
	v_mul_f32_e32 v72, v72, v29
	v_pk_fma_f32 v[76:77], v[76:77], v[28:29], v[78:79] op_sel_hi:[1,1,0] neg_lo:[0,0,1] neg_hi:[0,0,1]
	v_pk_fma_f32 v[78:79], v[80:81], v[28:29], v[72:73] op_sel_hi:[1,1,0]
	v_mov_b32_e32 v74, v73
	v_mul_f32_e32 v28, v75, v31
	s_waitcnt lgkmcnt(4)
	v_pk_mul_f32 v[60:61], v[78:79], v[60:61] op_sel_hi:[0,1]
	v_pk_mul_f32 v[62:63], v[78:79], v[62:63] op_sel_hi:[0,1]
	s_waitcnt lgkmcnt(2)
	v_pk_mul_f32 v[68:69], v[78:79], v[68:69] op_sel_hi:[0,1]
	v_pk_mul_f32 v[70:71], v[78:79], v[70:71] op_sel_hi:[0,1]
	v_mov_b32_e32 v72, v75
	v_pk_fma_f32 v[28:29], v[74:75], v[30:31], v[28:29] op_sel_hi:[1,1,0] neg_lo:[0,0,1] neg_hi:[0,0,1]
	v_mul_f32_e32 v74, v73, v31
	v_pk_mul_f32 v[80:81], v[56:57], v[78:79] op_sel_hi:[1,0]
	v_pk_mul_f32 v[82:83], v[58:59], v[78:79] op_sel_hi:[1,0]
	v_pk_mul_f32 v[64:65], v[78:79], v[64:65] op_sel_hi:[0,1]
	v_pk_mul_f32 v[66:67], v[78:79], v[66:67] op_sel_hi:[0,1]
	ds_read_b128 v[56:59], v35 offset:208
	v_pk_fma_f32 v[62:63], v[44:45], v[76:77], v[62:63] op_sel_hi:[1,0,1] neg_lo:[0,0,1] neg_hi:[0,0,1]
	v_pk_fma_f32 v[60:61], v[42:43], v[76:77], v[60:61] op_sel_hi:[1,0,1] neg_lo:[0,0,1] neg_hi:[0,0,1]
	ds_read_b128 v[42:45], v35 offset:224
	v_pk_fma_f32 v[70:71], v[76:77], v[54:55], v[70:71] op_sel_hi:[0,1,1] neg_lo:[0,0,1] neg_hi:[0,0,1]
	v_pk_fma_f32 v[68:69], v[76:77], v[52:53], v[68:69] op_sel_hi:[0,1,1] neg_lo:[0,0,1] neg_hi:[0,0,1]
	ds_read_b128 v[52:55], v35 offset:240
	v_pk_fma_f32 v[30:31], v[72:73], v[30:31], v[74:75] op_sel_hi:[1,1,0]
	ds_read_b128 v[72:75], v35 offset:144
	v_pk_fma_f32 v[78:79], v[40:41], v[76:77], v[82:83] op_sel_hi:[1,0,1] neg_lo:[0,0,1] neg_hi:[0,0,1]
	v_pk_fma_f32 v[80:81], v[38:39], v[76:77], v[80:81] op_sel_hi:[1,0,1] neg_lo:[0,0,1] neg_hi:[0,0,1]
	ds_read_b128 v[38:41], v35 offset:160
	v_pk_fma_f32 v[66:67], v[76:77], v[50:51], v[66:67] op_sel_hi:[0,1,1] neg_lo:[0,0,1] neg_hi:[0,0,1]
	v_pk_fma_f32 v[64:65], v[76:77], v[48:49], v[64:65] op_sel_hi:[0,1,1] neg_lo:[0,0,1] neg_hi:[0,0,1]
	ds_read_b128 v[48:51], v35 offset:176
	s_waitcnt lgkmcnt(6)
	v_pk_mul_f32 v[22:23], v[22:23], v[30:31] op_sel_hi:[1,0]
	v_pk_mul_f32 v[20:21], v[20:21], v[30:31] op_sel_hi:[1,0]
	s_waitcnt lgkmcnt(5)
	v_pk_mul_f32 v[58:59], v[30:31], v[58:59] op_sel_hi:[0,1]
	v_pk_mul_f32 v[56:57], v[30:31], v[56:57] op_sel_hi:[0,1]
	s_waitcnt lgkmcnt(4)
	v_pk_mul_f32 v[44:45], v[30:31], v[44:45] op_sel_hi:[0,1]
	v_pk_mul_f32 v[42:43], v[30:31], v[42:43] op_sel_hi:[0,1]
	s_waitcnt lgkmcnt(3)
	v_pk_mul_f32 v[54:55], v[30:31], v[54:55] op_sel_hi:[0,1]
	v_pk_mul_f32 v[30:31], v[30:31], v[52:53] op_sel_hi:[0,1]
	v_pk_fma_f32 v[16:17], v[16:17], v[28:29], v[20:21] op_sel_hi:[1,0,1] neg_lo:[0,0,1] neg_hi:[0,0,1]
	v_pk_fma_f32 v[18:19], v[18:19], v[28:29], v[22:23] op_sel_hi:[1,0,1] neg_lo:[0,0,1] neg_hi:[0,0,1]
	s_waitcnt lgkmcnt(2)
	v_pk_fma_f32 v[20:21], v[72:73], v[28:29], v[56:57] op_sel_hi:[1,0,1] neg_lo:[0,0,1] neg_hi:[0,0,1]
	v_pk_fma_f32 v[22:23], v[74:75], v[28:29], v[58:59] op_sel_hi:[1,0,1] neg_lo:[0,0,1] neg_hi:[0,0,1]
	s_waitcnt lgkmcnt(1)
	v_pk_fma_f32 v[38:39], v[28:29], v[38:39], v[42:43] op_sel_hi:[0,1,1] neg_lo:[0,0,1] neg_hi:[0,0,1]
	v_pk_fma_f32 v[40:41], v[28:29], v[40:41], v[44:45] op_sel_hi:[0,1,1] neg_lo:[0,0,1] neg_hi:[0,0,1]
	s_waitcnt lgkmcnt(0)
	v_pk_fma_f32 v[30:31], v[28:29], v[48:49], v[30:31] op_sel_hi:[0,1,1] neg_lo:[0,0,1] neg_hi:[0,0,1]
	v_pk_fma_f32 v[28:29], v[28:29], v[50:51], v[54:55] op_sel_hi:[0,1,1] neg_lo:[0,0,1] neg_hi:[0,0,1]
	v_pk_add_f32 v[12:13], v[12:13], v[80:81]
	v_pk_add_f32 v[14:15], v[14:15], v[78:79]
	v_pk_add_f32 v[8:9], v[8:9], v[60:61]
	v_pk_add_f32 v[10:11], v[10:11], v[62:63]
	v_pk_add_f32 v[4:5], v[4:5], v[64:65]
	v_pk_add_f32 v[6:7], v[6:7], v[66:67]
	v_pk_add_f32 v[0:1], v[0:1], v[68:69]
	v_pk_add_f32 v[2:3], v[2:3], v[70:71]
	v_add_u32_e32 v35, 0x100, v35
	v_pk_add_f32 v[14:15], v[14:15], v[18:19]
	v_pk_add_f32 v[12:13], v[12:13], v[16:17]
	v_pk_add_f32 v[10:11], v[10:11], v[22:23]
	v_pk_add_f32 v[8:9], v[8:9], v[20:21]
	v_pk_add_f32 v[6:7], v[6:7], v[40:41]
	v_pk_add_f32 v[4:5], v[4:5], v[38:39]
	v_pk_add_f32 v[2:3], v[2:3], v[28:29]
	v_pk_add_f32 v[0:1], v[0:1], v[30:31]
	v_lshl_add_u64 v[16:17], v[24:25], 0, s[0:1]
	v_lshl_add_u64 v[18:19], v[26:27], 0, s[0:1]
	s_waitcnt vmcnt(28)
	v_mov_b32_e32 v72, v90
	v_mov_b32_e32 v73, v91
	v_mov_b32_e32 v74, v182
	v_mov_b32_e32 v75, v183
	ds_read2_b64 v[28:31], v36 offset1:17
	ds_read_b128 v[38:41], v35
	ds_read_b128 v[42:45], v35 offset:16
	ds_read_b128 v[48:51], v35 offset:32
	ds_read_b128 v[52:55], v35 offset:48
	ds_read_b128 v[56:59], v35 offset:64
	ds_read_b128 v[60:63], v35 offset:80
	ds_read_b128 v[64:67], v35 offset:96
	ds_read_b128 v[68:71], v35 offset:112
	ds_read_b128 v[16:19], v35 offset:128
	ds_read_b128 v[20:23], v35 offset:192
	s_add_u32 s0, s0, 8
	s_addc_u32 s1, s1, 0
	v_add_u32_e32 v36, 0x110, v36
	s_cmpk_eq_i32 s0, 0x100
	v_mov_b32_e32 v76, v72
	v_mov_b32_e32 v77, v74
	s_waitcnt lgkmcnt(10)
	v_mul_f32_e32 v78, v74, v29
	v_mov_b32_e32 v80, v74
	v_mov_b32_e32 v81, v72
	v_mul_f32_e32 v72, v72, v29
	v_pk_fma_f32 v[76:77], v[76:77], v[28:29], v[78:79] op_sel_hi:[1,1,0] neg_lo:[0,0,1] neg_hi:[0,0,1]
	v_pk_fma_f32 v[78:79], v[80:81], v[28:29], v[72:73] op_sel_hi:[1,1,0]
	v_mov_b32_e32 v74, v73
	v_mul_f32_e32 v28, v75, v31
	s_waitcnt lgkmcnt(4)
	v_pk_mul_f32 v[60:61], v[78:79], v[60:61] op_sel_hi:[0,1]
	v_pk_mul_f32 v[62:63], v[78:79], v[62:63] op_sel_hi:[0,1]
	s_waitcnt lgkmcnt(2)
	v_pk_mul_f32 v[68:69], v[78:79], v[68:69] op_sel_hi:[0,1]
	v_pk_mul_f32 v[70:71], v[78:79], v[70:71] op_sel_hi:[0,1]
	v_mov_b32_e32 v72, v75
	v_pk_fma_f32 v[28:29], v[74:75], v[30:31], v[28:29] op_sel_hi:[1,1,0] neg_lo:[0,0,1] neg_hi:[0,0,1]
	v_mul_f32_e32 v74, v73, v31
	v_pk_mul_f32 v[80:81], v[56:57], v[78:79] op_sel_hi:[1,0]
	v_pk_mul_f32 v[82:83], v[58:59], v[78:79] op_sel_hi:[1,0]
	v_pk_mul_f32 v[64:65], v[78:79], v[64:65] op_sel_hi:[0,1]
	v_pk_mul_f32 v[66:67], v[78:79], v[66:67] op_sel_hi:[0,1]
	ds_read_b128 v[56:59], v35 offset:208
	v_pk_fma_f32 v[62:63], v[44:45], v[76:77], v[62:63] op_sel_hi:[1,0,1] neg_lo:[0,0,1] neg_hi:[0,0,1]
	v_pk_fma_f32 v[60:61], v[42:43], v[76:77], v[60:61] op_sel_hi:[1,0,1] neg_lo:[0,0,1] neg_hi:[0,0,1]
	ds_read_b128 v[42:45], v35 offset:224
	v_pk_fma_f32 v[70:71], v[76:77], v[54:55], v[70:71] op_sel_hi:[0,1,1] neg_lo:[0,0,1] neg_hi:[0,0,1]
	v_pk_fma_f32 v[68:69], v[76:77], v[52:53], v[68:69] op_sel_hi:[0,1,1] neg_lo:[0,0,1] neg_hi:[0,0,1]
	ds_read_b128 v[52:55], v35 offset:240
	v_pk_fma_f32 v[30:31], v[72:73], v[30:31], v[74:75] op_sel_hi:[1,1,0]
	ds_read_b128 v[72:75], v35 offset:144
	v_pk_fma_f32 v[78:79], v[40:41], v[76:77], v[82:83] op_sel_hi:[1,0,1] neg_lo:[0,0,1] neg_hi:[0,0,1]
	v_pk_fma_f32 v[80:81], v[38:39], v[76:77], v[80:81] op_sel_hi:[1,0,1] neg_lo:[0,0,1] neg_hi:[0,0,1]
	ds_read_b128 v[38:41], v35 offset:160
	v_pk_fma_f32 v[66:67], v[76:77], v[50:51], v[66:67] op_sel_hi:[0,1,1] neg_lo:[0,0,1] neg_hi:[0,0,1]
	v_pk_fma_f32 v[64:65], v[76:77], v[48:49], v[64:65] op_sel_hi:[0,1,1] neg_lo:[0,0,1] neg_hi:[0,0,1]
	ds_read_b128 v[48:51], v35 offset:176
	s_waitcnt lgkmcnt(6)
	v_pk_mul_f32 v[22:23], v[22:23], v[30:31] op_sel_hi:[1,0]
	v_pk_mul_f32 v[20:21], v[20:21], v[30:31] op_sel_hi:[1,0]
	s_waitcnt lgkmcnt(5)
	v_pk_mul_f32 v[58:59], v[30:31], v[58:59] op_sel_hi:[0,1]
	v_pk_mul_f32 v[56:57], v[30:31], v[56:57] op_sel_hi:[0,1]
	s_waitcnt lgkmcnt(4)
	v_pk_mul_f32 v[44:45], v[30:31], v[44:45] op_sel_hi:[0,1]
	v_pk_mul_f32 v[42:43], v[30:31], v[42:43] op_sel_hi:[0,1]
	s_waitcnt lgkmcnt(3)
	v_pk_mul_f32 v[54:55], v[30:31], v[54:55] op_sel_hi:[0,1]
	v_pk_mul_f32 v[30:31], v[30:31], v[52:53] op_sel_hi:[0,1]
	v_pk_fma_f32 v[16:17], v[16:17], v[28:29], v[20:21] op_sel_hi:[1,0,1] neg_lo:[0,0,1] neg_hi:[0,0,1]
	v_pk_fma_f32 v[18:19], v[18:19], v[28:29], v[22:23] op_sel_hi:[1,0,1] neg_lo:[0,0,1] neg_hi:[0,0,1]
	s_waitcnt lgkmcnt(2)
	v_pk_fma_f32 v[20:21], v[72:73], v[28:29], v[56:57] op_sel_hi:[1,0,1] neg_lo:[0,0,1] neg_hi:[0,0,1]
	v_pk_fma_f32 v[22:23], v[74:75], v[28:29], v[58:59] op_sel_hi:[1,0,1] neg_lo:[0,0,1] neg_hi:[0,0,1]
	s_waitcnt lgkmcnt(1)
	v_pk_fma_f32 v[38:39], v[28:29], v[38:39], v[42:43] op_sel_hi:[0,1,1] neg_lo:[0,0,1] neg_hi:[0,0,1]
	v_pk_fma_f32 v[40:41], v[28:29], v[40:41], v[44:45] op_sel_hi:[0,1,1] neg_lo:[0,0,1] neg_hi:[0,0,1]
	s_waitcnt lgkmcnt(0)
	v_pk_fma_f32 v[30:31], v[28:29], v[48:49], v[30:31] op_sel_hi:[0,1,1] neg_lo:[0,0,1] neg_hi:[0,0,1]
	v_pk_fma_f32 v[28:29], v[28:29], v[50:51], v[54:55] op_sel_hi:[0,1,1] neg_lo:[0,0,1] neg_hi:[0,0,1]
	v_pk_add_f32 v[12:13], v[12:13], v[80:81]
	v_pk_add_f32 v[14:15], v[14:15], v[78:79]
	v_pk_add_f32 v[8:9], v[8:9], v[60:61]
	v_pk_add_f32 v[10:11], v[10:11], v[62:63]
	v_pk_add_f32 v[4:5], v[4:5], v[64:65]
	v_pk_add_f32 v[6:7], v[6:7], v[66:67]
	v_pk_add_f32 v[0:1], v[0:1], v[68:69]
	v_pk_add_f32 v[2:3], v[2:3], v[70:71]
	v_add_u32_e32 v35, 0x100, v35
	v_pk_add_f32 v[14:15], v[14:15], v[18:19]
	v_pk_add_f32 v[12:13], v[12:13], v[16:17]
	v_pk_add_f32 v[10:11], v[10:11], v[22:23]
	v_pk_add_f32 v[8:9], v[8:9], v[20:21]
	v_pk_add_f32 v[6:7], v[6:7], v[40:41]
	v_pk_add_f32 v[4:5], v[4:5], v[38:39]
	v_pk_add_f32 v[2:3], v[2:3], v[28:29]
	v_pk_add_f32 v[0:1], v[0:1], v[30:31]
	v_lshl_add_u64 v[16:17], v[24:25], 0, s[0:1]
	v_lshl_add_u64 v[18:19], v[26:27], 0, s[0:1]
	s_waitcnt vmcnt(26)
	v_mov_b32_e32 v72, v92
	v_mov_b32_e32 v73, v93
	v_mov_b32_e32 v74, v184
	v_mov_b32_e32 v75, v185
	ds_read2_b64 v[28:31], v36 offset1:17
	ds_read_b128 v[38:41], v35
	ds_read_b128 v[42:45], v35 offset:16
	ds_read_b128 v[48:51], v35 offset:32
	ds_read_b128 v[52:55], v35 offset:48
	ds_read_b128 v[56:59], v35 offset:64
	ds_read_b128 v[60:63], v35 offset:80
	ds_read_b128 v[64:67], v35 offset:96
	ds_read_b128 v[68:71], v35 offset:112
	ds_read_b128 v[16:19], v35 offset:128
	ds_read_b128 v[20:23], v35 offset:192
	s_add_u32 s0, s0, 8
	s_addc_u32 s1, s1, 0
	v_add_u32_e32 v36, 0x110, v36
	s_cmpk_eq_i32 s0, 0x100
	v_mov_b32_e32 v76, v72
	v_mov_b32_e32 v77, v74
	s_waitcnt lgkmcnt(10)
	v_mul_f32_e32 v78, v74, v29
	v_mov_b32_e32 v80, v74
	v_mov_b32_e32 v81, v72
	v_mul_f32_e32 v72, v72, v29
	v_pk_fma_f32 v[76:77], v[76:77], v[28:29], v[78:79] op_sel_hi:[1,1,0] neg_lo:[0,0,1] neg_hi:[0,0,1]
	v_pk_fma_f32 v[78:79], v[80:81], v[28:29], v[72:73] op_sel_hi:[1,1,0]
	v_mov_b32_e32 v74, v73
	v_mul_f32_e32 v28, v75, v31
	s_waitcnt lgkmcnt(4)
	v_pk_mul_f32 v[60:61], v[78:79], v[60:61] op_sel_hi:[0,1]
	v_pk_mul_f32 v[62:63], v[78:79], v[62:63] op_sel_hi:[0,1]
	s_waitcnt lgkmcnt(2)
	v_pk_mul_f32 v[68:69], v[78:79], v[68:69] op_sel_hi:[0,1]
	v_pk_mul_f32 v[70:71], v[78:79], v[70:71] op_sel_hi:[0,1]
	v_mov_b32_e32 v72, v75
	v_pk_fma_f32 v[28:29], v[74:75], v[30:31], v[28:29] op_sel_hi:[1,1,0] neg_lo:[0,0,1] neg_hi:[0,0,1]
	v_mul_f32_e32 v74, v73, v31
	v_pk_mul_f32 v[80:81], v[56:57], v[78:79] op_sel_hi:[1,0]
	v_pk_mul_f32 v[82:83], v[58:59], v[78:79] op_sel_hi:[1,0]
	v_pk_mul_f32 v[64:65], v[78:79], v[64:65] op_sel_hi:[0,1]
	v_pk_mul_f32 v[66:67], v[78:79], v[66:67] op_sel_hi:[0,1]
	ds_read_b128 v[56:59], v35 offset:208
	v_pk_fma_f32 v[62:63], v[44:45], v[76:77], v[62:63] op_sel_hi:[1,0,1] neg_lo:[0,0,1] neg_hi:[0,0,1]
	v_pk_fma_f32 v[60:61], v[42:43], v[76:77], v[60:61] op_sel_hi:[1,0,1] neg_lo:[0,0,1] neg_hi:[0,0,1]
	ds_read_b128 v[42:45], v35 offset:224
	v_pk_fma_f32 v[70:71], v[76:77], v[54:55], v[70:71] op_sel_hi:[0,1,1] neg_lo:[0,0,1] neg_hi:[0,0,1]
	v_pk_fma_f32 v[68:69], v[76:77], v[52:53], v[68:69] op_sel_hi:[0,1,1] neg_lo:[0,0,1] neg_hi:[0,0,1]
	ds_read_b128 v[52:55], v35 offset:240
	v_pk_fma_f32 v[30:31], v[72:73], v[30:31], v[74:75] op_sel_hi:[1,1,0]
	ds_read_b128 v[72:75], v35 offset:144
	v_pk_fma_f32 v[78:79], v[40:41], v[76:77], v[82:83] op_sel_hi:[1,0,1] neg_lo:[0,0,1] neg_hi:[0,0,1]
	v_pk_fma_f32 v[80:81], v[38:39], v[76:77], v[80:81] op_sel_hi:[1,0,1] neg_lo:[0,0,1] neg_hi:[0,0,1]
	ds_read_b128 v[38:41], v35 offset:160
	v_pk_fma_f32 v[66:67], v[76:77], v[50:51], v[66:67] op_sel_hi:[0,1,1] neg_lo:[0,0,1] neg_hi:[0,0,1]
	v_pk_fma_f32 v[64:65], v[76:77], v[48:49], v[64:65] op_sel_hi:[0,1,1] neg_lo:[0,0,1] neg_hi:[0,0,1]
	ds_read_b128 v[48:51], v35 offset:176
	s_waitcnt lgkmcnt(6)
	v_pk_mul_f32 v[22:23], v[22:23], v[30:31] op_sel_hi:[1,0]
	v_pk_mul_f32 v[20:21], v[20:21], v[30:31] op_sel_hi:[1,0]
	s_waitcnt lgkmcnt(5)
	v_pk_mul_f32 v[58:59], v[30:31], v[58:59] op_sel_hi:[0,1]
	v_pk_mul_f32 v[56:57], v[30:31], v[56:57] op_sel_hi:[0,1]
	s_waitcnt lgkmcnt(4)
	v_pk_mul_f32 v[44:45], v[30:31], v[44:45] op_sel_hi:[0,1]
	v_pk_mul_f32 v[42:43], v[30:31], v[42:43] op_sel_hi:[0,1]
	s_waitcnt lgkmcnt(3)
	v_pk_mul_f32 v[54:55], v[30:31], v[54:55] op_sel_hi:[0,1]
	v_pk_mul_f32 v[30:31], v[30:31], v[52:53] op_sel_hi:[0,1]
	v_pk_fma_f32 v[16:17], v[16:17], v[28:29], v[20:21] op_sel_hi:[1,0,1] neg_lo:[0,0,1] neg_hi:[0,0,1]
	v_pk_fma_f32 v[18:19], v[18:19], v[28:29], v[22:23] op_sel_hi:[1,0,1] neg_lo:[0,0,1] neg_hi:[0,0,1]
	s_waitcnt lgkmcnt(2)
	v_pk_fma_f32 v[20:21], v[72:73], v[28:29], v[56:57] op_sel_hi:[1,0,1] neg_lo:[0,0,1] neg_hi:[0,0,1]
	v_pk_fma_f32 v[22:23], v[74:75], v[28:29], v[58:59] op_sel_hi:[1,0,1] neg_lo:[0,0,1] neg_hi:[0,0,1]
	s_waitcnt lgkmcnt(1)
	v_pk_fma_f32 v[38:39], v[28:29], v[38:39], v[42:43] op_sel_hi:[0,1,1] neg_lo:[0,0,1] neg_hi:[0,0,1]
	v_pk_fma_f32 v[40:41], v[28:29], v[40:41], v[44:45] op_sel_hi:[0,1,1] neg_lo:[0,0,1] neg_hi:[0,0,1]
	s_waitcnt lgkmcnt(0)
	v_pk_fma_f32 v[30:31], v[28:29], v[48:49], v[30:31] op_sel_hi:[0,1,1] neg_lo:[0,0,1] neg_hi:[0,0,1]
	v_pk_fma_f32 v[28:29], v[28:29], v[50:51], v[54:55] op_sel_hi:[0,1,1] neg_lo:[0,0,1] neg_hi:[0,0,1]
	v_pk_add_f32 v[12:13], v[12:13], v[80:81]
	v_pk_add_f32 v[14:15], v[14:15], v[78:79]
	v_pk_add_f32 v[8:9], v[8:9], v[60:61]
	v_pk_add_f32 v[10:11], v[10:11], v[62:63]
	v_pk_add_f32 v[4:5], v[4:5], v[64:65]
	v_pk_add_f32 v[6:7], v[6:7], v[66:67]
	v_pk_add_f32 v[0:1], v[0:1], v[68:69]
	v_pk_add_f32 v[2:3], v[2:3], v[70:71]
	v_add_u32_e32 v35, 0x100, v35
	v_pk_add_f32 v[14:15], v[14:15], v[18:19]
	v_pk_add_f32 v[12:13], v[12:13], v[16:17]
	v_pk_add_f32 v[10:11], v[10:11], v[22:23]
	v_pk_add_f32 v[8:9], v[8:9], v[20:21]
	v_pk_add_f32 v[6:7], v[6:7], v[40:41]
	v_pk_add_f32 v[4:5], v[4:5], v[38:39]
	v_pk_add_f32 v[2:3], v[2:3], v[28:29]
	v_pk_add_f32 v[0:1], v[0:1], v[30:31]
	v_lshl_add_u64 v[16:17], v[24:25], 0, s[0:1]
	v_lshl_add_u64 v[18:19], v[26:27], 0, s[0:1]
	s_waitcnt vmcnt(26)
	v_mov_b32_e32 v72, v94
	v_mov_b32_e32 v73, v95
	v_mov_b32_e32 v74, v186
	v_mov_b32_e32 v75, v187
	ds_read2_b64 v[28:31], v36 offset1:17
	ds_read_b128 v[38:41], v35
	ds_read_b128 v[42:45], v35 offset:16
	ds_read_b128 v[48:51], v35 offset:32
	ds_read_b128 v[52:55], v35 offset:48
	ds_read_b128 v[56:59], v35 offset:64
	ds_read_b128 v[60:63], v35 offset:80
	ds_read_b128 v[64:67], v35 offset:96
	ds_read_b128 v[68:71], v35 offset:112
	ds_read_b128 v[16:19], v35 offset:128
	ds_read_b128 v[20:23], v35 offset:192
	s_add_u32 s0, s0, 8
	s_addc_u32 s1, s1, 0
	v_add_u32_e32 v36, 0x110, v36
	s_cmpk_eq_i32 s0, 0x100
	v_mov_b32_e32 v76, v72
	v_mov_b32_e32 v77, v74
	s_waitcnt lgkmcnt(10)
	v_mul_f32_e32 v78, v74, v29
	v_mov_b32_e32 v80, v74
	v_mov_b32_e32 v81, v72
	v_mul_f32_e32 v72, v72, v29
	v_pk_fma_f32 v[76:77], v[76:77], v[28:29], v[78:79] op_sel_hi:[1,1,0] neg_lo:[0,0,1] neg_hi:[0,0,1]
	v_pk_fma_f32 v[78:79], v[80:81], v[28:29], v[72:73] op_sel_hi:[1,1,0]
	v_mov_b32_e32 v74, v73
	v_mul_f32_e32 v28, v75, v31
	s_waitcnt lgkmcnt(4)
	v_pk_mul_f32 v[60:61], v[78:79], v[60:61] op_sel_hi:[0,1]
	v_pk_mul_f32 v[62:63], v[78:79], v[62:63] op_sel_hi:[0,1]
	s_waitcnt lgkmcnt(2)
	v_pk_mul_f32 v[68:69], v[78:79], v[68:69] op_sel_hi:[0,1]
	v_pk_mul_f32 v[70:71], v[78:79], v[70:71] op_sel_hi:[0,1]
	v_mov_b32_e32 v72, v75
	v_pk_fma_f32 v[28:29], v[74:75], v[30:31], v[28:29] op_sel_hi:[1,1,0] neg_lo:[0,0,1] neg_hi:[0,0,1]
	v_mul_f32_e32 v74, v73, v31
	v_pk_mul_f32 v[80:81], v[56:57], v[78:79] op_sel_hi:[1,0]
	v_pk_mul_f32 v[82:83], v[58:59], v[78:79] op_sel_hi:[1,0]
	v_pk_mul_f32 v[64:65], v[78:79], v[64:65] op_sel_hi:[0,1]
	v_pk_mul_f32 v[66:67], v[78:79], v[66:67] op_sel_hi:[0,1]
	ds_read_b128 v[56:59], v35 offset:208
	v_pk_fma_f32 v[62:63], v[44:45], v[76:77], v[62:63] op_sel_hi:[1,0,1] neg_lo:[0,0,1] neg_hi:[0,0,1]
	v_pk_fma_f32 v[60:61], v[42:43], v[76:77], v[60:61] op_sel_hi:[1,0,1] neg_lo:[0,0,1] neg_hi:[0,0,1]
	ds_read_b128 v[42:45], v35 offset:224
	v_pk_fma_f32 v[70:71], v[76:77], v[54:55], v[70:71] op_sel_hi:[0,1,1] neg_lo:[0,0,1] neg_hi:[0,0,1]
	v_pk_fma_f32 v[68:69], v[76:77], v[52:53], v[68:69] op_sel_hi:[0,1,1] neg_lo:[0,0,1] neg_hi:[0,0,1]
	ds_read_b128 v[52:55], v35 offset:240
	v_pk_fma_f32 v[30:31], v[72:73], v[30:31], v[74:75] op_sel_hi:[1,1,0]
	ds_read_b128 v[72:75], v35 offset:144
	v_pk_fma_f32 v[78:79], v[40:41], v[76:77], v[82:83] op_sel_hi:[1,0,1] neg_lo:[0,0,1] neg_hi:[0,0,1]
	v_pk_fma_f32 v[80:81], v[38:39], v[76:77], v[80:81] op_sel_hi:[1,0,1] neg_lo:[0,0,1] neg_hi:[0,0,1]
	ds_read_b128 v[38:41], v35 offset:160
	v_pk_fma_f32 v[66:67], v[76:77], v[50:51], v[66:67] op_sel_hi:[0,1,1] neg_lo:[0,0,1] neg_hi:[0,0,1]
	v_pk_fma_f32 v[64:65], v[76:77], v[48:49], v[64:65] op_sel_hi:[0,1,1] neg_lo:[0,0,1] neg_hi:[0,0,1]
	ds_read_b128 v[48:51], v35 offset:176
	s_waitcnt lgkmcnt(6)
	v_pk_mul_f32 v[22:23], v[22:23], v[30:31] op_sel_hi:[1,0]
	v_pk_mul_f32 v[20:21], v[20:21], v[30:31] op_sel_hi:[1,0]
	s_waitcnt lgkmcnt(5)
	v_pk_mul_f32 v[58:59], v[30:31], v[58:59] op_sel_hi:[0,1]
	v_pk_mul_f32 v[56:57], v[30:31], v[56:57] op_sel_hi:[0,1]
	s_waitcnt lgkmcnt(4)
	v_pk_mul_f32 v[44:45], v[30:31], v[44:45] op_sel_hi:[0,1]
	v_pk_mul_f32 v[42:43], v[30:31], v[42:43] op_sel_hi:[0,1]
	s_waitcnt lgkmcnt(3)
	v_pk_mul_f32 v[54:55], v[30:31], v[54:55] op_sel_hi:[0,1]
	v_pk_mul_f32 v[30:31], v[30:31], v[52:53] op_sel_hi:[0,1]
	v_pk_fma_f32 v[16:17], v[16:17], v[28:29], v[20:21] op_sel_hi:[1,0,1] neg_lo:[0,0,1] neg_hi:[0,0,1]
	v_pk_fma_f32 v[18:19], v[18:19], v[28:29], v[22:23] op_sel_hi:[1,0,1] neg_lo:[0,0,1] neg_hi:[0,0,1]
	s_waitcnt lgkmcnt(2)
	v_pk_fma_f32 v[20:21], v[72:73], v[28:29], v[56:57] op_sel_hi:[1,0,1] neg_lo:[0,0,1] neg_hi:[0,0,1]
	v_pk_fma_f32 v[22:23], v[74:75], v[28:29], v[58:59] op_sel_hi:[1,0,1] neg_lo:[0,0,1] neg_hi:[0,0,1]
	s_waitcnt lgkmcnt(1)
	v_pk_fma_f32 v[38:39], v[28:29], v[38:39], v[42:43] op_sel_hi:[0,1,1] neg_lo:[0,0,1] neg_hi:[0,0,1]
	v_pk_fma_f32 v[40:41], v[28:29], v[40:41], v[44:45] op_sel_hi:[0,1,1] neg_lo:[0,0,1] neg_hi:[0,0,1]
	s_waitcnt lgkmcnt(0)
	v_pk_fma_f32 v[30:31], v[28:29], v[48:49], v[30:31] op_sel_hi:[0,1,1] neg_lo:[0,0,1] neg_hi:[0,0,1]
	v_pk_fma_f32 v[28:29], v[28:29], v[50:51], v[54:55] op_sel_hi:[0,1,1] neg_lo:[0,0,1] neg_hi:[0,0,1]
	v_pk_add_f32 v[12:13], v[12:13], v[80:81]
	v_pk_add_f32 v[14:15], v[14:15], v[78:79]
	v_pk_add_f32 v[8:9], v[8:9], v[60:61]
	v_pk_add_f32 v[10:11], v[10:11], v[62:63]
	v_pk_add_f32 v[4:5], v[4:5], v[64:65]
	v_pk_add_f32 v[6:7], v[6:7], v[66:67]
	v_pk_add_f32 v[0:1], v[0:1], v[68:69]
	v_pk_add_f32 v[2:3], v[2:3], v[70:71]
	v_add_u32_e32 v35, 0x100, v35
	v_pk_add_f32 v[14:15], v[14:15], v[18:19]
	v_pk_add_f32 v[12:13], v[12:13], v[16:17]
	v_pk_add_f32 v[10:11], v[10:11], v[22:23]
	v_pk_add_f32 v[8:9], v[8:9], v[20:21]
	v_pk_add_f32 v[6:7], v[6:7], v[40:41]
	v_pk_add_f32 v[4:5], v[4:5], v[38:39]
	v_pk_add_f32 v[2:3], v[2:3], v[28:29]
	v_pk_add_f32 v[0:1], v[0:1], v[30:31]
	v_lshl_add_u64 v[16:17], v[24:25], 0, s[0:1]
	v_lshl_add_u64 v[18:19], v[26:27], 0, s[0:1]
	s_waitcnt vmcnt(24)
	v_mov_b32_e32 v72, v96
	v_mov_b32_e32 v73, v97
	v_mov_b32_e32 v74, v188
	v_mov_b32_e32 v75, v189
	ds_read2_b64 v[28:31], v36 offset1:17
	ds_read_b128 v[38:41], v35
	ds_read_b128 v[42:45], v35 offset:16
	ds_read_b128 v[48:51], v35 offset:32
	ds_read_b128 v[52:55], v35 offset:48
	ds_read_b128 v[56:59], v35 offset:64
	ds_read_b128 v[60:63], v35 offset:80
	ds_read_b128 v[64:67], v35 offset:96
	ds_read_b128 v[68:71], v35 offset:112
	ds_read_b128 v[16:19], v35 offset:128
	ds_read_b128 v[20:23], v35 offset:192
	s_add_u32 s0, s0, 8
	s_addc_u32 s1, s1, 0
	v_add_u32_e32 v36, 0x110, v36
	s_cmpk_eq_i32 s0, 0x100
	v_mov_b32_e32 v76, v72
	v_mov_b32_e32 v77, v74
	s_waitcnt lgkmcnt(10)
	v_mul_f32_e32 v78, v74, v29
	v_mov_b32_e32 v80, v74
	v_mov_b32_e32 v81, v72
	v_mul_f32_e32 v72, v72, v29
	v_pk_fma_f32 v[76:77], v[76:77], v[28:29], v[78:79] op_sel_hi:[1,1,0] neg_lo:[0,0,1] neg_hi:[0,0,1]
	v_pk_fma_f32 v[78:79], v[80:81], v[28:29], v[72:73] op_sel_hi:[1,1,0]
	v_mov_b32_e32 v74, v73
	v_mul_f32_e32 v28, v75, v31
	s_waitcnt lgkmcnt(4)
	v_pk_mul_f32 v[60:61], v[78:79], v[60:61] op_sel_hi:[0,1]
	v_pk_mul_f32 v[62:63], v[78:79], v[62:63] op_sel_hi:[0,1]
	s_waitcnt lgkmcnt(2)
	v_pk_mul_f32 v[68:69], v[78:79], v[68:69] op_sel_hi:[0,1]
	v_pk_mul_f32 v[70:71], v[78:79], v[70:71] op_sel_hi:[0,1]
	v_mov_b32_e32 v72, v75
	v_pk_fma_f32 v[28:29], v[74:75], v[30:31], v[28:29] op_sel_hi:[1,1,0] neg_lo:[0,0,1] neg_hi:[0,0,1]
	v_mul_f32_e32 v74, v73, v31
	v_pk_mul_f32 v[80:81], v[56:57], v[78:79] op_sel_hi:[1,0]
	v_pk_mul_f32 v[82:83], v[58:59], v[78:79] op_sel_hi:[1,0]
	v_pk_mul_f32 v[64:65], v[78:79], v[64:65] op_sel_hi:[0,1]
	v_pk_mul_f32 v[66:67], v[78:79], v[66:67] op_sel_hi:[0,1]
	ds_read_b128 v[56:59], v35 offset:208
	v_pk_fma_f32 v[62:63], v[44:45], v[76:77], v[62:63] op_sel_hi:[1,0,1] neg_lo:[0,0,1] neg_hi:[0,0,1]
	v_pk_fma_f32 v[60:61], v[42:43], v[76:77], v[60:61] op_sel_hi:[1,0,1] neg_lo:[0,0,1] neg_hi:[0,0,1]
	ds_read_b128 v[42:45], v35 offset:224
	v_pk_fma_f32 v[70:71], v[76:77], v[54:55], v[70:71] op_sel_hi:[0,1,1] neg_lo:[0,0,1] neg_hi:[0,0,1]
	v_pk_fma_f32 v[68:69], v[76:77], v[52:53], v[68:69] op_sel_hi:[0,1,1] neg_lo:[0,0,1] neg_hi:[0,0,1]
	ds_read_b128 v[52:55], v35 offset:240
	v_pk_fma_f32 v[30:31], v[72:73], v[30:31], v[74:75] op_sel_hi:[1,1,0]
	ds_read_b128 v[72:75], v35 offset:144
	v_pk_fma_f32 v[78:79], v[40:41], v[76:77], v[82:83] op_sel_hi:[1,0,1] neg_lo:[0,0,1] neg_hi:[0,0,1]
	v_pk_fma_f32 v[80:81], v[38:39], v[76:77], v[80:81] op_sel_hi:[1,0,1] neg_lo:[0,0,1] neg_hi:[0,0,1]
	ds_read_b128 v[38:41], v35 offset:160
	v_pk_fma_f32 v[66:67], v[76:77], v[50:51], v[66:67] op_sel_hi:[0,1,1] neg_lo:[0,0,1] neg_hi:[0,0,1]
	v_pk_fma_f32 v[64:65], v[76:77], v[48:49], v[64:65] op_sel_hi:[0,1,1] neg_lo:[0,0,1] neg_hi:[0,0,1]
	ds_read_b128 v[48:51], v35 offset:176
	s_waitcnt lgkmcnt(6)
	v_pk_mul_f32 v[22:23], v[22:23], v[30:31] op_sel_hi:[1,0]
	v_pk_mul_f32 v[20:21], v[20:21], v[30:31] op_sel_hi:[1,0]
	s_waitcnt lgkmcnt(5)
	v_pk_mul_f32 v[58:59], v[30:31], v[58:59] op_sel_hi:[0,1]
	v_pk_mul_f32 v[56:57], v[30:31], v[56:57] op_sel_hi:[0,1]
	s_waitcnt lgkmcnt(4)
	v_pk_mul_f32 v[44:45], v[30:31], v[44:45] op_sel_hi:[0,1]
	v_pk_mul_f32 v[42:43], v[30:31], v[42:43] op_sel_hi:[0,1]
	s_waitcnt lgkmcnt(3)
	v_pk_mul_f32 v[54:55], v[30:31], v[54:55] op_sel_hi:[0,1]
	v_pk_mul_f32 v[30:31], v[30:31], v[52:53] op_sel_hi:[0,1]
	v_pk_fma_f32 v[16:17], v[16:17], v[28:29], v[20:21] op_sel_hi:[1,0,1] neg_lo:[0,0,1] neg_hi:[0,0,1]
	v_pk_fma_f32 v[18:19], v[18:19], v[28:29], v[22:23] op_sel_hi:[1,0,1] neg_lo:[0,0,1] neg_hi:[0,0,1]
	s_waitcnt lgkmcnt(2)
	v_pk_fma_f32 v[20:21], v[72:73], v[28:29], v[56:57] op_sel_hi:[1,0,1] neg_lo:[0,0,1] neg_hi:[0,0,1]
	v_pk_fma_f32 v[22:23], v[74:75], v[28:29], v[58:59] op_sel_hi:[1,0,1] neg_lo:[0,0,1] neg_hi:[0,0,1]
	s_waitcnt lgkmcnt(1)
	v_pk_fma_f32 v[38:39], v[28:29], v[38:39], v[42:43] op_sel_hi:[0,1,1] neg_lo:[0,0,1] neg_hi:[0,0,1]
	v_pk_fma_f32 v[40:41], v[28:29], v[40:41], v[44:45] op_sel_hi:[0,1,1] neg_lo:[0,0,1] neg_hi:[0,0,1]
	s_waitcnt lgkmcnt(0)
	v_pk_fma_f32 v[30:31], v[28:29], v[48:49], v[30:31] op_sel_hi:[0,1,1] neg_lo:[0,0,1] neg_hi:[0,0,1]
	v_pk_fma_f32 v[28:29], v[28:29], v[50:51], v[54:55] op_sel_hi:[0,1,1] neg_lo:[0,0,1] neg_hi:[0,0,1]
	v_pk_add_f32 v[12:13], v[12:13], v[80:81]
	v_pk_add_f32 v[14:15], v[14:15], v[78:79]
	v_pk_add_f32 v[8:9], v[8:9], v[60:61]
	v_pk_add_f32 v[10:11], v[10:11], v[62:63]
	v_pk_add_f32 v[4:5], v[4:5], v[64:65]
	v_pk_add_f32 v[6:7], v[6:7], v[66:67]
	v_pk_add_f32 v[0:1], v[0:1], v[68:69]
	v_pk_add_f32 v[2:3], v[2:3], v[70:71]
	v_add_u32_e32 v35, 0x100, v35
	v_pk_add_f32 v[14:15], v[14:15], v[18:19]
	v_pk_add_f32 v[12:13], v[12:13], v[16:17]
	v_pk_add_f32 v[10:11], v[10:11], v[22:23]
	v_pk_add_f32 v[8:9], v[8:9], v[20:21]
	v_pk_add_f32 v[6:7], v[6:7], v[40:41]
	v_pk_add_f32 v[4:5], v[4:5], v[38:39]
	v_pk_add_f32 v[2:3], v[2:3], v[28:29]
	v_pk_add_f32 v[0:1], v[0:1], v[30:31]
	v_lshl_add_u64 v[16:17], v[24:25], 0, s[0:1]
	v_lshl_add_u64 v[18:19], v[26:27], 0, s[0:1]
	s_waitcnt vmcnt(24)
	v_mov_b32_e32 v72, v98
	v_mov_b32_e32 v73, v99
	v_mov_b32_e32 v74, v190
	v_mov_b32_e32 v75, v191
	ds_read2_b64 v[28:31], v36 offset1:17
	ds_read_b128 v[38:41], v35
	ds_read_b128 v[42:45], v35 offset:16
	ds_read_b128 v[48:51], v35 offset:32
	ds_read_b128 v[52:55], v35 offset:48
	ds_read_b128 v[56:59], v35 offset:64
	ds_read_b128 v[60:63], v35 offset:80
	ds_read_b128 v[64:67], v35 offset:96
	ds_read_b128 v[68:71], v35 offset:112
	ds_read_b128 v[16:19], v35 offset:128
	ds_read_b128 v[20:23], v35 offset:192
	s_add_u32 s0, s0, 8
	s_addc_u32 s1, s1, 0
	v_add_u32_e32 v36, 0x110, v36
	s_cmpk_eq_i32 s0, 0x100
	v_mov_b32_e32 v76, v72
	v_mov_b32_e32 v77, v74
	s_waitcnt lgkmcnt(10)
	v_mul_f32_e32 v78, v74, v29
	v_mov_b32_e32 v80, v74
	v_mov_b32_e32 v81, v72
	v_mul_f32_e32 v72, v72, v29
	v_pk_fma_f32 v[76:77], v[76:77], v[28:29], v[78:79] op_sel_hi:[1,1,0] neg_lo:[0,0,1] neg_hi:[0,0,1]
	v_pk_fma_f32 v[78:79], v[80:81], v[28:29], v[72:73] op_sel_hi:[1,1,0]
	v_mov_b32_e32 v74, v73
	v_mul_f32_e32 v28, v75, v31
	s_waitcnt lgkmcnt(4)
	v_pk_mul_f32 v[60:61], v[78:79], v[60:61] op_sel_hi:[0,1]
	v_pk_mul_f32 v[62:63], v[78:79], v[62:63] op_sel_hi:[0,1]
	s_waitcnt lgkmcnt(2)
	v_pk_mul_f32 v[68:69], v[78:79], v[68:69] op_sel_hi:[0,1]
	v_pk_mul_f32 v[70:71], v[78:79], v[70:71] op_sel_hi:[0,1]
	v_mov_b32_e32 v72, v75
	v_pk_fma_f32 v[28:29], v[74:75], v[30:31], v[28:29] op_sel_hi:[1,1,0] neg_lo:[0,0,1] neg_hi:[0,0,1]
	v_mul_f32_e32 v74, v73, v31
	v_pk_mul_f32 v[80:81], v[56:57], v[78:79] op_sel_hi:[1,0]
	v_pk_mul_f32 v[82:83], v[58:59], v[78:79] op_sel_hi:[1,0]
	v_pk_mul_f32 v[64:65], v[78:79], v[64:65] op_sel_hi:[0,1]
	v_pk_mul_f32 v[66:67], v[78:79], v[66:67] op_sel_hi:[0,1]
	ds_read_b128 v[56:59], v35 offset:208
	v_pk_fma_f32 v[62:63], v[44:45], v[76:77], v[62:63] op_sel_hi:[1,0,1] neg_lo:[0,0,1] neg_hi:[0,0,1]
	v_pk_fma_f32 v[60:61], v[42:43], v[76:77], v[60:61] op_sel_hi:[1,0,1] neg_lo:[0,0,1] neg_hi:[0,0,1]
	ds_read_b128 v[42:45], v35 offset:224
	v_pk_fma_f32 v[70:71], v[76:77], v[54:55], v[70:71] op_sel_hi:[0,1,1] neg_lo:[0,0,1] neg_hi:[0,0,1]
	v_pk_fma_f32 v[68:69], v[76:77], v[52:53], v[68:69] op_sel_hi:[0,1,1] neg_lo:[0,0,1] neg_hi:[0,0,1]
	ds_read_b128 v[52:55], v35 offset:240
	v_pk_fma_f32 v[30:31], v[72:73], v[30:31], v[74:75] op_sel_hi:[1,1,0]
	ds_read_b128 v[72:75], v35 offset:144
	v_pk_fma_f32 v[78:79], v[40:41], v[76:77], v[82:83] op_sel_hi:[1,0,1] neg_lo:[0,0,1] neg_hi:[0,0,1]
	v_pk_fma_f32 v[80:81], v[38:39], v[76:77], v[80:81] op_sel_hi:[1,0,1] neg_lo:[0,0,1] neg_hi:[0,0,1]
	ds_read_b128 v[38:41], v35 offset:160
	v_pk_fma_f32 v[66:67], v[76:77], v[50:51], v[66:67] op_sel_hi:[0,1,1] neg_lo:[0,0,1] neg_hi:[0,0,1]
	v_pk_fma_f32 v[64:65], v[76:77], v[48:49], v[64:65] op_sel_hi:[0,1,1] neg_lo:[0,0,1] neg_hi:[0,0,1]
	ds_read_b128 v[48:51], v35 offset:176
	s_waitcnt lgkmcnt(6)
	v_pk_mul_f32 v[22:23], v[22:23], v[30:31] op_sel_hi:[1,0]
	v_pk_mul_f32 v[20:21], v[20:21], v[30:31] op_sel_hi:[1,0]
	s_waitcnt lgkmcnt(5)
	v_pk_mul_f32 v[58:59], v[30:31], v[58:59] op_sel_hi:[0,1]
	v_pk_mul_f32 v[56:57], v[30:31], v[56:57] op_sel_hi:[0,1]
	s_waitcnt lgkmcnt(4)
	v_pk_mul_f32 v[44:45], v[30:31], v[44:45] op_sel_hi:[0,1]
	v_pk_mul_f32 v[42:43], v[30:31], v[42:43] op_sel_hi:[0,1]
	s_waitcnt lgkmcnt(3)
	v_pk_mul_f32 v[54:55], v[30:31], v[54:55] op_sel_hi:[0,1]
	v_pk_mul_f32 v[30:31], v[30:31], v[52:53] op_sel_hi:[0,1]
	v_pk_fma_f32 v[16:17], v[16:17], v[28:29], v[20:21] op_sel_hi:[1,0,1] neg_lo:[0,0,1] neg_hi:[0,0,1]
	v_pk_fma_f32 v[18:19], v[18:19], v[28:29], v[22:23] op_sel_hi:[1,0,1] neg_lo:[0,0,1] neg_hi:[0,0,1]
	s_waitcnt lgkmcnt(2)
	v_pk_fma_f32 v[20:21], v[72:73], v[28:29], v[56:57] op_sel_hi:[1,0,1] neg_lo:[0,0,1] neg_hi:[0,0,1]
	v_pk_fma_f32 v[22:23], v[74:75], v[28:29], v[58:59] op_sel_hi:[1,0,1] neg_lo:[0,0,1] neg_hi:[0,0,1]
	s_waitcnt lgkmcnt(1)
	v_pk_fma_f32 v[38:39], v[28:29], v[38:39], v[42:43] op_sel_hi:[0,1,1] neg_lo:[0,0,1] neg_hi:[0,0,1]
	v_pk_fma_f32 v[40:41], v[28:29], v[40:41], v[44:45] op_sel_hi:[0,1,1] neg_lo:[0,0,1] neg_hi:[0,0,1]
	s_waitcnt lgkmcnt(0)
	v_pk_fma_f32 v[30:31], v[28:29], v[48:49], v[30:31] op_sel_hi:[0,1,1] neg_lo:[0,0,1] neg_hi:[0,0,1]
	v_pk_fma_f32 v[28:29], v[28:29], v[50:51], v[54:55] op_sel_hi:[0,1,1] neg_lo:[0,0,1] neg_hi:[0,0,1]
	v_pk_add_f32 v[12:13], v[12:13], v[80:81]
	v_pk_add_f32 v[14:15], v[14:15], v[78:79]
	v_pk_add_f32 v[8:9], v[8:9], v[60:61]
	v_pk_add_f32 v[10:11], v[10:11], v[62:63]
	v_pk_add_f32 v[4:5], v[4:5], v[64:65]
	v_pk_add_f32 v[6:7], v[6:7], v[66:67]
	v_pk_add_f32 v[0:1], v[0:1], v[68:69]
	v_pk_add_f32 v[2:3], v[2:3], v[70:71]
	v_add_u32_e32 v35, 0x100, v35
	v_pk_add_f32 v[14:15], v[14:15], v[18:19]
	v_pk_add_f32 v[12:13], v[12:13], v[16:17]
	v_pk_add_f32 v[10:11], v[10:11], v[22:23]
	v_pk_add_f32 v[8:9], v[8:9], v[20:21]
	v_pk_add_f32 v[6:7], v[6:7], v[40:41]
	v_pk_add_f32 v[4:5], v[4:5], v[38:39]
	v_pk_add_f32 v[2:3], v[2:3], v[28:29]
	v_pk_add_f32 v[0:1], v[0:1], v[30:31]
	v_lshl_add_u64 v[16:17], v[24:25], 0, s[0:1]
	v_lshl_add_u64 v[18:19], v[26:27], 0, s[0:1]
	s_waitcnt vmcnt(22)
	v_mov_b32_e32 v72, v100
	v_mov_b32_e32 v73, v101
	v_mov_b32_e32 v74, v192
	v_mov_b32_e32 v75, v193
	ds_read2_b64 v[28:31], v36 offset1:17
	ds_read_b128 v[38:41], v35
	ds_read_b128 v[42:45], v35 offset:16
	ds_read_b128 v[48:51], v35 offset:32
	ds_read_b128 v[52:55], v35 offset:48
	ds_read_b128 v[56:59], v35 offset:64
	ds_read_b128 v[60:63], v35 offset:80
	ds_read_b128 v[64:67], v35 offset:96
	ds_read_b128 v[68:71], v35 offset:112
	ds_read_b128 v[16:19], v35 offset:128
	ds_read_b128 v[20:23], v35 offset:192
	s_add_u32 s0, s0, 8
	s_addc_u32 s1, s1, 0
	v_add_u32_e32 v36, 0x110, v36
	s_cmpk_eq_i32 s0, 0x100
	v_mov_b32_e32 v76, v72
	v_mov_b32_e32 v77, v74
	s_waitcnt lgkmcnt(10)
	v_mul_f32_e32 v78, v74, v29
	v_mov_b32_e32 v80, v74
	v_mov_b32_e32 v81, v72
	v_mul_f32_e32 v72, v72, v29
	v_pk_fma_f32 v[76:77], v[76:77], v[28:29], v[78:79] op_sel_hi:[1,1,0] neg_lo:[0,0,1] neg_hi:[0,0,1]
	v_pk_fma_f32 v[78:79], v[80:81], v[28:29], v[72:73] op_sel_hi:[1,1,0]
	v_mov_b32_e32 v74, v73
	v_mul_f32_e32 v28, v75, v31
	s_waitcnt lgkmcnt(4)
	v_pk_mul_f32 v[60:61], v[78:79], v[60:61] op_sel_hi:[0,1]
	v_pk_mul_f32 v[62:63], v[78:79], v[62:63] op_sel_hi:[0,1]
	s_waitcnt lgkmcnt(2)
	v_pk_mul_f32 v[68:69], v[78:79], v[68:69] op_sel_hi:[0,1]
	v_pk_mul_f32 v[70:71], v[78:79], v[70:71] op_sel_hi:[0,1]
	v_mov_b32_e32 v72, v75
	v_pk_fma_f32 v[28:29], v[74:75], v[30:31], v[28:29] op_sel_hi:[1,1,0] neg_lo:[0,0,1] neg_hi:[0,0,1]
	v_mul_f32_e32 v74, v73, v31
	v_pk_mul_f32 v[80:81], v[56:57], v[78:79] op_sel_hi:[1,0]
	v_pk_mul_f32 v[82:83], v[58:59], v[78:79] op_sel_hi:[1,0]
	v_pk_mul_f32 v[64:65], v[78:79], v[64:65] op_sel_hi:[0,1]
	v_pk_mul_f32 v[66:67], v[78:79], v[66:67] op_sel_hi:[0,1]
	ds_read_b128 v[56:59], v35 offset:208
	v_pk_fma_f32 v[62:63], v[44:45], v[76:77], v[62:63] op_sel_hi:[1,0,1] neg_lo:[0,0,1] neg_hi:[0,0,1]
	v_pk_fma_f32 v[60:61], v[42:43], v[76:77], v[60:61] op_sel_hi:[1,0,1] neg_lo:[0,0,1] neg_hi:[0,0,1]
	ds_read_b128 v[42:45], v35 offset:224
	v_pk_fma_f32 v[70:71], v[76:77], v[54:55], v[70:71] op_sel_hi:[0,1,1] neg_lo:[0,0,1] neg_hi:[0,0,1]
	v_pk_fma_f32 v[68:69], v[76:77], v[52:53], v[68:69] op_sel_hi:[0,1,1] neg_lo:[0,0,1] neg_hi:[0,0,1]
	ds_read_b128 v[52:55], v35 offset:240
	v_pk_fma_f32 v[30:31], v[72:73], v[30:31], v[74:75] op_sel_hi:[1,1,0]
	ds_read_b128 v[72:75], v35 offset:144
	v_pk_fma_f32 v[78:79], v[40:41], v[76:77], v[82:83] op_sel_hi:[1,0,1] neg_lo:[0,0,1] neg_hi:[0,0,1]
	v_pk_fma_f32 v[80:81], v[38:39], v[76:77], v[80:81] op_sel_hi:[1,0,1] neg_lo:[0,0,1] neg_hi:[0,0,1]
	ds_read_b128 v[38:41], v35 offset:160
	v_pk_fma_f32 v[66:67], v[76:77], v[50:51], v[66:67] op_sel_hi:[0,1,1] neg_lo:[0,0,1] neg_hi:[0,0,1]
	v_pk_fma_f32 v[64:65], v[76:77], v[48:49], v[64:65] op_sel_hi:[0,1,1] neg_lo:[0,0,1] neg_hi:[0,0,1]
	ds_read_b128 v[48:51], v35 offset:176
	s_waitcnt lgkmcnt(6)
	v_pk_mul_f32 v[22:23], v[22:23], v[30:31] op_sel_hi:[1,0]
	v_pk_mul_f32 v[20:21], v[20:21], v[30:31] op_sel_hi:[1,0]
	s_waitcnt lgkmcnt(5)
	v_pk_mul_f32 v[58:59], v[30:31], v[58:59] op_sel_hi:[0,1]
	v_pk_mul_f32 v[56:57], v[30:31], v[56:57] op_sel_hi:[0,1]
	s_waitcnt lgkmcnt(4)
	v_pk_mul_f32 v[44:45], v[30:31], v[44:45] op_sel_hi:[0,1]
	v_pk_mul_f32 v[42:43], v[30:31], v[42:43] op_sel_hi:[0,1]
	s_waitcnt lgkmcnt(3)
	v_pk_mul_f32 v[54:55], v[30:31], v[54:55] op_sel_hi:[0,1]
	v_pk_mul_f32 v[30:31], v[30:31], v[52:53] op_sel_hi:[0,1]
	v_pk_fma_f32 v[16:17], v[16:17], v[28:29], v[20:21] op_sel_hi:[1,0,1] neg_lo:[0,0,1] neg_hi:[0,0,1]
	v_pk_fma_f32 v[18:19], v[18:19], v[28:29], v[22:23] op_sel_hi:[1,0,1] neg_lo:[0,0,1] neg_hi:[0,0,1]
	s_waitcnt lgkmcnt(2)
	v_pk_fma_f32 v[20:21], v[72:73], v[28:29], v[56:57] op_sel_hi:[1,0,1] neg_lo:[0,0,1] neg_hi:[0,0,1]
	v_pk_fma_f32 v[22:23], v[74:75], v[28:29], v[58:59] op_sel_hi:[1,0,1] neg_lo:[0,0,1] neg_hi:[0,0,1]
	s_waitcnt lgkmcnt(1)
	v_pk_fma_f32 v[38:39], v[28:29], v[38:39], v[42:43] op_sel_hi:[0,1,1] neg_lo:[0,0,1] neg_hi:[0,0,1]
	v_pk_fma_f32 v[40:41], v[28:29], v[40:41], v[44:45] op_sel_hi:[0,1,1] neg_lo:[0,0,1] neg_hi:[0,0,1]
	s_waitcnt lgkmcnt(0)
	v_pk_fma_f32 v[30:31], v[28:29], v[48:49], v[30:31] op_sel_hi:[0,1,1] neg_lo:[0,0,1] neg_hi:[0,0,1]
	v_pk_fma_f32 v[28:29], v[28:29], v[50:51], v[54:55] op_sel_hi:[0,1,1] neg_lo:[0,0,1] neg_hi:[0,0,1]
	v_pk_add_f32 v[12:13], v[12:13], v[80:81]
	v_pk_add_f32 v[14:15], v[14:15], v[78:79]
	v_pk_add_f32 v[8:9], v[8:9], v[60:61]
	v_pk_add_f32 v[10:11], v[10:11], v[62:63]
	v_pk_add_f32 v[4:5], v[4:5], v[64:65]
	v_pk_add_f32 v[6:7], v[6:7], v[66:67]
	v_pk_add_f32 v[0:1], v[0:1], v[68:69]
	v_pk_add_f32 v[2:3], v[2:3], v[70:71]
	v_add_u32_e32 v35, 0x100, v35
	v_pk_add_f32 v[14:15], v[14:15], v[18:19]
	v_pk_add_f32 v[12:13], v[12:13], v[16:17]
	v_pk_add_f32 v[10:11], v[10:11], v[22:23]
	v_pk_add_f32 v[8:9], v[8:9], v[20:21]
	v_pk_add_f32 v[6:7], v[6:7], v[40:41]
	v_pk_add_f32 v[4:5], v[4:5], v[38:39]
	v_pk_add_f32 v[2:3], v[2:3], v[28:29]
	v_pk_add_f32 v[0:1], v[0:1], v[30:31]
	v_lshl_add_u64 v[16:17], v[24:25], 0, s[0:1]
	v_lshl_add_u64 v[18:19], v[26:27], 0, s[0:1]
	s_waitcnt vmcnt(22)
	v_mov_b32_e32 v72, v102
	v_mov_b32_e32 v73, v103
	v_mov_b32_e32 v74, v194
	v_mov_b32_e32 v75, v195
	ds_read2_b64 v[28:31], v36 offset1:17
	ds_read_b128 v[38:41], v35
	ds_read_b128 v[42:45], v35 offset:16
	ds_read_b128 v[48:51], v35 offset:32
	ds_read_b128 v[52:55], v35 offset:48
	ds_read_b128 v[56:59], v35 offset:64
	ds_read_b128 v[60:63], v35 offset:80
	ds_read_b128 v[64:67], v35 offset:96
	ds_read_b128 v[68:71], v35 offset:112
	ds_read_b128 v[16:19], v35 offset:128
	ds_read_b128 v[20:23], v35 offset:192
	s_add_u32 s0, s0, 8
	s_addc_u32 s1, s1, 0
	v_add_u32_e32 v36, 0x110, v36
	s_cmpk_eq_i32 s0, 0x100
	v_mov_b32_e32 v76, v72
	v_mov_b32_e32 v77, v74
	s_waitcnt lgkmcnt(10)
	v_mul_f32_e32 v78, v74, v29
	v_mov_b32_e32 v80, v74
	v_mov_b32_e32 v81, v72
	v_mul_f32_e32 v72, v72, v29
	v_pk_fma_f32 v[76:77], v[76:77], v[28:29], v[78:79] op_sel_hi:[1,1,0] neg_lo:[0,0,1] neg_hi:[0,0,1]
	v_pk_fma_f32 v[78:79], v[80:81], v[28:29], v[72:73] op_sel_hi:[1,1,0]
	v_mov_b32_e32 v74, v73
	v_mul_f32_e32 v28, v75, v31
	s_waitcnt lgkmcnt(4)
	v_pk_mul_f32 v[60:61], v[78:79], v[60:61] op_sel_hi:[0,1]
	v_pk_mul_f32 v[62:63], v[78:79], v[62:63] op_sel_hi:[0,1]
	s_waitcnt lgkmcnt(2)
	v_pk_mul_f32 v[68:69], v[78:79], v[68:69] op_sel_hi:[0,1]
	v_pk_mul_f32 v[70:71], v[78:79], v[70:71] op_sel_hi:[0,1]
	v_mov_b32_e32 v72, v75
	v_pk_fma_f32 v[28:29], v[74:75], v[30:31], v[28:29] op_sel_hi:[1,1,0] neg_lo:[0,0,1] neg_hi:[0,0,1]
	v_mul_f32_e32 v74, v73, v31
	v_pk_mul_f32 v[80:81], v[56:57], v[78:79] op_sel_hi:[1,0]
	v_pk_mul_f32 v[82:83], v[58:59], v[78:79] op_sel_hi:[1,0]
	v_pk_mul_f32 v[64:65], v[78:79], v[64:65] op_sel_hi:[0,1]
	v_pk_mul_f32 v[66:67], v[78:79], v[66:67] op_sel_hi:[0,1]
	ds_read_b128 v[56:59], v35 offset:208
	v_pk_fma_f32 v[62:63], v[44:45], v[76:77], v[62:63] op_sel_hi:[1,0,1] neg_lo:[0,0,1] neg_hi:[0,0,1]
	v_pk_fma_f32 v[60:61], v[42:43], v[76:77], v[60:61] op_sel_hi:[1,0,1] neg_lo:[0,0,1] neg_hi:[0,0,1]
	ds_read_b128 v[42:45], v35 offset:224
	v_pk_fma_f32 v[70:71], v[76:77], v[54:55], v[70:71] op_sel_hi:[0,1,1] neg_lo:[0,0,1] neg_hi:[0,0,1]
	v_pk_fma_f32 v[68:69], v[76:77], v[52:53], v[68:69] op_sel_hi:[0,1,1] neg_lo:[0,0,1] neg_hi:[0,0,1]
	ds_read_b128 v[52:55], v35 offset:240
	v_pk_fma_f32 v[30:31], v[72:73], v[30:31], v[74:75] op_sel_hi:[1,1,0]
	ds_read_b128 v[72:75], v35 offset:144
	v_pk_fma_f32 v[78:79], v[40:41], v[76:77], v[82:83] op_sel_hi:[1,0,1] neg_lo:[0,0,1] neg_hi:[0,0,1]
	v_pk_fma_f32 v[80:81], v[38:39], v[76:77], v[80:81] op_sel_hi:[1,0,1] neg_lo:[0,0,1] neg_hi:[0,0,1]
	ds_read_b128 v[38:41], v35 offset:160
	v_pk_fma_f32 v[66:67], v[76:77], v[50:51], v[66:67] op_sel_hi:[0,1,1] neg_lo:[0,0,1] neg_hi:[0,0,1]
	v_pk_fma_f32 v[64:65], v[76:77], v[48:49], v[64:65] op_sel_hi:[0,1,1] neg_lo:[0,0,1] neg_hi:[0,0,1]
	ds_read_b128 v[48:51], v35 offset:176
	s_waitcnt lgkmcnt(6)
	v_pk_mul_f32 v[22:23], v[22:23], v[30:31] op_sel_hi:[1,0]
	v_pk_mul_f32 v[20:21], v[20:21], v[30:31] op_sel_hi:[1,0]
	s_waitcnt lgkmcnt(5)
	v_pk_mul_f32 v[58:59], v[30:31], v[58:59] op_sel_hi:[0,1]
	v_pk_mul_f32 v[56:57], v[30:31], v[56:57] op_sel_hi:[0,1]
	s_waitcnt lgkmcnt(4)
	v_pk_mul_f32 v[44:45], v[30:31], v[44:45] op_sel_hi:[0,1]
	v_pk_mul_f32 v[42:43], v[30:31], v[42:43] op_sel_hi:[0,1]
	s_waitcnt lgkmcnt(3)
	v_pk_mul_f32 v[54:55], v[30:31], v[54:55] op_sel_hi:[0,1]
	v_pk_mul_f32 v[30:31], v[30:31], v[52:53] op_sel_hi:[0,1]
	v_pk_fma_f32 v[16:17], v[16:17], v[28:29], v[20:21] op_sel_hi:[1,0,1] neg_lo:[0,0,1] neg_hi:[0,0,1]
	v_pk_fma_f32 v[18:19], v[18:19], v[28:29], v[22:23] op_sel_hi:[1,0,1] neg_lo:[0,0,1] neg_hi:[0,0,1]
	s_waitcnt lgkmcnt(2)
	v_pk_fma_f32 v[20:21], v[72:73], v[28:29], v[56:57] op_sel_hi:[1,0,1] neg_lo:[0,0,1] neg_hi:[0,0,1]
	v_pk_fma_f32 v[22:23], v[74:75], v[28:29], v[58:59] op_sel_hi:[1,0,1] neg_lo:[0,0,1] neg_hi:[0,0,1]
	s_waitcnt lgkmcnt(1)
	v_pk_fma_f32 v[38:39], v[28:29], v[38:39], v[42:43] op_sel_hi:[0,1,1] neg_lo:[0,0,1] neg_hi:[0,0,1]
	v_pk_fma_f32 v[40:41], v[28:29], v[40:41], v[44:45] op_sel_hi:[0,1,1] neg_lo:[0,0,1] neg_hi:[0,0,1]
	s_waitcnt lgkmcnt(0)
	v_pk_fma_f32 v[30:31], v[28:29], v[48:49], v[30:31] op_sel_hi:[0,1,1] neg_lo:[0,0,1] neg_hi:[0,0,1]
	v_pk_fma_f32 v[28:29], v[28:29], v[50:51], v[54:55] op_sel_hi:[0,1,1] neg_lo:[0,0,1] neg_hi:[0,0,1]
	v_pk_add_f32 v[12:13], v[12:13], v[80:81]
	v_pk_add_f32 v[14:15], v[14:15], v[78:79]
	v_pk_add_f32 v[8:9], v[8:9], v[60:61]
	v_pk_add_f32 v[10:11], v[10:11], v[62:63]
	v_pk_add_f32 v[4:5], v[4:5], v[64:65]
	v_pk_add_f32 v[6:7], v[6:7], v[66:67]
	v_pk_add_f32 v[0:1], v[0:1], v[68:69]
	v_pk_add_f32 v[2:3], v[2:3], v[70:71]
	v_add_u32_e32 v35, 0x100, v35
	v_pk_add_f32 v[14:15], v[14:15], v[18:19]
	v_pk_add_f32 v[12:13], v[12:13], v[16:17]
	v_pk_add_f32 v[10:11], v[10:11], v[22:23]
	v_pk_add_f32 v[8:9], v[8:9], v[20:21]
	v_pk_add_f32 v[6:7], v[6:7], v[40:41]
	v_pk_add_f32 v[4:5], v[4:5], v[38:39]
	v_pk_add_f32 v[2:3], v[2:3], v[28:29]
	v_pk_add_f32 v[0:1], v[0:1], v[30:31]
	v_lshl_add_u64 v[16:17], v[24:25], 0, s[0:1]
	v_lshl_add_u64 v[18:19], v[26:27], 0, s[0:1]
	s_waitcnt vmcnt(20)
	v_mov_b32_e32 v72, v104
	v_mov_b32_e32 v73, v105
	v_mov_b32_e32 v74, v196
	v_mov_b32_e32 v75, v197
	ds_read2_b64 v[28:31], v36 offset1:17
	ds_read_b128 v[38:41], v35
	ds_read_b128 v[42:45], v35 offset:16
	ds_read_b128 v[48:51], v35 offset:32
	ds_read_b128 v[52:55], v35 offset:48
	ds_read_b128 v[56:59], v35 offset:64
	ds_read_b128 v[60:63], v35 offset:80
	ds_read_b128 v[64:67], v35 offset:96
	ds_read_b128 v[68:71], v35 offset:112
	ds_read_b128 v[16:19], v35 offset:128
	ds_read_b128 v[20:23], v35 offset:192
	s_add_u32 s0, s0, 8
	s_addc_u32 s1, s1, 0
	v_add_u32_e32 v36, 0x110, v36
	s_cmpk_eq_i32 s0, 0x100
	v_mov_b32_e32 v76, v72
	v_mov_b32_e32 v77, v74
	s_waitcnt lgkmcnt(10)
	v_mul_f32_e32 v78, v74, v29
	v_mov_b32_e32 v80, v74
	v_mov_b32_e32 v81, v72
	v_mul_f32_e32 v72, v72, v29
	v_pk_fma_f32 v[76:77], v[76:77], v[28:29], v[78:79] op_sel_hi:[1,1,0] neg_lo:[0,0,1] neg_hi:[0,0,1]
	v_pk_fma_f32 v[78:79], v[80:81], v[28:29], v[72:73] op_sel_hi:[1,1,0]
	v_mov_b32_e32 v74, v73
	v_mul_f32_e32 v28, v75, v31
	s_waitcnt lgkmcnt(4)
	v_pk_mul_f32 v[60:61], v[78:79], v[60:61] op_sel_hi:[0,1]
	v_pk_mul_f32 v[62:63], v[78:79], v[62:63] op_sel_hi:[0,1]
	s_waitcnt lgkmcnt(2)
	v_pk_mul_f32 v[68:69], v[78:79], v[68:69] op_sel_hi:[0,1]
	v_pk_mul_f32 v[70:71], v[78:79], v[70:71] op_sel_hi:[0,1]
	v_mov_b32_e32 v72, v75
	v_pk_fma_f32 v[28:29], v[74:75], v[30:31], v[28:29] op_sel_hi:[1,1,0] neg_lo:[0,0,1] neg_hi:[0,0,1]
	v_mul_f32_e32 v74, v73, v31
	v_pk_mul_f32 v[80:81], v[56:57], v[78:79] op_sel_hi:[1,0]
	v_pk_mul_f32 v[82:83], v[58:59], v[78:79] op_sel_hi:[1,0]
	v_pk_mul_f32 v[64:65], v[78:79], v[64:65] op_sel_hi:[0,1]
	v_pk_mul_f32 v[66:67], v[78:79], v[66:67] op_sel_hi:[0,1]
	ds_read_b128 v[56:59], v35 offset:208
	v_pk_fma_f32 v[62:63], v[44:45], v[76:77], v[62:63] op_sel_hi:[1,0,1] neg_lo:[0,0,1] neg_hi:[0,0,1]
	v_pk_fma_f32 v[60:61], v[42:43], v[76:77], v[60:61] op_sel_hi:[1,0,1] neg_lo:[0,0,1] neg_hi:[0,0,1]
	ds_read_b128 v[42:45], v35 offset:224
	v_pk_fma_f32 v[70:71], v[76:77], v[54:55], v[70:71] op_sel_hi:[0,1,1] neg_lo:[0,0,1] neg_hi:[0,0,1]
	v_pk_fma_f32 v[68:69], v[76:77], v[52:53], v[68:69] op_sel_hi:[0,1,1] neg_lo:[0,0,1] neg_hi:[0,0,1]
	ds_read_b128 v[52:55], v35 offset:240
	v_pk_fma_f32 v[30:31], v[72:73], v[30:31], v[74:75] op_sel_hi:[1,1,0]
	ds_read_b128 v[72:75], v35 offset:144
	v_pk_fma_f32 v[78:79], v[40:41], v[76:77], v[82:83] op_sel_hi:[1,0,1] neg_lo:[0,0,1] neg_hi:[0,0,1]
	v_pk_fma_f32 v[80:81], v[38:39], v[76:77], v[80:81] op_sel_hi:[1,0,1] neg_lo:[0,0,1] neg_hi:[0,0,1]
	ds_read_b128 v[38:41], v35 offset:160
	v_pk_fma_f32 v[66:67], v[76:77], v[50:51], v[66:67] op_sel_hi:[0,1,1] neg_lo:[0,0,1] neg_hi:[0,0,1]
	v_pk_fma_f32 v[64:65], v[76:77], v[48:49], v[64:65] op_sel_hi:[0,1,1] neg_lo:[0,0,1] neg_hi:[0,0,1]
	ds_read_b128 v[48:51], v35 offset:176
	s_waitcnt lgkmcnt(6)
	v_pk_mul_f32 v[22:23], v[22:23], v[30:31] op_sel_hi:[1,0]
	v_pk_mul_f32 v[20:21], v[20:21], v[30:31] op_sel_hi:[1,0]
	s_waitcnt lgkmcnt(5)
	v_pk_mul_f32 v[58:59], v[30:31], v[58:59] op_sel_hi:[0,1]
	v_pk_mul_f32 v[56:57], v[30:31], v[56:57] op_sel_hi:[0,1]
	s_waitcnt lgkmcnt(4)
	v_pk_mul_f32 v[44:45], v[30:31], v[44:45] op_sel_hi:[0,1]
	v_pk_mul_f32 v[42:43], v[30:31], v[42:43] op_sel_hi:[0,1]
	s_waitcnt lgkmcnt(3)
	v_pk_mul_f32 v[54:55], v[30:31], v[54:55] op_sel_hi:[0,1]
	v_pk_mul_f32 v[30:31], v[30:31], v[52:53] op_sel_hi:[0,1]
	v_pk_fma_f32 v[16:17], v[16:17], v[28:29], v[20:21] op_sel_hi:[1,0,1] neg_lo:[0,0,1] neg_hi:[0,0,1]
	v_pk_fma_f32 v[18:19], v[18:19], v[28:29], v[22:23] op_sel_hi:[1,0,1] neg_lo:[0,0,1] neg_hi:[0,0,1]
	s_waitcnt lgkmcnt(2)
	v_pk_fma_f32 v[20:21], v[72:73], v[28:29], v[56:57] op_sel_hi:[1,0,1] neg_lo:[0,0,1] neg_hi:[0,0,1]
	v_pk_fma_f32 v[22:23], v[74:75], v[28:29], v[58:59] op_sel_hi:[1,0,1] neg_lo:[0,0,1] neg_hi:[0,0,1]
	s_waitcnt lgkmcnt(1)
	v_pk_fma_f32 v[38:39], v[28:29], v[38:39], v[42:43] op_sel_hi:[0,1,1] neg_lo:[0,0,1] neg_hi:[0,0,1]
	v_pk_fma_f32 v[40:41], v[28:29], v[40:41], v[44:45] op_sel_hi:[0,1,1] neg_lo:[0,0,1] neg_hi:[0,0,1]
	s_waitcnt lgkmcnt(0)
	v_pk_fma_f32 v[30:31], v[28:29], v[48:49], v[30:31] op_sel_hi:[0,1,1] neg_lo:[0,0,1] neg_hi:[0,0,1]
	v_pk_fma_f32 v[28:29], v[28:29], v[50:51], v[54:55] op_sel_hi:[0,1,1] neg_lo:[0,0,1] neg_hi:[0,0,1]
	v_pk_add_f32 v[12:13], v[12:13], v[80:81]
	v_pk_add_f32 v[14:15], v[14:15], v[78:79]
	v_pk_add_f32 v[8:9], v[8:9], v[60:61]
	v_pk_add_f32 v[10:11], v[10:11], v[62:63]
	v_pk_add_f32 v[4:5], v[4:5], v[64:65]
	v_pk_add_f32 v[6:7], v[6:7], v[66:67]
	v_pk_add_f32 v[0:1], v[0:1], v[68:69]
	v_pk_add_f32 v[2:3], v[2:3], v[70:71]
	v_add_u32_e32 v35, 0x100, v35
	v_pk_add_f32 v[14:15], v[14:15], v[18:19]
	v_pk_add_f32 v[12:13], v[12:13], v[16:17]
	v_pk_add_f32 v[10:11], v[10:11], v[22:23]
	v_pk_add_f32 v[8:9], v[8:9], v[20:21]
	v_pk_add_f32 v[6:7], v[6:7], v[40:41]
	v_pk_add_f32 v[4:5], v[4:5], v[38:39]
	v_pk_add_f32 v[2:3], v[2:3], v[28:29]
	v_pk_add_f32 v[0:1], v[0:1], v[30:31]
	v_lshl_add_u64 v[16:17], v[24:25], 0, s[0:1]
	v_lshl_add_u64 v[18:19], v[26:27], 0, s[0:1]
	s_waitcnt vmcnt(20)
	v_mov_b32_e32 v72, v106
	v_mov_b32_e32 v73, v107
	v_mov_b32_e32 v74, v198
	v_mov_b32_e32 v75, v199
	ds_read2_b64 v[28:31], v36 offset1:17
	ds_read_b128 v[38:41], v35
	ds_read_b128 v[42:45], v35 offset:16
	ds_read_b128 v[48:51], v35 offset:32
	ds_read_b128 v[52:55], v35 offset:48
	ds_read_b128 v[56:59], v35 offset:64
	ds_read_b128 v[60:63], v35 offset:80
	ds_read_b128 v[64:67], v35 offset:96
	ds_read_b128 v[68:71], v35 offset:112
	ds_read_b128 v[16:19], v35 offset:128
	ds_read_b128 v[20:23], v35 offset:192
	s_add_u32 s0, s0, 8
	s_addc_u32 s1, s1, 0
	v_add_u32_e32 v36, 0x110, v36
	s_cmpk_eq_i32 s0, 0x100
	v_mov_b32_e32 v76, v72
	v_mov_b32_e32 v77, v74
	s_waitcnt lgkmcnt(10)
	v_mul_f32_e32 v78, v74, v29
	v_mov_b32_e32 v80, v74
	v_mov_b32_e32 v81, v72
	v_mul_f32_e32 v72, v72, v29
	v_pk_fma_f32 v[76:77], v[76:77], v[28:29], v[78:79] op_sel_hi:[1,1,0] neg_lo:[0,0,1] neg_hi:[0,0,1]
	v_pk_fma_f32 v[78:79], v[80:81], v[28:29], v[72:73] op_sel_hi:[1,1,0]
	v_mov_b32_e32 v74, v73
	v_mul_f32_e32 v28, v75, v31
	s_waitcnt lgkmcnt(4)
	v_pk_mul_f32 v[60:61], v[78:79], v[60:61] op_sel_hi:[0,1]
	v_pk_mul_f32 v[62:63], v[78:79], v[62:63] op_sel_hi:[0,1]
	s_waitcnt lgkmcnt(2)
	v_pk_mul_f32 v[68:69], v[78:79], v[68:69] op_sel_hi:[0,1]
	v_pk_mul_f32 v[70:71], v[78:79], v[70:71] op_sel_hi:[0,1]
	v_mov_b32_e32 v72, v75
	v_pk_fma_f32 v[28:29], v[74:75], v[30:31], v[28:29] op_sel_hi:[1,1,0] neg_lo:[0,0,1] neg_hi:[0,0,1]
	v_mul_f32_e32 v74, v73, v31
	v_pk_mul_f32 v[80:81], v[56:57], v[78:79] op_sel_hi:[1,0]
	v_pk_mul_f32 v[82:83], v[58:59], v[78:79] op_sel_hi:[1,0]
	v_pk_mul_f32 v[64:65], v[78:79], v[64:65] op_sel_hi:[0,1]
	v_pk_mul_f32 v[66:67], v[78:79], v[66:67] op_sel_hi:[0,1]
	ds_read_b128 v[56:59], v35 offset:208
	v_pk_fma_f32 v[62:63], v[44:45], v[76:77], v[62:63] op_sel_hi:[1,0,1] neg_lo:[0,0,1] neg_hi:[0,0,1]
	v_pk_fma_f32 v[60:61], v[42:43], v[76:77], v[60:61] op_sel_hi:[1,0,1] neg_lo:[0,0,1] neg_hi:[0,0,1]
	ds_read_b128 v[42:45], v35 offset:224
	v_pk_fma_f32 v[70:71], v[76:77], v[54:55], v[70:71] op_sel_hi:[0,1,1] neg_lo:[0,0,1] neg_hi:[0,0,1]
	v_pk_fma_f32 v[68:69], v[76:77], v[52:53], v[68:69] op_sel_hi:[0,1,1] neg_lo:[0,0,1] neg_hi:[0,0,1]
	ds_read_b128 v[52:55], v35 offset:240
	v_pk_fma_f32 v[30:31], v[72:73], v[30:31], v[74:75] op_sel_hi:[1,1,0]
	ds_read_b128 v[72:75], v35 offset:144
	v_pk_fma_f32 v[78:79], v[40:41], v[76:77], v[82:83] op_sel_hi:[1,0,1] neg_lo:[0,0,1] neg_hi:[0,0,1]
	v_pk_fma_f32 v[80:81], v[38:39], v[76:77], v[80:81] op_sel_hi:[1,0,1] neg_lo:[0,0,1] neg_hi:[0,0,1]
	ds_read_b128 v[38:41], v35 offset:160
	v_pk_fma_f32 v[66:67], v[76:77], v[50:51], v[66:67] op_sel_hi:[0,1,1] neg_lo:[0,0,1] neg_hi:[0,0,1]
	v_pk_fma_f32 v[64:65], v[76:77], v[48:49], v[64:65] op_sel_hi:[0,1,1] neg_lo:[0,0,1] neg_hi:[0,0,1]
	ds_read_b128 v[48:51], v35 offset:176
	s_waitcnt lgkmcnt(6)
	v_pk_mul_f32 v[22:23], v[22:23], v[30:31] op_sel_hi:[1,0]
	v_pk_mul_f32 v[20:21], v[20:21], v[30:31] op_sel_hi:[1,0]
	s_waitcnt lgkmcnt(5)
	v_pk_mul_f32 v[58:59], v[30:31], v[58:59] op_sel_hi:[0,1]
	v_pk_mul_f32 v[56:57], v[30:31], v[56:57] op_sel_hi:[0,1]
	s_waitcnt lgkmcnt(4)
	v_pk_mul_f32 v[44:45], v[30:31], v[44:45] op_sel_hi:[0,1]
	v_pk_mul_f32 v[42:43], v[30:31], v[42:43] op_sel_hi:[0,1]
	s_waitcnt lgkmcnt(3)
	v_pk_mul_f32 v[54:55], v[30:31], v[54:55] op_sel_hi:[0,1]
	v_pk_mul_f32 v[30:31], v[30:31], v[52:53] op_sel_hi:[0,1]
	v_pk_fma_f32 v[16:17], v[16:17], v[28:29], v[20:21] op_sel_hi:[1,0,1] neg_lo:[0,0,1] neg_hi:[0,0,1]
	v_pk_fma_f32 v[18:19], v[18:19], v[28:29], v[22:23] op_sel_hi:[1,0,1] neg_lo:[0,0,1] neg_hi:[0,0,1]
	s_waitcnt lgkmcnt(2)
	v_pk_fma_f32 v[20:21], v[72:73], v[28:29], v[56:57] op_sel_hi:[1,0,1] neg_lo:[0,0,1] neg_hi:[0,0,1]
	v_pk_fma_f32 v[22:23], v[74:75], v[28:29], v[58:59] op_sel_hi:[1,0,1] neg_lo:[0,0,1] neg_hi:[0,0,1]
	s_waitcnt lgkmcnt(1)
	v_pk_fma_f32 v[38:39], v[28:29], v[38:39], v[42:43] op_sel_hi:[0,1,1] neg_lo:[0,0,1] neg_hi:[0,0,1]
	v_pk_fma_f32 v[40:41], v[28:29], v[40:41], v[44:45] op_sel_hi:[0,1,1] neg_lo:[0,0,1] neg_hi:[0,0,1]
	s_waitcnt lgkmcnt(0)
	v_pk_fma_f32 v[30:31], v[28:29], v[48:49], v[30:31] op_sel_hi:[0,1,1] neg_lo:[0,0,1] neg_hi:[0,0,1]
	v_pk_fma_f32 v[28:29], v[28:29], v[50:51], v[54:55] op_sel_hi:[0,1,1] neg_lo:[0,0,1] neg_hi:[0,0,1]
	v_pk_add_f32 v[12:13], v[12:13], v[80:81]
	v_pk_add_f32 v[14:15], v[14:15], v[78:79]
	v_pk_add_f32 v[8:9], v[8:9], v[60:61]
	v_pk_add_f32 v[10:11], v[10:11], v[62:63]
	v_pk_add_f32 v[4:5], v[4:5], v[64:65]
	v_pk_add_f32 v[6:7], v[6:7], v[66:67]
	v_pk_add_f32 v[0:1], v[0:1], v[68:69]
	v_pk_add_f32 v[2:3], v[2:3], v[70:71]
	v_add_u32_e32 v35, 0x100, v35
	v_pk_add_f32 v[14:15], v[14:15], v[18:19]
	v_pk_add_f32 v[12:13], v[12:13], v[16:17]
	v_pk_add_f32 v[10:11], v[10:11], v[22:23]
	v_pk_add_f32 v[8:9], v[8:9], v[20:21]
	v_pk_add_f32 v[6:7], v[6:7], v[40:41]
	v_pk_add_f32 v[4:5], v[4:5], v[38:39]
	v_pk_add_f32 v[2:3], v[2:3], v[28:29]
	v_pk_add_f32 v[0:1], v[0:1], v[30:31]
	v_lshl_add_u64 v[16:17], v[24:25], 0, s[0:1]
	v_lshl_add_u64 v[18:19], v[26:27], 0, s[0:1]
	s_waitcnt vmcnt(18)
	v_mov_b32_e32 v72, v108
	v_mov_b32_e32 v73, v109
	v_mov_b32_e32 v74, v200
	v_mov_b32_e32 v75, v201
	ds_read2_b64 v[28:31], v36 offset1:17
	ds_read_b128 v[38:41], v35
	ds_read_b128 v[42:45], v35 offset:16
	ds_read_b128 v[48:51], v35 offset:32
	ds_read_b128 v[52:55], v35 offset:48
	ds_read_b128 v[56:59], v35 offset:64
	ds_read_b128 v[60:63], v35 offset:80
	ds_read_b128 v[64:67], v35 offset:96
	ds_read_b128 v[68:71], v35 offset:112
	ds_read_b128 v[16:19], v35 offset:128
	ds_read_b128 v[20:23], v35 offset:192
	s_add_u32 s0, s0, 8
	s_addc_u32 s1, s1, 0
	v_add_u32_e32 v36, 0x110, v36
	s_cmpk_eq_i32 s0, 0x100
	v_mov_b32_e32 v76, v72
	v_mov_b32_e32 v77, v74
	s_waitcnt lgkmcnt(10)
	v_mul_f32_e32 v78, v74, v29
	v_mov_b32_e32 v80, v74
	v_mov_b32_e32 v81, v72
	v_mul_f32_e32 v72, v72, v29
	v_pk_fma_f32 v[76:77], v[76:77], v[28:29], v[78:79] op_sel_hi:[1,1,0] neg_lo:[0,0,1] neg_hi:[0,0,1]
	v_pk_fma_f32 v[78:79], v[80:81], v[28:29], v[72:73] op_sel_hi:[1,1,0]
	v_mov_b32_e32 v74, v73
	v_mul_f32_e32 v28, v75, v31
	s_waitcnt lgkmcnt(4)
	v_pk_mul_f32 v[60:61], v[78:79], v[60:61] op_sel_hi:[0,1]
	v_pk_mul_f32 v[62:63], v[78:79], v[62:63] op_sel_hi:[0,1]
	s_waitcnt lgkmcnt(2)
	v_pk_mul_f32 v[68:69], v[78:79], v[68:69] op_sel_hi:[0,1]
	v_pk_mul_f32 v[70:71], v[78:79], v[70:71] op_sel_hi:[0,1]
	v_mov_b32_e32 v72, v75
	v_pk_fma_f32 v[28:29], v[74:75], v[30:31], v[28:29] op_sel_hi:[1,1,0] neg_lo:[0,0,1] neg_hi:[0,0,1]
	v_mul_f32_e32 v74, v73, v31
	v_pk_mul_f32 v[80:81], v[56:57], v[78:79] op_sel_hi:[1,0]
	v_pk_mul_f32 v[82:83], v[58:59], v[78:79] op_sel_hi:[1,0]
	v_pk_mul_f32 v[64:65], v[78:79], v[64:65] op_sel_hi:[0,1]
	v_pk_mul_f32 v[66:67], v[78:79], v[66:67] op_sel_hi:[0,1]
	ds_read_b128 v[56:59], v35 offset:208
	v_pk_fma_f32 v[62:63], v[44:45], v[76:77], v[62:63] op_sel_hi:[1,0,1] neg_lo:[0,0,1] neg_hi:[0,0,1]
	v_pk_fma_f32 v[60:61], v[42:43], v[76:77], v[60:61] op_sel_hi:[1,0,1] neg_lo:[0,0,1] neg_hi:[0,0,1]
	ds_read_b128 v[42:45], v35 offset:224
	v_pk_fma_f32 v[70:71], v[76:77], v[54:55], v[70:71] op_sel_hi:[0,1,1] neg_lo:[0,0,1] neg_hi:[0,0,1]
	v_pk_fma_f32 v[68:69], v[76:77], v[52:53], v[68:69] op_sel_hi:[0,1,1] neg_lo:[0,0,1] neg_hi:[0,0,1]
	ds_read_b128 v[52:55], v35 offset:240
	v_pk_fma_f32 v[30:31], v[72:73], v[30:31], v[74:75] op_sel_hi:[1,1,0]
	ds_read_b128 v[72:75], v35 offset:144
	v_pk_fma_f32 v[78:79], v[40:41], v[76:77], v[82:83] op_sel_hi:[1,0,1] neg_lo:[0,0,1] neg_hi:[0,0,1]
	v_pk_fma_f32 v[80:81], v[38:39], v[76:77], v[80:81] op_sel_hi:[1,0,1] neg_lo:[0,0,1] neg_hi:[0,0,1]
	ds_read_b128 v[38:41], v35 offset:160
	v_pk_fma_f32 v[66:67], v[76:77], v[50:51], v[66:67] op_sel_hi:[0,1,1] neg_lo:[0,0,1] neg_hi:[0,0,1]
	v_pk_fma_f32 v[64:65], v[76:77], v[48:49], v[64:65] op_sel_hi:[0,1,1] neg_lo:[0,0,1] neg_hi:[0,0,1]
	ds_read_b128 v[48:51], v35 offset:176
	s_waitcnt lgkmcnt(6)
	v_pk_mul_f32 v[22:23], v[22:23], v[30:31] op_sel_hi:[1,0]
	v_pk_mul_f32 v[20:21], v[20:21], v[30:31] op_sel_hi:[1,0]
	s_waitcnt lgkmcnt(5)
	v_pk_mul_f32 v[58:59], v[30:31], v[58:59] op_sel_hi:[0,1]
	v_pk_mul_f32 v[56:57], v[30:31], v[56:57] op_sel_hi:[0,1]
	s_waitcnt lgkmcnt(4)
	v_pk_mul_f32 v[44:45], v[30:31], v[44:45] op_sel_hi:[0,1]
	v_pk_mul_f32 v[42:43], v[30:31], v[42:43] op_sel_hi:[0,1]
	s_waitcnt lgkmcnt(3)
	v_pk_mul_f32 v[54:55], v[30:31], v[54:55] op_sel_hi:[0,1]
	v_pk_mul_f32 v[30:31], v[30:31], v[52:53] op_sel_hi:[0,1]
	v_pk_fma_f32 v[16:17], v[16:17], v[28:29], v[20:21] op_sel_hi:[1,0,1] neg_lo:[0,0,1] neg_hi:[0,0,1]
	v_pk_fma_f32 v[18:19], v[18:19], v[28:29], v[22:23] op_sel_hi:[1,0,1] neg_lo:[0,0,1] neg_hi:[0,0,1]
	s_waitcnt lgkmcnt(2)
	v_pk_fma_f32 v[20:21], v[72:73], v[28:29], v[56:57] op_sel_hi:[1,0,1] neg_lo:[0,0,1] neg_hi:[0,0,1]
	v_pk_fma_f32 v[22:23], v[74:75], v[28:29], v[58:59] op_sel_hi:[1,0,1] neg_lo:[0,0,1] neg_hi:[0,0,1]
	s_waitcnt lgkmcnt(1)
	v_pk_fma_f32 v[38:39], v[28:29], v[38:39], v[42:43] op_sel_hi:[0,1,1] neg_lo:[0,0,1] neg_hi:[0,0,1]
	v_pk_fma_f32 v[40:41], v[28:29], v[40:41], v[44:45] op_sel_hi:[0,1,1] neg_lo:[0,0,1] neg_hi:[0,0,1]
	s_waitcnt lgkmcnt(0)
	v_pk_fma_f32 v[30:31], v[28:29], v[48:49], v[30:31] op_sel_hi:[0,1,1] neg_lo:[0,0,1] neg_hi:[0,0,1]
	v_pk_fma_f32 v[28:29], v[28:29], v[50:51], v[54:55] op_sel_hi:[0,1,1] neg_lo:[0,0,1] neg_hi:[0,0,1]
	v_pk_add_f32 v[12:13], v[12:13], v[80:81]
	v_pk_add_f32 v[14:15], v[14:15], v[78:79]
	v_pk_add_f32 v[8:9], v[8:9], v[60:61]
	v_pk_add_f32 v[10:11], v[10:11], v[62:63]
	v_pk_add_f32 v[4:5], v[4:5], v[64:65]
	v_pk_add_f32 v[6:7], v[6:7], v[66:67]
	v_pk_add_f32 v[0:1], v[0:1], v[68:69]
	v_pk_add_f32 v[2:3], v[2:3], v[70:71]
	v_add_u32_e32 v35, 0x100, v35
	v_pk_add_f32 v[14:15], v[14:15], v[18:19]
	v_pk_add_f32 v[12:13], v[12:13], v[16:17]
	v_pk_add_f32 v[10:11], v[10:11], v[22:23]
	v_pk_add_f32 v[8:9], v[8:9], v[20:21]
	v_pk_add_f32 v[6:7], v[6:7], v[40:41]
	v_pk_add_f32 v[4:5], v[4:5], v[38:39]
	v_pk_add_f32 v[2:3], v[2:3], v[28:29]
	v_pk_add_f32 v[0:1], v[0:1], v[30:31]
	v_lshl_add_u64 v[16:17], v[24:25], 0, s[0:1]
	v_lshl_add_u64 v[18:19], v[26:27], 0, s[0:1]
	s_waitcnt vmcnt(18)
	v_mov_b32_e32 v72, v110
	v_mov_b32_e32 v73, v111
	v_mov_b32_e32 v74, v202
	v_mov_b32_e32 v75, v203
	ds_read2_b64 v[28:31], v36 offset1:17
	ds_read_b128 v[38:41], v35
	ds_read_b128 v[42:45], v35 offset:16
	ds_read_b128 v[48:51], v35 offset:32
	ds_read_b128 v[52:55], v35 offset:48
	ds_read_b128 v[56:59], v35 offset:64
	ds_read_b128 v[60:63], v35 offset:80
	ds_read_b128 v[64:67], v35 offset:96
	ds_read_b128 v[68:71], v35 offset:112
	ds_read_b128 v[16:19], v35 offset:128
	ds_read_b128 v[20:23], v35 offset:192
	s_add_u32 s0, s0, 8
	s_addc_u32 s1, s1, 0
	v_add_u32_e32 v36, 0x110, v36
	s_cmpk_eq_i32 s0, 0x100
	v_mov_b32_e32 v76, v72
	v_mov_b32_e32 v77, v74
	s_waitcnt lgkmcnt(10)
	v_mul_f32_e32 v78, v74, v29
	v_mov_b32_e32 v80, v74
	v_mov_b32_e32 v81, v72
	v_mul_f32_e32 v72, v72, v29
	v_pk_fma_f32 v[76:77], v[76:77], v[28:29], v[78:79] op_sel_hi:[1,1,0] neg_lo:[0,0,1] neg_hi:[0,0,1]
	v_pk_fma_f32 v[78:79], v[80:81], v[28:29], v[72:73] op_sel_hi:[1,1,0]
	v_mov_b32_e32 v74, v73
	v_mul_f32_e32 v28, v75, v31
	s_waitcnt lgkmcnt(4)
	v_pk_mul_f32 v[60:61], v[78:79], v[60:61] op_sel_hi:[0,1]
	v_pk_mul_f32 v[62:63], v[78:79], v[62:63] op_sel_hi:[0,1]
	s_waitcnt lgkmcnt(2)
	v_pk_mul_f32 v[68:69], v[78:79], v[68:69] op_sel_hi:[0,1]
	v_pk_mul_f32 v[70:71], v[78:79], v[70:71] op_sel_hi:[0,1]
	v_mov_b32_e32 v72, v75
	v_pk_fma_f32 v[28:29], v[74:75], v[30:31], v[28:29] op_sel_hi:[1,1,0] neg_lo:[0,0,1] neg_hi:[0,0,1]
	v_mul_f32_e32 v74, v73, v31
	v_pk_mul_f32 v[80:81], v[56:57], v[78:79] op_sel_hi:[1,0]
	v_pk_mul_f32 v[82:83], v[58:59], v[78:79] op_sel_hi:[1,0]
	v_pk_mul_f32 v[64:65], v[78:79], v[64:65] op_sel_hi:[0,1]
	v_pk_mul_f32 v[66:67], v[78:79], v[66:67] op_sel_hi:[0,1]
	ds_read_b128 v[56:59], v35 offset:208
	v_pk_fma_f32 v[62:63], v[44:45], v[76:77], v[62:63] op_sel_hi:[1,0,1] neg_lo:[0,0,1] neg_hi:[0,0,1]
	v_pk_fma_f32 v[60:61], v[42:43], v[76:77], v[60:61] op_sel_hi:[1,0,1] neg_lo:[0,0,1] neg_hi:[0,0,1]
	ds_read_b128 v[42:45], v35 offset:224
	v_pk_fma_f32 v[70:71], v[76:77], v[54:55], v[70:71] op_sel_hi:[0,1,1] neg_lo:[0,0,1] neg_hi:[0,0,1]
	v_pk_fma_f32 v[68:69], v[76:77], v[52:53], v[68:69] op_sel_hi:[0,1,1] neg_lo:[0,0,1] neg_hi:[0,0,1]
	ds_read_b128 v[52:55], v35 offset:240
	v_pk_fma_f32 v[30:31], v[72:73], v[30:31], v[74:75] op_sel_hi:[1,1,0]
	ds_read_b128 v[72:75], v35 offset:144
	v_pk_fma_f32 v[78:79], v[40:41], v[76:77], v[82:83] op_sel_hi:[1,0,1] neg_lo:[0,0,1] neg_hi:[0,0,1]
	v_pk_fma_f32 v[80:81], v[38:39], v[76:77], v[80:81] op_sel_hi:[1,0,1] neg_lo:[0,0,1] neg_hi:[0,0,1]
	ds_read_b128 v[38:41], v35 offset:160
	v_pk_fma_f32 v[66:67], v[76:77], v[50:51], v[66:67] op_sel_hi:[0,1,1] neg_lo:[0,0,1] neg_hi:[0,0,1]
	v_pk_fma_f32 v[64:65], v[76:77], v[48:49], v[64:65] op_sel_hi:[0,1,1] neg_lo:[0,0,1] neg_hi:[0,0,1]
	ds_read_b128 v[48:51], v35 offset:176
	s_waitcnt lgkmcnt(6)
	v_pk_mul_f32 v[22:23], v[22:23], v[30:31] op_sel_hi:[1,0]
	v_pk_mul_f32 v[20:21], v[20:21], v[30:31] op_sel_hi:[1,0]
	s_waitcnt lgkmcnt(5)
	v_pk_mul_f32 v[58:59], v[30:31], v[58:59] op_sel_hi:[0,1]
	v_pk_mul_f32 v[56:57], v[30:31], v[56:57] op_sel_hi:[0,1]
	s_waitcnt lgkmcnt(4)
	v_pk_mul_f32 v[44:45], v[30:31], v[44:45] op_sel_hi:[0,1]
	v_pk_mul_f32 v[42:43], v[30:31], v[42:43] op_sel_hi:[0,1]
	s_waitcnt lgkmcnt(3)
	v_pk_mul_f32 v[54:55], v[30:31], v[54:55] op_sel_hi:[0,1]
	v_pk_mul_f32 v[30:31], v[30:31], v[52:53] op_sel_hi:[0,1]
	v_pk_fma_f32 v[16:17], v[16:17], v[28:29], v[20:21] op_sel_hi:[1,0,1] neg_lo:[0,0,1] neg_hi:[0,0,1]
	v_pk_fma_f32 v[18:19], v[18:19], v[28:29], v[22:23] op_sel_hi:[1,0,1] neg_lo:[0,0,1] neg_hi:[0,0,1]
	s_waitcnt lgkmcnt(2)
	v_pk_fma_f32 v[20:21], v[72:73], v[28:29], v[56:57] op_sel_hi:[1,0,1] neg_lo:[0,0,1] neg_hi:[0,0,1]
	v_pk_fma_f32 v[22:23], v[74:75], v[28:29], v[58:59] op_sel_hi:[1,0,1] neg_lo:[0,0,1] neg_hi:[0,0,1]
	s_waitcnt lgkmcnt(1)
	v_pk_fma_f32 v[38:39], v[28:29], v[38:39], v[42:43] op_sel_hi:[0,1,1] neg_lo:[0,0,1] neg_hi:[0,0,1]
	v_pk_fma_f32 v[40:41], v[28:29], v[40:41], v[44:45] op_sel_hi:[0,1,1] neg_lo:[0,0,1] neg_hi:[0,0,1]
	s_waitcnt lgkmcnt(0)
	v_pk_fma_f32 v[30:31], v[28:29], v[48:49], v[30:31] op_sel_hi:[0,1,1] neg_lo:[0,0,1] neg_hi:[0,0,1]
	v_pk_fma_f32 v[28:29], v[28:29], v[50:51], v[54:55] op_sel_hi:[0,1,1] neg_lo:[0,0,1] neg_hi:[0,0,1]
	v_pk_add_f32 v[12:13], v[12:13], v[80:81]
	v_pk_add_f32 v[14:15], v[14:15], v[78:79]
	v_pk_add_f32 v[8:9], v[8:9], v[60:61]
	v_pk_add_f32 v[10:11], v[10:11], v[62:63]
	v_pk_add_f32 v[4:5], v[4:5], v[64:65]
	v_pk_add_f32 v[6:7], v[6:7], v[66:67]
	v_pk_add_f32 v[0:1], v[0:1], v[68:69]
	v_pk_add_f32 v[2:3], v[2:3], v[70:71]
	v_add_u32_e32 v35, 0x100, v35
	v_pk_add_f32 v[14:15], v[14:15], v[18:19]
	v_pk_add_f32 v[12:13], v[12:13], v[16:17]
	v_pk_add_f32 v[10:11], v[10:11], v[22:23]
	v_pk_add_f32 v[8:9], v[8:9], v[20:21]
	v_pk_add_f32 v[6:7], v[6:7], v[40:41]
	v_pk_add_f32 v[4:5], v[4:5], v[38:39]
	v_pk_add_f32 v[2:3], v[2:3], v[28:29]
	v_pk_add_f32 v[0:1], v[0:1], v[30:31]
	v_lshl_add_u64 v[16:17], v[24:25], 0, s[0:1]
	v_lshl_add_u64 v[18:19], v[26:27], 0, s[0:1]
	s_waitcnt vmcnt(16)
	v_mov_b32_e32 v72, v112
	v_mov_b32_e32 v73, v113
	v_mov_b32_e32 v74, v204
	v_mov_b32_e32 v75, v205
	ds_read2_b64 v[28:31], v36 offset1:17
	ds_read_b128 v[38:41], v35
	ds_read_b128 v[42:45], v35 offset:16
	ds_read_b128 v[48:51], v35 offset:32
	ds_read_b128 v[52:55], v35 offset:48
	ds_read_b128 v[56:59], v35 offset:64
	ds_read_b128 v[60:63], v35 offset:80
	ds_read_b128 v[64:67], v35 offset:96
	ds_read_b128 v[68:71], v35 offset:112
	ds_read_b128 v[16:19], v35 offset:128
	ds_read_b128 v[20:23], v35 offset:192
	s_add_u32 s0, s0, 8
	s_addc_u32 s1, s1, 0
	v_add_u32_e32 v36, 0x110, v36
	s_cmpk_eq_i32 s0, 0x100
	v_mov_b32_e32 v76, v72
	v_mov_b32_e32 v77, v74
	s_waitcnt lgkmcnt(10)
	v_mul_f32_e32 v78, v74, v29
	v_mov_b32_e32 v80, v74
	v_mov_b32_e32 v81, v72
	v_mul_f32_e32 v72, v72, v29
	v_pk_fma_f32 v[76:77], v[76:77], v[28:29], v[78:79] op_sel_hi:[1,1,0] neg_lo:[0,0,1] neg_hi:[0,0,1]
	v_pk_fma_f32 v[78:79], v[80:81], v[28:29], v[72:73] op_sel_hi:[1,1,0]
	v_mov_b32_e32 v74, v73
	v_mul_f32_e32 v28, v75, v31
	s_waitcnt lgkmcnt(4)
	v_pk_mul_f32 v[60:61], v[78:79], v[60:61] op_sel_hi:[0,1]
	v_pk_mul_f32 v[62:63], v[78:79], v[62:63] op_sel_hi:[0,1]
	s_waitcnt lgkmcnt(2)
	v_pk_mul_f32 v[68:69], v[78:79], v[68:69] op_sel_hi:[0,1]
	v_pk_mul_f32 v[70:71], v[78:79], v[70:71] op_sel_hi:[0,1]
	v_mov_b32_e32 v72, v75
	v_pk_fma_f32 v[28:29], v[74:75], v[30:31], v[28:29] op_sel_hi:[1,1,0] neg_lo:[0,0,1] neg_hi:[0,0,1]
	v_mul_f32_e32 v74, v73, v31
	v_pk_mul_f32 v[80:81], v[56:57], v[78:79] op_sel_hi:[1,0]
	v_pk_mul_f32 v[82:83], v[58:59], v[78:79] op_sel_hi:[1,0]
	v_pk_mul_f32 v[64:65], v[78:79], v[64:65] op_sel_hi:[0,1]
	v_pk_mul_f32 v[66:67], v[78:79], v[66:67] op_sel_hi:[0,1]
	ds_read_b128 v[56:59], v35 offset:208
	v_pk_fma_f32 v[62:63], v[44:45], v[76:77], v[62:63] op_sel_hi:[1,0,1] neg_lo:[0,0,1] neg_hi:[0,0,1]
	v_pk_fma_f32 v[60:61], v[42:43], v[76:77], v[60:61] op_sel_hi:[1,0,1] neg_lo:[0,0,1] neg_hi:[0,0,1]
	ds_read_b128 v[42:45], v35 offset:224
	v_pk_fma_f32 v[70:71], v[76:77], v[54:55], v[70:71] op_sel_hi:[0,1,1] neg_lo:[0,0,1] neg_hi:[0,0,1]
	v_pk_fma_f32 v[68:69], v[76:77], v[52:53], v[68:69] op_sel_hi:[0,1,1] neg_lo:[0,0,1] neg_hi:[0,0,1]
	ds_read_b128 v[52:55], v35 offset:240
	v_pk_fma_f32 v[30:31], v[72:73], v[30:31], v[74:75] op_sel_hi:[1,1,0]
	ds_read_b128 v[72:75], v35 offset:144
	v_pk_fma_f32 v[78:79], v[40:41], v[76:77], v[82:83] op_sel_hi:[1,0,1] neg_lo:[0,0,1] neg_hi:[0,0,1]
	v_pk_fma_f32 v[80:81], v[38:39], v[76:77], v[80:81] op_sel_hi:[1,0,1] neg_lo:[0,0,1] neg_hi:[0,0,1]
	ds_read_b128 v[38:41], v35 offset:160
	v_pk_fma_f32 v[66:67], v[76:77], v[50:51], v[66:67] op_sel_hi:[0,1,1] neg_lo:[0,0,1] neg_hi:[0,0,1]
	v_pk_fma_f32 v[64:65], v[76:77], v[48:49], v[64:65] op_sel_hi:[0,1,1] neg_lo:[0,0,1] neg_hi:[0,0,1]
	ds_read_b128 v[48:51], v35 offset:176
	s_waitcnt lgkmcnt(6)
	v_pk_mul_f32 v[22:23], v[22:23], v[30:31] op_sel_hi:[1,0]
	v_pk_mul_f32 v[20:21], v[20:21], v[30:31] op_sel_hi:[1,0]
	s_waitcnt lgkmcnt(5)
	v_pk_mul_f32 v[58:59], v[30:31], v[58:59] op_sel_hi:[0,1]
	v_pk_mul_f32 v[56:57], v[30:31], v[56:57] op_sel_hi:[0,1]
	s_waitcnt lgkmcnt(4)
	v_pk_mul_f32 v[44:45], v[30:31], v[44:45] op_sel_hi:[0,1]
	v_pk_mul_f32 v[42:43], v[30:31], v[42:43] op_sel_hi:[0,1]
	s_waitcnt lgkmcnt(3)
	v_pk_mul_f32 v[54:55], v[30:31], v[54:55] op_sel_hi:[0,1]
	v_pk_mul_f32 v[30:31], v[30:31], v[52:53] op_sel_hi:[0,1]
	v_pk_fma_f32 v[16:17], v[16:17], v[28:29], v[20:21] op_sel_hi:[1,0,1] neg_lo:[0,0,1] neg_hi:[0,0,1]
	v_pk_fma_f32 v[18:19], v[18:19], v[28:29], v[22:23] op_sel_hi:[1,0,1] neg_lo:[0,0,1] neg_hi:[0,0,1]
	s_waitcnt lgkmcnt(2)
	v_pk_fma_f32 v[20:21], v[72:73], v[28:29], v[56:57] op_sel_hi:[1,0,1] neg_lo:[0,0,1] neg_hi:[0,0,1]
	v_pk_fma_f32 v[22:23], v[74:75], v[28:29], v[58:59] op_sel_hi:[1,0,1] neg_lo:[0,0,1] neg_hi:[0,0,1]
	s_waitcnt lgkmcnt(1)
	v_pk_fma_f32 v[38:39], v[28:29], v[38:39], v[42:43] op_sel_hi:[0,1,1] neg_lo:[0,0,1] neg_hi:[0,0,1]
	v_pk_fma_f32 v[40:41], v[28:29], v[40:41], v[44:45] op_sel_hi:[0,1,1] neg_lo:[0,0,1] neg_hi:[0,0,1]
	s_waitcnt lgkmcnt(0)
	v_pk_fma_f32 v[30:31], v[28:29], v[48:49], v[30:31] op_sel_hi:[0,1,1] neg_lo:[0,0,1] neg_hi:[0,0,1]
	v_pk_fma_f32 v[28:29], v[28:29], v[50:51], v[54:55] op_sel_hi:[0,1,1] neg_lo:[0,0,1] neg_hi:[0,0,1]
	v_pk_add_f32 v[12:13], v[12:13], v[80:81]
	v_pk_add_f32 v[14:15], v[14:15], v[78:79]
	v_pk_add_f32 v[8:9], v[8:9], v[60:61]
	v_pk_add_f32 v[10:11], v[10:11], v[62:63]
	v_pk_add_f32 v[4:5], v[4:5], v[64:65]
	v_pk_add_f32 v[6:7], v[6:7], v[66:67]
	v_pk_add_f32 v[0:1], v[0:1], v[68:69]
	v_pk_add_f32 v[2:3], v[2:3], v[70:71]
	v_add_u32_e32 v35, 0x100, v35
	v_pk_add_f32 v[14:15], v[14:15], v[18:19]
	v_pk_add_f32 v[12:13], v[12:13], v[16:17]
	v_pk_add_f32 v[10:11], v[10:11], v[22:23]
	v_pk_add_f32 v[8:9], v[8:9], v[20:21]
	v_pk_add_f32 v[6:7], v[6:7], v[40:41]
	v_pk_add_f32 v[4:5], v[4:5], v[38:39]
	v_pk_add_f32 v[2:3], v[2:3], v[28:29]
	v_pk_add_f32 v[0:1], v[0:1], v[30:31]
	v_lshl_add_u64 v[16:17], v[24:25], 0, s[0:1]
	v_lshl_add_u64 v[18:19], v[26:27], 0, s[0:1]
	s_waitcnt vmcnt(16)
	v_mov_b32_e32 v72, v114
	v_mov_b32_e32 v73, v115
	v_mov_b32_e32 v74, v206
	v_mov_b32_e32 v75, v207
	ds_read2_b64 v[28:31], v36 offset1:17
	ds_read_b128 v[38:41], v35
	ds_read_b128 v[42:45], v35 offset:16
	ds_read_b128 v[48:51], v35 offset:32
	ds_read_b128 v[52:55], v35 offset:48
	ds_read_b128 v[56:59], v35 offset:64
	ds_read_b128 v[60:63], v35 offset:80
	ds_read_b128 v[64:67], v35 offset:96
	ds_read_b128 v[68:71], v35 offset:112
	ds_read_b128 v[16:19], v35 offset:128
	ds_read_b128 v[20:23], v35 offset:192
	s_add_u32 s0, s0, 8
	s_addc_u32 s1, s1, 0
	v_add_u32_e32 v36, 0x110, v36
	s_cmpk_eq_i32 s0, 0x100
	v_mov_b32_e32 v76, v72
	v_mov_b32_e32 v77, v74
	s_waitcnt lgkmcnt(10)
	v_mul_f32_e32 v78, v74, v29
	v_mov_b32_e32 v80, v74
	v_mov_b32_e32 v81, v72
	v_mul_f32_e32 v72, v72, v29
	v_pk_fma_f32 v[76:77], v[76:77], v[28:29], v[78:79] op_sel_hi:[1,1,0] neg_lo:[0,0,1] neg_hi:[0,0,1]
	v_pk_fma_f32 v[78:79], v[80:81], v[28:29], v[72:73] op_sel_hi:[1,1,0]
	v_mov_b32_e32 v74, v73
	v_mul_f32_e32 v28, v75, v31
	s_waitcnt lgkmcnt(4)
	v_pk_mul_f32 v[60:61], v[78:79], v[60:61] op_sel_hi:[0,1]
	v_pk_mul_f32 v[62:63], v[78:79], v[62:63] op_sel_hi:[0,1]
	s_waitcnt lgkmcnt(2)
	v_pk_mul_f32 v[68:69], v[78:79], v[68:69] op_sel_hi:[0,1]
	v_pk_mul_f32 v[70:71], v[78:79], v[70:71] op_sel_hi:[0,1]
	v_mov_b32_e32 v72, v75
	v_pk_fma_f32 v[28:29], v[74:75], v[30:31], v[28:29] op_sel_hi:[1,1,0] neg_lo:[0,0,1] neg_hi:[0,0,1]
	v_mul_f32_e32 v74, v73, v31
	v_pk_mul_f32 v[80:81], v[56:57], v[78:79] op_sel_hi:[1,0]
	v_pk_mul_f32 v[82:83], v[58:59], v[78:79] op_sel_hi:[1,0]
	v_pk_mul_f32 v[64:65], v[78:79], v[64:65] op_sel_hi:[0,1]
	v_pk_mul_f32 v[66:67], v[78:79], v[66:67] op_sel_hi:[0,1]
	ds_read_b128 v[56:59], v35 offset:208
	v_pk_fma_f32 v[62:63], v[44:45], v[76:77], v[62:63] op_sel_hi:[1,0,1] neg_lo:[0,0,1] neg_hi:[0,0,1]
	v_pk_fma_f32 v[60:61], v[42:43], v[76:77], v[60:61] op_sel_hi:[1,0,1] neg_lo:[0,0,1] neg_hi:[0,0,1]
	ds_read_b128 v[42:45], v35 offset:224
	v_pk_fma_f32 v[70:71], v[76:77], v[54:55], v[70:71] op_sel_hi:[0,1,1] neg_lo:[0,0,1] neg_hi:[0,0,1]
	v_pk_fma_f32 v[68:69], v[76:77], v[52:53], v[68:69] op_sel_hi:[0,1,1] neg_lo:[0,0,1] neg_hi:[0,0,1]
	ds_read_b128 v[52:55], v35 offset:240
	v_pk_fma_f32 v[30:31], v[72:73], v[30:31], v[74:75] op_sel_hi:[1,1,0]
	ds_read_b128 v[72:75], v35 offset:144
	v_pk_fma_f32 v[78:79], v[40:41], v[76:77], v[82:83] op_sel_hi:[1,0,1] neg_lo:[0,0,1] neg_hi:[0,0,1]
	v_pk_fma_f32 v[80:81], v[38:39], v[76:77], v[80:81] op_sel_hi:[1,0,1] neg_lo:[0,0,1] neg_hi:[0,0,1]
	ds_read_b128 v[38:41], v35 offset:160
	v_pk_fma_f32 v[66:67], v[76:77], v[50:51], v[66:67] op_sel_hi:[0,1,1] neg_lo:[0,0,1] neg_hi:[0,0,1]
	v_pk_fma_f32 v[64:65], v[76:77], v[48:49], v[64:65] op_sel_hi:[0,1,1] neg_lo:[0,0,1] neg_hi:[0,0,1]
	ds_read_b128 v[48:51], v35 offset:176
	s_waitcnt lgkmcnt(6)
	v_pk_mul_f32 v[22:23], v[22:23], v[30:31] op_sel_hi:[1,0]
	v_pk_mul_f32 v[20:21], v[20:21], v[30:31] op_sel_hi:[1,0]
	s_waitcnt lgkmcnt(5)
	v_pk_mul_f32 v[58:59], v[30:31], v[58:59] op_sel_hi:[0,1]
	v_pk_mul_f32 v[56:57], v[30:31], v[56:57] op_sel_hi:[0,1]
	s_waitcnt lgkmcnt(4)
	v_pk_mul_f32 v[44:45], v[30:31], v[44:45] op_sel_hi:[0,1]
	v_pk_mul_f32 v[42:43], v[30:31], v[42:43] op_sel_hi:[0,1]
	s_waitcnt lgkmcnt(3)
	v_pk_mul_f32 v[54:55], v[30:31], v[54:55] op_sel_hi:[0,1]
	v_pk_mul_f32 v[30:31], v[30:31], v[52:53] op_sel_hi:[0,1]
	v_pk_fma_f32 v[16:17], v[16:17], v[28:29], v[20:21] op_sel_hi:[1,0,1] neg_lo:[0,0,1] neg_hi:[0,0,1]
	v_pk_fma_f32 v[18:19], v[18:19], v[28:29], v[22:23] op_sel_hi:[1,0,1] neg_lo:[0,0,1] neg_hi:[0,0,1]
	s_waitcnt lgkmcnt(2)
	v_pk_fma_f32 v[20:21], v[72:73], v[28:29], v[56:57] op_sel_hi:[1,0,1] neg_lo:[0,0,1] neg_hi:[0,0,1]
	v_pk_fma_f32 v[22:23], v[74:75], v[28:29], v[58:59] op_sel_hi:[1,0,1] neg_lo:[0,0,1] neg_hi:[0,0,1]
	s_waitcnt lgkmcnt(1)
	v_pk_fma_f32 v[38:39], v[28:29], v[38:39], v[42:43] op_sel_hi:[0,1,1] neg_lo:[0,0,1] neg_hi:[0,0,1]
	v_pk_fma_f32 v[40:41], v[28:29], v[40:41], v[44:45] op_sel_hi:[0,1,1] neg_lo:[0,0,1] neg_hi:[0,0,1]
	s_waitcnt lgkmcnt(0)
	v_pk_fma_f32 v[30:31], v[28:29], v[48:49], v[30:31] op_sel_hi:[0,1,1] neg_lo:[0,0,1] neg_hi:[0,0,1]
	v_pk_fma_f32 v[28:29], v[28:29], v[50:51], v[54:55] op_sel_hi:[0,1,1] neg_lo:[0,0,1] neg_hi:[0,0,1]
	v_pk_add_f32 v[12:13], v[12:13], v[80:81]
	v_pk_add_f32 v[14:15], v[14:15], v[78:79]
	v_pk_add_f32 v[8:9], v[8:9], v[60:61]
	v_pk_add_f32 v[10:11], v[10:11], v[62:63]
	v_pk_add_f32 v[4:5], v[4:5], v[64:65]
	v_pk_add_f32 v[6:7], v[6:7], v[66:67]
	v_pk_add_f32 v[0:1], v[0:1], v[68:69]
	v_pk_add_f32 v[2:3], v[2:3], v[70:71]
	v_add_u32_e32 v35, 0x100, v35
	v_pk_add_f32 v[14:15], v[14:15], v[18:19]
	v_pk_add_f32 v[12:13], v[12:13], v[16:17]
	v_pk_add_f32 v[10:11], v[10:11], v[22:23]
	v_pk_add_f32 v[8:9], v[8:9], v[20:21]
	v_pk_add_f32 v[6:7], v[6:7], v[40:41]
	v_pk_add_f32 v[4:5], v[4:5], v[38:39]
	v_pk_add_f32 v[2:3], v[2:3], v[28:29]
	v_pk_add_f32 v[0:1], v[0:1], v[30:31]
	v_lshl_add_u64 v[16:17], v[24:25], 0, s[0:1]
	v_lshl_add_u64 v[18:19], v[26:27], 0, s[0:1]
	s_waitcnt vmcnt(14)
	v_mov_b32_e32 v72, v116
	v_mov_b32_e32 v73, v117
	v_mov_b32_e32 v74, v208
	v_mov_b32_e32 v75, v209
	ds_read2_b64 v[28:31], v36 offset1:17
	ds_read_b128 v[38:41], v35
	ds_read_b128 v[42:45], v35 offset:16
	ds_read_b128 v[48:51], v35 offset:32
	ds_read_b128 v[52:55], v35 offset:48
	ds_read_b128 v[56:59], v35 offset:64
	ds_read_b128 v[60:63], v35 offset:80
	ds_read_b128 v[64:67], v35 offset:96
	ds_read_b128 v[68:71], v35 offset:112
	ds_read_b128 v[16:19], v35 offset:128
	ds_read_b128 v[20:23], v35 offset:192
	s_add_u32 s0, s0, 8
	s_addc_u32 s1, s1, 0
	v_add_u32_e32 v36, 0x110, v36
	s_cmpk_eq_i32 s0, 0x100
	v_mov_b32_e32 v76, v72
	v_mov_b32_e32 v77, v74
	s_waitcnt lgkmcnt(10)
	v_mul_f32_e32 v78, v74, v29
	v_mov_b32_e32 v80, v74
	v_mov_b32_e32 v81, v72
	v_mul_f32_e32 v72, v72, v29
	v_pk_fma_f32 v[76:77], v[76:77], v[28:29], v[78:79] op_sel_hi:[1,1,0] neg_lo:[0,0,1] neg_hi:[0,0,1]
	v_pk_fma_f32 v[78:79], v[80:81], v[28:29], v[72:73] op_sel_hi:[1,1,0]
	v_mov_b32_e32 v74, v73
	v_mul_f32_e32 v28, v75, v31
	s_waitcnt lgkmcnt(4)
	v_pk_mul_f32 v[60:61], v[78:79], v[60:61] op_sel_hi:[0,1]
	v_pk_mul_f32 v[62:63], v[78:79], v[62:63] op_sel_hi:[0,1]
	s_waitcnt lgkmcnt(2)
	v_pk_mul_f32 v[68:69], v[78:79], v[68:69] op_sel_hi:[0,1]
	v_pk_mul_f32 v[70:71], v[78:79], v[70:71] op_sel_hi:[0,1]
	v_mov_b32_e32 v72, v75
	v_pk_fma_f32 v[28:29], v[74:75], v[30:31], v[28:29] op_sel_hi:[1,1,0] neg_lo:[0,0,1] neg_hi:[0,0,1]
	v_mul_f32_e32 v74, v73, v31
	v_pk_mul_f32 v[80:81], v[56:57], v[78:79] op_sel_hi:[1,0]
	v_pk_mul_f32 v[82:83], v[58:59], v[78:79] op_sel_hi:[1,0]
	v_pk_mul_f32 v[64:65], v[78:79], v[64:65] op_sel_hi:[0,1]
	v_pk_mul_f32 v[66:67], v[78:79], v[66:67] op_sel_hi:[0,1]
	ds_read_b128 v[56:59], v35 offset:208
	v_pk_fma_f32 v[62:63], v[44:45], v[76:77], v[62:63] op_sel_hi:[1,0,1] neg_lo:[0,0,1] neg_hi:[0,0,1]
	v_pk_fma_f32 v[60:61], v[42:43], v[76:77], v[60:61] op_sel_hi:[1,0,1] neg_lo:[0,0,1] neg_hi:[0,0,1]
	ds_read_b128 v[42:45], v35 offset:224
	v_pk_fma_f32 v[70:71], v[76:77], v[54:55], v[70:71] op_sel_hi:[0,1,1] neg_lo:[0,0,1] neg_hi:[0,0,1]
	v_pk_fma_f32 v[68:69], v[76:77], v[52:53], v[68:69] op_sel_hi:[0,1,1] neg_lo:[0,0,1] neg_hi:[0,0,1]
	ds_read_b128 v[52:55], v35 offset:240
	v_pk_fma_f32 v[30:31], v[72:73], v[30:31], v[74:75] op_sel_hi:[1,1,0]
	ds_read_b128 v[72:75], v35 offset:144
	v_pk_fma_f32 v[78:79], v[40:41], v[76:77], v[82:83] op_sel_hi:[1,0,1] neg_lo:[0,0,1] neg_hi:[0,0,1]
	v_pk_fma_f32 v[80:81], v[38:39], v[76:77], v[80:81] op_sel_hi:[1,0,1] neg_lo:[0,0,1] neg_hi:[0,0,1]
	ds_read_b128 v[38:41], v35 offset:160
	v_pk_fma_f32 v[66:67], v[76:77], v[50:51], v[66:67] op_sel_hi:[0,1,1] neg_lo:[0,0,1] neg_hi:[0,0,1]
	v_pk_fma_f32 v[64:65], v[76:77], v[48:49], v[64:65] op_sel_hi:[0,1,1] neg_lo:[0,0,1] neg_hi:[0,0,1]
	ds_read_b128 v[48:51], v35 offset:176
	s_waitcnt lgkmcnt(6)
	v_pk_mul_f32 v[22:23], v[22:23], v[30:31] op_sel_hi:[1,0]
	v_pk_mul_f32 v[20:21], v[20:21], v[30:31] op_sel_hi:[1,0]
	s_waitcnt lgkmcnt(5)
	v_pk_mul_f32 v[58:59], v[30:31], v[58:59] op_sel_hi:[0,1]
	v_pk_mul_f32 v[56:57], v[30:31], v[56:57] op_sel_hi:[0,1]
	s_waitcnt lgkmcnt(4)
	v_pk_mul_f32 v[44:45], v[30:31], v[44:45] op_sel_hi:[0,1]
	v_pk_mul_f32 v[42:43], v[30:31], v[42:43] op_sel_hi:[0,1]
	s_waitcnt lgkmcnt(3)
	v_pk_mul_f32 v[54:55], v[30:31], v[54:55] op_sel_hi:[0,1]
	v_pk_mul_f32 v[30:31], v[30:31], v[52:53] op_sel_hi:[0,1]
	v_pk_fma_f32 v[16:17], v[16:17], v[28:29], v[20:21] op_sel_hi:[1,0,1] neg_lo:[0,0,1] neg_hi:[0,0,1]
	v_pk_fma_f32 v[18:19], v[18:19], v[28:29], v[22:23] op_sel_hi:[1,0,1] neg_lo:[0,0,1] neg_hi:[0,0,1]
	s_waitcnt lgkmcnt(2)
	v_pk_fma_f32 v[20:21], v[72:73], v[28:29], v[56:57] op_sel_hi:[1,0,1] neg_lo:[0,0,1] neg_hi:[0,0,1]
	v_pk_fma_f32 v[22:23], v[74:75], v[28:29], v[58:59] op_sel_hi:[1,0,1] neg_lo:[0,0,1] neg_hi:[0,0,1]
	s_waitcnt lgkmcnt(1)
	v_pk_fma_f32 v[38:39], v[28:29], v[38:39], v[42:43] op_sel_hi:[0,1,1] neg_lo:[0,0,1] neg_hi:[0,0,1]
	v_pk_fma_f32 v[40:41], v[28:29], v[40:41], v[44:45] op_sel_hi:[0,1,1] neg_lo:[0,0,1] neg_hi:[0,0,1]
	s_waitcnt lgkmcnt(0)
	v_pk_fma_f32 v[30:31], v[28:29], v[48:49], v[30:31] op_sel_hi:[0,1,1] neg_lo:[0,0,1] neg_hi:[0,0,1]
	v_pk_fma_f32 v[28:29], v[28:29], v[50:51], v[54:55] op_sel_hi:[0,1,1] neg_lo:[0,0,1] neg_hi:[0,0,1]
	v_pk_add_f32 v[12:13], v[12:13], v[80:81]
	v_pk_add_f32 v[14:15], v[14:15], v[78:79]
	v_pk_add_f32 v[8:9], v[8:9], v[60:61]
	v_pk_add_f32 v[10:11], v[10:11], v[62:63]
	v_pk_add_f32 v[4:5], v[4:5], v[64:65]
	v_pk_add_f32 v[6:7], v[6:7], v[66:67]
	v_pk_add_f32 v[0:1], v[0:1], v[68:69]
	v_pk_add_f32 v[2:3], v[2:3], v[70:71]
	v_add_u32_e32 v35, 0x100, v35
	v_pk_add_f32 v[14:15], v[14:15], v[18:19]
	v_pk_add_f32 v[12:13], v[12:13], v[16:17]
	v_pk_add_f32 v[10:11], v[10:11], v[22:23]
	v_pk_add_f32 v[8:9], v[8:9], v[20:21]
	v_pk_add_f32 v[6:7], v[6:7], v[40:41]
	v_pk_add_f32 v[4:5], v[4:5], v[38:39]
	v_pk_add_f32 v[2:3], v[2:3], v[28:29]
	v_pk_add_f32 v[0:1], v[0:1], v[30:31]
	v_lshl_add_u64 v[16:17], v[24:25], 0, s[0:1]
	v_lshl_add_u64 v[18:19], v[26:27], 0, s[0:1]
	s_waitcnt vmcnt(14)
	v_mov_b32_e32 v72, v118
	v_mov_b32_e32 v73, v119
	v_mov_b32_e32 v74, v210
	v_mov_b32_e32 v75, v211
	ds_read2_b64 v[28:31], v36 offset1:17
	ds_read_b128 v[38:41], v35
	ds_read_b128 v[42:45], v35 offset:16
	ds_read_b128 v[48:51], v35 offset:32
	ds_read_b128 v[52:55], v35 offset:48
	ds_read_b128 v[56:59], v35 offset:64
	ds_read_b128 v[60:63], v35 offset:80
	ds_read_b128 v[64:67], v35 offset:96
	ds_read_b128 v[68:71], v35 offset:112
	ds_read_b128 v[16:19], v35 offset:128
	ds_read_b128 v[20:23], v35 offset:192
	s_add_u32 s0, s0, 8
	s_addc_u32 s1, s1, 0
	v_add_u32_e32 v36, 0x110, v36
	s_cmpk_eq_i32 s0, 0x100
	v_mov_b32_e32 v76, v72
	v_mov_b32_e32 v77, v74
	s_waitcnt lgkmcnt(10)
	v_mul_f32_e32 v78, v74, v29
	v_mov_b32_e32 v80, v74
	v_mov_b32_e32 v81, v72
	v_mul_f32_e32 v72, v72, v29
	v_pk_fma_f32 v[76:77], v[76:77], v[28:29], v[78:79] op_sel_hi:[1,1,0] neg_lo:[0,0,1] neg_hi:[0,0,1]
	v_pk_fma_f32 v[78:79], v[80:81], v[28:29], v[72:73] op_sel_hi:[1,1,0]
	v_mov_b32_e32 v74, v73
	v_mul_f32_e32 v28, v75, v31
	s_waitcnt lgkmcnt(4)
	v_pk_mul_f32 v[60:61], v[78:79], v[60:61] op_sel_hi:[0,1]
	v_pk_mul_f32 v[62:63], v[78:79], v[62:63] op_sel_hi:[0,1]
	s_waitcnt lgkmcnt(2)
	v_pk_mul_f32 v[68:69], v[78:79], v[68:69] op_sel_hi:[0,1]
	v_pk_mul_f32 v[70:71], v[78:79], v[70:71] op_sel_hi:[0,1]
	v_mov_b32_e32 v72, v75
	v_pk_fma_f32 v[28:29], v[74:75], v[30:31], v[28:29] op_sel_hi:[1,1,0] neg_lo:[0,0,1] neg_hi:[0,0,1]
	v_mul_f32_e32 v74, v73, v31
	v_pk_mul_f32 v[80:81], v[56:57], v[78:79] op_sel_hi:[1,0]
	v_pk_mul_f32 v[82:83], v[58:59], v[78:79] op_sel_hi:[1,0]
	v_pk_mul_f32 v[64:65], v[78:79], v[64:65] op_sel_hi:[0,1]
	v_pk_mul_f32 v[66:67], v[78:79], v[66:67] op_sel_hi:[0,1]
	ds_read_b128 v[56:59], v35 offset:208
	v_pk_fma_f32 v[62:63], v[44:45], v[76:77], v[62:63] op_sel_hi:[1,0,1] neg_lo:[0,0,1] neg_hi:[0,0,1]
	v_pk_fma_f32 v[60:61], v[42:43], v[76:77], v[60:61] op_sel_hi:[1,0,1] neg_lo:[0,0,1] neg_hi:[0,0,1]
	ds_read_b128 v[42:45], v35 offset:224
	v_pk_fma_f32 v[70:71], v[76:77], v[54:55], v[70:71] op_sel_hi:[0,1,1] neg_lo:[0,0,1] neg_hi:[0,0,1]
	v_pk_fma_f32 v[68:69], v[76:77], v[52:53], v[68:69] op_sel_hi:[0,1,1] neg_lo:[0,0,1] neg_hi:[0,0,1]
	ds_read_b128 v[52:55], v35 offset:240
	v_pk_fma_f32 v[30:31], v[72:73], v[30:31], v[74:75] op_sel_hi:[1,1,0]
	ds_read_b128 v[72:75], v35 offset:144
	v_pk_fma_f32 v[78:79], v[40:41], v[76:77], v[82:83] op_sel_hi:[1,0,1] neg_lo:[0,0,1] neg_hi:[0,0,1]
	v_pk_fma_f32 v[80:81], v[38:39], v[76:77], v[80:81] op_sel_hi:[1,0,1] neg_lo:[0,0,1] neg_hi:[0,0,1]
	ds_read_b128 v[38:41], v35 offset:160
	v_pk_fma_f32 v[66:67], v[76:77], v[50:51], v[66:67] op_sel_hi:[0,1,1] neg_lo:[0,0,1] neg_hi:[0,0,1]
	v_pk_fma_f32 v[64:65], v[76:77], v[48:49], v[64:65] op_sel_hi:[0,1,1] neg_lo:[0,0,1] neg_hi:[0,0,1]
	ds_read_b128 v[48:51], v35 offset:176
	s_waitcnt lgkmcnt(6)
	v_pk_mul_f32 v[22:23], v[22:23], v[30:31] op_sel_hi:[1,0]
	v_pk_mul_f32 v[20:21], v[20:21], v[30:31] op_sel_hi:[1,0]
	s_waitcnt lgkmcnt(5)
	v_pk_mul_f32 v[58:59], v[30:31], v[58:59] op_sel_hi:[0,1]
	v_pk_mul_f32 v[56:57], v[30:31], v[56:57] op_sel_hi:[0,1]
	s_waitcnt lgkmcnt(4)
	v_pk_mul_f32 v[44:45], v[30:31], v[44:45] op_sel_hi:[0,1]
	v_pk_mul_f32 v[42:43], v[30:31], v[42:43] op_sel_hi:[0,1]
	s_waitcnt lgkmcnt(3)
	v_pk_mul_f32 v[54:55], v[30:31], v[54:55] op_sel_hi:[0,1]
	v_pk_mul_f32 v[30:31], v[30:31], v[52:53] op_sel_hi:[0,1]
	v_pk_fma_f32 v[16:17], v[16:17], v[28:29], v[20:21] op_sel_hi:[1,0,1] neg_lo:[0,0,1] neg_hi:[0,0,1]
	v_pk_fma_f32 v[18:19], v[18:19], v[28:29], v[22:23] op_sel_hi:[1,0,1] neg_lo:[0,0,1] neg_hi:[0,0,1]
	s_waitcnt lgkmcnt(2)
	v_pk_fma_f32 v[20:21], v[72:73], v[28:29], v[56:57] op_sel_hi:[1,0,1] neg_lo:[0,0,1] neg_hi:[0,0,1]
	v_pk_fma_f32 v[22:23], v[74:75], v[28:29], v[58:59] op_sel_hi:[1,0,1] neg_lo:[0,0,1] neg_hi:[0,0,1]
	s_waitcnt lgkmcnt(1)
	v_pk_fma_f32 v[38:39], v[28:29], v[38:39], v[42:43] op_sel_hi:[0,1,1] neg_lo:[0,0,1] neg_hi:[0,0,1]
	v_pk_fma_f32 v[40:41], v[28:29], v[40:41], v[44:45] op_sel_hi:[0,1,1] neg_lo:[0,0,1] neg_hi:[0,0,1]
	s_waitcnt lgkmcnt(0)
	v_pk_fma_f32 v[30:31], v[28:29], v[48:49], v[30:31] op_sel_hi:[0,1,1] neg_lo:[0,0,1] neg_hi:[0,0,1]
	v_pk_fma_f32 v[28:29], v[28:29], v[50:51], v[54:55] op_sel_hi:[0,1,1] neg_lo:[0,0,1] neg_hi:[0,0,1]
	v_pk_add_f32 v[12:13], v[12:13], v[80:81]
	v_pk_add_f32 v[14:15], v[14:15], v[78:79]
	v_pk_add_f32 v[8:9], v[8:9], v[60:61]
	v_pk_add_f32 v[10:11], v[10:11], v[62:63]
	v_pk_add_f32 v[4:5], v[4:5], v[64:65]
	v_pk_add_f32 v[6:7], v[6:7], v[66:67]
	v_pk_add_f32 v[0:1], v[0:1], v[68:69]
	v_pk_add_f32 v[2:3], v[2:3], v[70:71]
	v_add_u32_e32 v35, 0x100, v35
	v_pk_add_f32 v[14:15], v[14:15], v[18:19]
	v_pk_add_f32 v[12:13], v[12:13], v[16:17]
	v_pk_add_f32 v[10:11], v[10:11], v[22:23]
	v_pk_add_f32 v[8:9], v[8:9], v[20:21]
	v_pk_add_f32 v[6:7], v[6:7], v[40:41]
	v_pk_add_f32 v[4:5], v[4:5], v[38:39]
	v_pk_add_f32 v[2:3], v[2:3], v[28:29]
	v_pk_add_f32 v[0:1], v[0:1], v[30:31]
	v_lshl_add_u64 v[16:17], v[24:25], 0, s[0:1]
	v_lshl_add_u64 v[18:19], v[26:27], 0, s[0:1]
	s_waitcnt vmcnt(12)
	v_mov_b32_e32 v72, v120
	v_mov_b32_e32 v73, v121
	v_mov_b32_e32 v74, v212
	v_mov_b32_e32 v75, v213
	ds_read2_b64 v[28:31], v36 offset1:17
	ds_read_b128 v[38:41], v35
	ds_read_b128 v[42:45], v35 offset:16
	ds_read_b128 v[48:51], v35 offset:32
	ds_read_b128 v[52:55], v35 offset:48
	ds_read_b128 v[56:59], v35 offset:64
	ds_read_b128 v[60:63], v35 offset:80
	ds_read_b128 v[64:67], v35 offset:96
	ds_read_b128 v[68:71], v35 offset:112
	ds_read_b128 v[16:19], v35 offset:128
	ds_read_b128 v[20:23], v35 offset:192
	s_add_u32 s0, s0, 8
	s_addc_u32 s1, s1, 0
	v_add_u32_e32 v36, 0x110, v36
	s_cmpk_eq_i32 s0, 0x100
	v_mov_b32_e32 v76, v72
	v_mov_b32_e32 v77, v74
	s_waitcnt lgkmcnt(10)
	v_mul_f32_e32 v78, v74, v29
	v_mov_b32_e32 v80, v74
	v_mov_b32_e32 v81, v72
	v_mul_f32_e32 v72, v72, v29
	v_pk_fma_f32 v[76:77], v[76:77], v[28:29], v[78:79] op_sel_hi:[1,1,0] neg_lo:[0,0,1] neg_hi:[0,0,1]
	v_pk_fma_f32 v[78:79], v[80:81], v[28:29], v[72:73] op_sel_hi:[1,1,0]
	v_mov_b32_e32 v74, v73
	v_mul_f32_e32 v28, v75, v31
	s_waitcnt lgkmcnt(4)
	v_pk_mul_f32 v[60:61], v[78:79], v[60:61] op_sel_hi:[0,1]
	v_pk_mul_f32 v[62:63], v[78:79], v[62:63] op_sel_hi:[0,1]
	s_waitcnt lgkmcnt(2)
	v_pk_mul_f32 v[68:69], v[78:79], v[68:69] op_sel_hi:[0,1]
	v_pk_mul_f32 v[70:71], v[78:79], v[70:71] op_sel_hi:[0,1]
	v_mov_b32_e32 v72, v75
	v_pk_fma_f32 v[28:29], v[74:75], v[30:31], v[28:29] op_sel_hi:[1,1,0] neg_lo:[0,0,1] neg_hi:[0,0,1]
	v_mul_f32_e32 v74, v73, v31
	v_pk_mul_f32 v[80:81], v[56:57], v[78:79] op_sel_hi:[1,0]
	v_pk_mul_f32 v[82:83], v[58:59], v[78:79] op_sel_hi:[1,0]
	v_pk_mul_f32 v[64:65], v[78:79], v[64:65] op_sel_hi:[0,1]
	v_pk_mul_f32 v[66:67], v[78:79], v[66:67] op_sel_hi:[0,1]
	ds_read_b128 v[56:59], v35 offset:208
	v_pk_fma_f32 v[62:63], v[44:45], v[76:77], v[62:63] op_sel_hi:[1,0,1] neg_lo:[0,0,1] neg_hi:[0,0,1]
	v_pk_fma_f32 v[60:61], v[42:43], v[76:77], v[60:61] op_sel_hi:[1,0,1] neg_lo:[0,0,1] neg_hi:[0,0,1]
	ds_read_b128 v[42:45], v35 offset:224
	v_pk_fma_f32 v[70:71], v[76:77], v[54:55], v[70:71] op_sel_hi:[0,1,1] neg_lo:[0,0,1] neg_hi:[0,0,1]
	v_pk_fma_f32 v[68:69], v[76:77], v[52:53], v[68:69] op_sel_hi:[0,1,1] neg_lo:[0,0,1] neg_hi:[0,0,1]
	ds_read_b128 v[52:55], v35 offset:240
	v_pk_fma_f32 v[30:31], v[72:73], v[30:31], v[74:75] op_sel_hi:[1,1,0]
	ds_read_b128 v[72:75], v35 offset:144
	v_pk_fma_f32 v[78:79], v[40:41], v[76:77], v[82:83] op_sel_hi:[1,0,1] neg_lo:[0,0,1] neg_hi:[0,0,1]
	v_pk_fma_f32 v[80:81], v[38:39], v[76:77], v[80:81] op_sel_hi:[1,0,1] neg_lo:[0,0,1] neg_hi:[0,0,1]
	ds_read_b128 v[38:41], v35 offset:160
	v_pk_fma_f32 v[66:67], v[76:77], v[50:51], v[66:67] op_sel_hi:[0,1,1] neg_lo:[0,0,1] neg_hi:[0,0,1]
	v_pk_fma_f32 v[64:65], v[76:77], v[48:49], v[64:65] op_sel_hi:[0,1,1] neg_lo:[0,0,1] neg_hi:[0,0,1]
	ds_read_b128 v[48:51], v35 offset:176
	s_waitcnt lgkmcnt(6)
	v_pk_mul_f32 v[22:23], v[22:23], v[30:31] op_sel_hi:[1,0]
	v_pk_mul_f32 v[20:21], v[20:21], v[30:31] op_sel_hi:[1,0]
	s_waitcnt lgkmcnt(5)
	v_pk_mul_f32 v[58:59], v[30:31], v[58:59] op_sel_hi:[0,1]
	v_pk_mul_f32 v[56:57], v[30:31], v[56:57] op_sel_hi:[0,1]
	s_waitcnt lgkmcnt(4)
	v_pk_mul_f32 v[44:45], v[30:31], v[44:45] op_sel_hi:[0,1]
	v_pk_mul_f32 v[42:43], v[30:31], v[42:43] op_sel_hi:[0,1]
	s_waitcnt lgkmcnt(3)
	v_pk_mul_f32 v[54:55], v[30:31], v[54:55] op_sel_hi:[0,1]
	v_pk_mul_f32 v[30:31], v[30:31], v[52:53] op_sel_hi:[0,1]
	v_pk_fma_f32 v[16:17], v[16:17], v[28:29], v[20:21] op_sel_hi:[1,0,1] neg_lo:[0,0,1] neg_hi:[0,0,1]
	v_pk_fma_f32 v[18:19], v[18:19], v[28:29], v[22:23] op_sel_hi:[1,0,1] neg_lo:[0,0,1] neg_hi:[0,0,1]
	s_waitcnt lgkmcnt(2)
	v_pk_fma_f32 v[20:21], v[72:73], v[28:29], v[56:57] op_sel_hi:[1,0,1] neg_lo:[0,0,1] neg_hi:[0,0,1]
	v_pk_fma_f32 v[22:23], v[74:75], v[28:29], v[58:59] op_sel_hi:[1,0,1] neg_lo:[0,0,1] neg_hi:[0,0,1]
	s_waitcnt lgkmcnt(1)
	v_pk_fma_f32 v[38:39], v[28:29], v[38:39], v[42:43] op_sel_hi:[0,1,1] neg_lo:[0,0,1] neg_hi:[0,0,1]
	v_pk_fma_f32 v[40:41], v[28:29], v[40:41], v[44:45] op_sel_hi:[0,1,1] neg_lo:[0,0,1] neg_hi:[0,0,1]
	s_waitcnt lgkmcnt(0)
	v_pk_fma_f32 v[30:31], v[28:29], v[48:49], v[30:31] op_sel_hi:[0,1,1] neg_lo:[0,0,1] neg_hi:[0,0,1]
	v_pk_fma_f32 v[28:29], v[28:29], v[50:51], v[54:55] op_sel_hi:[0,1,1] neg_lo:[0,0,1] neg_hi:[0,0,1]
	v_pk_add_f32 v[12:13], v[12:13], v[80:81]
	v_pk_add_f32 v[14:15], v[14:15], v[78:79]
	v_pk_add_f32 v[8:9], v[8:9], v[60:61]
	v_pk_add_f32 v[10:11], v[10:11], v[62:63]
	v_pk_add_f32 v[4:5], v[4:5], v[64:65]
	v_pk_add_f32 v[6:7], v[6:7], v[66:67]
	v_pk_add_f32 v[0:1], v[0:1], v[68:69]
	v_pk_add_f32 v[2:3], v[2:3], v[70:71]
	v_add_u32_e32 v35, 0x100, v35
	v_pk_add_f32 v[14:15], v[14:15], v[18:19]
	v_pk_add_f32 v[12:13], v[12:13], v[16:17]
	v_pk_add_f32 v[10:11], v[10:11], v[22:23]
	v_pk_add_f32 v[8:9], v[8:9], v[20:21]
	v_pk_add_f32 v[6:7], v[6:7], v[40:41]
	v_pk_add_f32 v[4:5], v[4:5], v[38:39]
	v_pk_add_f32 v[2:3], v[2:3], v[28:29]
	v_pk_add_f32 v[0:1], v[0:1], v[30:31]
	v_lshl_add_u64 v[16:17], v[24:25], 0, s[0:1]
	v_lshl_add_u64 v[18:19], v[26:27], 0, s[0:1]
	s_waitcnt vmcnt(12)
	v_mov_b32_e32 v72, v122
	v_mov_b32_e32 v73, v123
	v_mov_b32_e32 v74, v214
	v_mov_b32_e32 v75, v215
	ds_read2_b64 v[28:31], v36 offset1:17
	ds_read_b128 v[38:41], v35
	ds_read_b128 v[42:45], v35 offset:16
	ds_read_b128 v[48:51], v35 offset:32
	ds_read_b128 v[52:55], v35 offset:48
	ds_read_b128 v[56:59], v35 offset:64
	ds_read_b128 v[60:63], v35 offset:80
	ds_read_b128 v[64:67], v35 offset:96
	ds_read_b128 v[68:71], v35 offset:112
	ds_read_b128 v[16:19], v35 offset:128
	ds_read_b128 v[20:23], v35 offset:192
	s_add_u32 s0, s0, 8
	s_addc_u32 s1, s1, 0
	v_add_u32_e32 v36, 0x110, v36
	s_cmpk_eq_i32 s0, 0x100
	v_mov_b32_e32 v76, v72
	v_mov_b32_e32 v77, v74
	s_waitcnt lgkmcnt(10)
	v_mul_f32_e32 v78, v74, v29
	v_mov_b32_e32 v80, v74
	v_mov_b32_e32 v81, v72
	v_mul_f32_e32 v72, v72, v29
	v_pk_fma_f32 v[76:77], v[76:77], v[28:29], v[78:79] op_sel_hi:[1,1,0] neg_lo:[0,0,1] neg_hi:[0,0,1]
	v_pk_fma_f32 v[78:79], v[80:81], v[28:29], v[72:73] op_sel_hi:[1,1,0]
	v_mov_b32_e32 v74, v73
	v_mul_f32_e32 v28, v75, v31
	s_waitcnt lgkmcnt(4)
	v_pk_mul_f32 v[60:61], v[78:79], v[60:61] op_sel_hi:[0,1]
	v_pk_mul_f32 v[62:63], v[78:79], v[62:63] op_sel_hi:[0,1]
	s_waitcnt lgkmcnt(2)
	v_pk_mul_f32 v[68:69], v[78:79], v[68:69] op_sel_hi:[0,1]
	v_pk_mul_f32 v[70:71], v[78:79], v[70:71] op_sel_hi:[0,1]
	v_mov_b32_e32 v72, v75
	v_pk_fma_f32 v[28:29], v[74:75], v[30:31], v[28:29] op_sel_hi:[1,1,0] neg_lo:[0,0,1] neg_hi:[0,0,1]
	v_mul_f32_e32 v74, v73, v31
	v_pk_mul_f32 v[80:81], v[56:57], v[78:79] op_sel_hi:[1,0]
	v_pk_mul_f32 v[82:83], v[58:59], v[78:79] op_sel_hi:[1,0]
	v_pk_mul_f32 v[64:65], v[78:79], v[64:65] op_sel_hi:[0,1]
	v_pk_mul_f32 v[66:67], v[78:79], v[66:67] op_sel_hi:[0,1]
	ds_read_b128 v[56:59], v35 offset:208
	v_pk_fma_f32 v[62:63], v[44:45], v[76:77], v[62:63] op_sel_hi:[1,0,1] neg_lo:[0,0,1] neg_hi:[0,0,1]
	v_pk_fma_f32 v[60:61], v[42:43], v[76:77], v[60:61] op_sel_hi:[1,0,1] neg_lo:[0,0,1] neg_hi:[0,0,1]
	ds_read_b128 v[42:45], v35 offset:224
	v_pk_fma_f32 v[70:71], v[76:77], v[54:55], v[70:71] op_sel_hi:[0,1,1] neg_lo:[0,0,1] neg_hi:[0,0,1]
	v_pk_fma_f32 v[68:69], v[76:77], v[52:53], v[68:69] op_sel_hi:[0,1,1] neg_lo:[0,0,1] neg_hi:[0,0,1]
	ds_read_b128 v[52:55], v35 offset:240
	v_pk_fma_f32 v[30:31], v[72:73], v[30:31], v[74:75] op_sel_hi:[1,1,0]
	ds_read_b128 v[72:75], v35 offset:144
	v_pk_fma_f32 v[78:79], v[40:41], v[76:77], v[82:83] op_sel_hi:[1,0,1] neg_lo:[0,0,1] neg_hi:[0,0,1]
	v_pk_fma_f32 v[80:81], v[38:39], v[76:77], v[80:81] op_sel_hi:[1,0,1] neg_lo:[0,0,1] neg_hi:[0,0,1]
	ds_read_b128 v[38:41], v35 offset:160
	v_pk_fma_f32 v[66:67], v[76:77], v[50:51], v[66:67] op_sel_hi:[0,1,1] neg_lo:[0,0,1] neg_hi:[0,0,1]
	v_pk_fma_f32 v[64:65], v[76:77], v[48:49], v[64:65] op_sel_hi:[0,1,1] neg_lo:[0,0,1] neg_hi:[0,0,1]
	ds_read_b128 v[48:51], v35 offset:176
	s_waitcnt lgkmcnt(6)
	v_pk_mul_f32 v[22:23], v[22:23], v[30:31] op_sel_hi:[1,0]
	v_pk_mul_f32 v[20:21], v[20:21], v[30:31] op_sel_hi:[1,0]
	s_waitcnt lgkmcnt(5)
	v_pk_mul_f32 v[58:59], v[30:31], v[58:59] op_sel_hi:[0,1]
	v_pk_mul_f32 v[56:57], v[30:31], v[56:57] op_sel_hi:[0,1]
	s_waitcnt lgkmcnt(4)
	v_pk_mul_f32 v[44:45], v[30:31], v[44:45] op_sel_hi:[0,1]
	v_pk_mul_f32 v[42:43], v[30:31], v[42:43] op_sel_hi:[0,1]
	s_waitcnt lgkmcnt(3)
	v_pk_mul_f32 v[54:55], v[30:31], v[54:55] op_sel_hi:[0,1]
	v_pk_mul_f32 v[30:31], v[30:31], v[52:53] op_sel_hi:[0,1]
	v_pk_fma_f32 v[16:17], v[16:17], v[28:29], v[20:21] op_sel_hi:[1,0,1] neg_lo:[0,0,1] neg_hi:[0,0,1]
	v_pk_fma_f32 v[18:19], v[18:19], v[28:29], v[22:23] op_sel_hi:[1,0,1] neg_lo:[0,0,1] neg_hi:[0,0,1]
	s_waitcnt lgkmcnt(2)
	v_pk_fma_f32 v[20:21], v[72:73], v[28:29], v[56:57] op_sel_hi:[1,0,1] neg_lo:[0,0,1] neg_hi:[0,0,1]
	v_pk_fma_f32 v[22:23], v[74:75], v[28:29], v[58:59] op_sel_hi:[1,0,1] neg_lo:[0,0,1] neg_hi:[0,0,1]
	s_waitcnt lgkmcnt(1)
	v_pk_fma_f32 v[38:39], v[28:29], v[38:39], v[42:43] op_sel_hi:[0,1,1] neg_lo:[0,0,1] neg_hi:[0,0,1]
	v_pk_fma_f32 v[40:41], v[28:29], v[40:41], v[44:45] op_sel_hi:[0,1,1] neg_lo:[0,0,1] neg_hi:[0,0,1]
	s_waitcnt lgkmcnt(0)
	v_pk_fma_f32 v[30:31], v[28:29], v[48:49], v[30:31] op_sel_hi:[0,1,1] neg_lo:[0,0,1] neg_hi:[0,0,1]
	v_pk_fma_f32 v[28:29], v[28:29], v[50:51], v[54:55] op_sel_hi:[0,1,1] neg_lo:[0,0,1] neg_hi:[0,0,1]
	v_pk_add_f32 v[12:13], v[12:13], v[80:81]
	v_pk_add_f32 v[14:15], v[14:15], v[78:79]
	v_pk_add_f32 v[8:9], v[8:9], v[60:61]
	v_pk_add_f32 v[10:11], v[10:11], v[62:63]
	v_pk_add_f32 v[4:5], v[4:5], v[64:65]
	v_pk_add_f32 v[6:7], v[6:7], v[66:67]
	v_pk_add_f32 v[0:1], v[0:1], v[68:69]
	v_pk_add_f32 v[2:3], v[2:3], v[70:71]
	v_add_u32_e32 v35, 0x100, v35
	v_pk_add_f32 v[14:15], v[14:15], v[18:19]
	v_pk_add_f32 v[12:13], v[12:13], v[16:17]
	v_pk_add_f32 v[10:11], v[10:11], v[22:23]
	v_pk_add_f32 v[8:9], v[8:9], v[20:21]
	v_pk_add_f32 v[6:7], v[6:7], v[40:41]
	v_pk_add_f32 v[4:5], v[4:5], v[38:39]
	v_pk_add_f32 v[2:3], v[2:3], v[28:29]
	v_pk_add_f32 v[0:1], v[0:1], v[30:31]
	v_lshl_add_u64 v[16:17], v[24:25], 0, s[0:1]
	v_lshl_add_u64 v[18:19], v[26:27], 0, s[0:1]
	s_waitcnt vmcnt(10)
	v_mov_b32_e32 v72, v124
	v_mov_b32_e32 v73, v125
	v_mov_b32_e32 v74, v216
	v_mov_b32_e32 v75, v217
	ds_read2_b64 v[28:31], v36 offset1:17
	ds_read_b128 v[38:41], v35
	ds_read_b128 v[42:45], v35 offset:16
	ds_read_b128 v[48:51], v35 offset:32
	ds_read_b128 v[52:55], v35 offset:48
	ds_read_b128 v[56:59], v35 offset:64
	ds_read_b128 v[60:63], v35 offset:80
	ds_read_b128 v[64:67], v35 offset:96
	ds_read_b128 v[68:71], v35 offset:112
	ds_read_b128 v[16:19], v35 offset:128
	ds_read_b128 v[20:23], v35 offset:192
	s_add_u32 s0, s0, 8
	s_addc_u32 s1, s1, 0
	v_add_u32_e32 v36, 0x110, v36
	s_cmpk_eq_i32 s0, 0x100
	v_mov_b32_e32 v76, v72
	v_mov_b32_e32 v77, v74
	s_waitcnt lgkmcnt(10)
	v_mul_f32_e32 v78, v74, v29
	v_mov_b32_e32 v80, v74
	v_mov_b32_e32 v81, v72
	v_mul_f32_e32 v72, v72, v29
	v_pk_fma_f32 v[76:77], v[76:77], v[28:29], v[78:79] op_sel_hi:[1,1,0] neg_lo:[0,0,1] neg_hi:[0,0,1]
	v_pk_fma_f32 v[78:79], v[80:81], v[28:29], v[72:73] op_sel_hi:[1,1,0]
	v_mov_b32_e32 v74, v73
	v_mul_f32_e32 v28, v75, v31
	s_waitcnt lgkmcnt(4)
	v_pk_mul_f32 v[60:61], v[78:79], v[60:61] op_sel_hi:[0,1]
	v_pk_mul_f32 v[62:63], v[78:79], v[62:63] op_sel_hi:[0,1]
	s_waitcnt lgkmcnt(2)
	v_pk_mul_f32 v[68:69], v[78:79], v[68:69] op_sel_hi:[0,1]
	v_pk_mul_f32 v[70:71], v[78:79], v[70:71] op_sel_hi:[0,1]
	v_mov_b32_e32 v72, v75
	v_pk_fma_f32 v[28:29], v[74:75], v[30:31], v[28:29] op_sel_hi:[1,1,0] neg_lo:[0,0,1] neg_hi:[0,0,1]
	v_mul_f32_e32 v74, v73, v31
	v_pk_mul_f32 v[80:81], v[56:57], v[78:79] op_sel_hi:[1,0]
	v_pk_mul_f32 v[82:83], v[58:59], v[78:79] op_sel_hi:[1,0]
	v_pk_mul_f32 v[64:65], v[78:79], v[64:65] op_sel_hi:[0,1]
	v_pk_mul_f32 v[66:67], v[78:79], v[66:67] op_sel_hi:[0,1]
	ds_read_b128 v[56:59], v35 offset:208
	v_pk_fma_f32 v[62:63], v[44:45], v[76:77], v[62:63] op_sel_hi:[1,0,1] neg_lo:[0,0,1] neg_hi:[0,0,1]
	v_pk_fma_f32 v[60:61], v[42:43], v[76:77], v[60:61] op_sel_hi:[1,0,1] neg_lo:[0,0,1] neg_hi:[0,0,1]
	ds_read_b128 v[42:45], v35 offset:224
	v_pk_fma_f32 v[70:71], v[76:77], v[54:55], v[70:71] op_sel_hi:[0,1,1] neg_lo:[0,0,1] neg_hi:[0,0,1]
	v_pk_fma_f32 v[68:69], v[76:77], v[52:53], v[68:69] op_sel_hi:[0,1,1] neg_lo:[0,0,1] neg_hi:[0,0,1]
	ds_read_b128 v[52:55], v35 offset:240
	v_pk_fma_f32 v[30:31], v[72:73], v[30:31], v[74:75] op_sel_hi:[1,1,0]
	ds_read_b128 v[72:75], v35 offset:144
	v_pk_fma_f32 v[78:79], v[40:41], v[76:77], v[82:83] op_sel_hi:[1,0,1] neg_lo:[0,0,1] neg_hi:[0,0,1]
	v_pk_fma_f32 v[80:81], v[38:39], v[76:77], v[80:81] op_sel_hi:[1,0,1] neg_lo:[0,0,1] neg_hi:[0,0,1]
	ds_read_b128 v[38:41], v35 offset:160
	v_pk_fma_f32 v[66:67], v[76:77], v[50:51], v[66:67] op_sel_hi:[0,1,1] neg_lo:[0,0,1] neg_hi:[0,0,1]
	v_pk_fma_f32 v[64:65], v[76:77], v[48:49], v[64:65] op_sel_hi:[0,1,1] neg_lo:[0,0,1] neg_hi:[0,0,1]
	ds_read_b128 v[48:51], v35 offset:176
	s_waitcnt lgkmcnt(6)
	v_pk_mul_f32 v[22:23], v[22:23], v[30:31] op_sel_hi:[1,0]
	v_pk_mul_f32 v[20:21], v[20:21], v[30:31] op_sel_hi:[1,0]
	s_waitcnt lgkmcnt(5)
	v_pk_mul_f32 v[58:59], v[30:31], v[58:59] op_sel_hi:[0,1]
	v_pk_mul_f32 v[56:57], v[30:31], v[56:57] op_sel_hi:[0,1]
	s_waitcnt lgkmcnt(4)
	v_pk_mul_f32 v[44:45], v[30:31], v[44:45] op_sel_hi:[0,1]
	v_pk_mul_f32 v[42:43], v[30:31], v[42:43] op_sel_hi:[0,1]
	s_waitcnt lgkmcnt(3)
	v_pk_mul_f32 v[54:55], v[30:31], v[54:55] op_sel_hi:[0,1]
	v_pk_mul_f32 v[30:31], v[30:31], v[52:53] op_sel_hi:[0,1]
	v_pk_fma_f32 v[16:17], v[16:17], v[28:29], v[20:21] op_sel_hi:[1,0,1] neg_lo:[0,0,1] neg_hi:[0,0,1]
	v_pk_fma_f32 v[18:19], v[18:19], v[28:29], v[22:23] op_sel_hi:[1,0,1] neg_lo:[0,0,1] neg_hi:[0,0,1]
	s_waitcnt lgkmcnt(2)
	v_pk_fma_f32 v[20:21], v[72:73], v[28:29], v[56:57] op_sel_hi:[1,0,1] neg_lo:[0,0,1] neg_hi:[0,0,1]
	v_pk_fma_f32 v[22:23], v[74:75], v[28:29], v[58:59] op_sel_hi:[1,0,1] neg_lo:[0,0,1] neg_hi:[0,0,1]
	s_waitcnt lgkmcnt(1)
	v_pk_fma_f32 v[38:39], v[28:29], v[38:39], v[42:43] op_sel_hi:[0,1,1] neg_lo:[0,0,1] neg_hi:[0,0,1]
	v_pk_fma_f32 v[40:41], v[28:29], v[40:41], v[44:45] op_sel_hi:[0,1,1] neg_lo:[0,0,1] neg_hi:[0,0,1]
	s_waitcnt lgkmcnt(0)
	v_pk_fma_f32 v[30:31], v[28:29], v[48:49], v[30:31] op_sel_hi:[0,1,1] neg_lo:[0,0,1] neg_hi:[0,0,1]
	v_pk_fma_f32 v[28:29], v[28:29], v[50:51], v[54:55] op_sel_hi:[0,1,1] neg_lo:[0,0,1] neg_hi:[0,0,1]
	v_pk_add_f32 v[12:13], v[12:13], v[80:81]
	v_pk_add_f32 v[14:15], v[14:15], v[78:79]
	v_pk_add_f32 v[8:9], v[8:9], v[60:61]
	v_pk_add_f32 v[10:11], v[10:11], v[62:63]
	v_pk_add_f32 v[4:5], v[4:5], v[64:65]
	v_pk_add_f32 v[6:7], v[6:7], v[66:67]
	v_pk_add_f32 v[0:1], v[0:1], v[68:69]
	v_pk_add_f32 v[2:3], v[2:3], v[70:71]
	v_add_u32_e32 v35, 0x100, v35
	v_pk_add_f32 v[14:15], v[14:15], v[18:19]
	v_pk_add_f32 v[12:13], v[12:13], v[16:17]
	v_pk_add_f32 v[10:11], v[10:11], v[22:23]
	v_pk_add_f32 v[8:9], v[8:9], v[20:21]
	v_pk_add_f32 v[6:7], v[6:7], v[40:41]
	v_pk_add_f32 v[4:5], v[4:5], v[38:39]
	v_pk_add_f32 v[2:3], v[2:3], v[28:29]
	v_pk_add_f32 v[0:1], v[0:1], v[30:31]
	v_lshl_add_u64 v[16:17], v[24:25], 0, s[0:1]
	v_lshl_add_u64 v[18:19], v[26:27], 0, s[0:1]
	s_waitcnt vmcnt(10)
	v_mov_b32_e32 v72, v126
	v_mov_b32_e32 v73, v127
	v_mov_b32_e32 v74, v218
	v_mov_b32_e32 v75, v219
	ds_read2_b64 v[28:31], v36 offset1:17
	ds_read_b128 v[38:41], v35
	ds_read_b128 v[42:45], v35 offset:16
	ds_read_b128 v[48:51], v35 offset:32
	ds_read_b128 v[52:55], v35 offset:48
	ds_read_b128 v[56:59], v35 offset:64
	ds_read_b128 v[60:63], v35 offset:80
	ds_read_b128 v[64:67], v35 offset:96
	ds_read_b128 v[68:71], v35 offset:112
	ds_read_b128 v[16:19], v35 offset:128
	ds_read_b128 v[20:23], v35 offset:192
	s_add_u32 s0, s0, 8
	s_addc_u32 s1, s1, 0
	v_add_u32_e32 v36, 0x110, v36
	s_cmpk_eq_i32 s0, 0x100
	v_mov_b32_e32 v76, v72
	v_mov_b32_e32 v77, v74
	s_waitcnt lgkmcnt(10)
	v_mul_f32_e32 v78, v74, v29
	v_mov_b32_e32 v80, v74
	v_mov_b32_e32 v81, v72
	v_mul_f32_e32 v72, v72, v29
	v_pk_fma_f32 v[76:77], v[76:77], v[28:29], v[78:79] op_sel_hi:[1,1,0] neg_lo:[0,0,1] neg_hi:[0,0,1]
	v_pk_fma_f32 v[78:79], v[80:81], v[28:29], v[72:73] op_sel_hi:[1,1,0]
	v_mov_b32_e32 v74, v73
	v_mul_f32_e32 v28, v75, v31
	s_waitcnt lgkmcnt(4)
	v_pk_mul_f32 v[60:61], v[78:79], v[60:61] op_sel_hi:[0,1]
	v_pk_mul_f32 v[62:63], v[78:79], v[62:63] op_sel_hi:[0,1]
	s_waitcnt lgkmcnt(2)
	v_pk_mul_f32 v[68:69], v[78:79], v[68:69] op_sel_hi:[0,1]
	v_pk_mul_f32 v[70:71], v[78:79], v[70:71] op_sel_hi:[0,1]
	v_mov_b32_e32 v72, v75
	v_pk_fma_f32 v[28:29], v[74:75], v[30:31], v[28:29] op_sel_hi:[1,1,0] neg_lo:[0,0,1] neg_hi:[0,0,1]
	v_mul_f32_e32 v74, v73, v31
	v_pk_mul_f32 v[80:81], v[56:57], v[78:79] op_sel_hi:[1,0]
	v_pk_mul_f32 v[82:83], v[58:59], v[78:79] op_sel_hi:[1,0]
	v_pk_mul_f32 v[64:65], v[78:79], v[64:65] op_sel_hi:[0,1]
	v_pk_mul_f32 v[66:67], v[78:79], v[66:67] op_sel_hi:[0,1]
	ds_read_b128 v[56:59], v35 offset:208
	v_pk_fma_f32 v[62:63], v[44:45], v[76:77], v[62:63] op_sel_hi:[1,0,1] neg_lo:[0,0,1] neg_hi:[0,0,1]
	v_pk_fma_f32 v[60:61], v[42:43], v[76:77], v[60:61] op_sel_hi:[1,0,1] neg_lo:[0,0,1] neg_hi:[0,0,1]
	ds_read_b128 v[42:45], v35 offset:224
	v_pk_fma_f32 v[70:71], v[76:77], v[54:55], v[70:71] op_sel_hi:[0,1,1] neg_lo:[0,0,1] neg_hi:[0,0,1]
	v_pk_fma_f32 v[68:69], v[76:77], v[52:53], v[68:69] op_sel_hi:[0,1,1] neg_lo:[0,0,1] neg_hi:[0,0,1]
	ds_read_b128 v[52:55], v35 offset:240
	v_pk_fma_f32 v[30:31], v[72:73], v[30:31], v[74:75] op_sel_hi:[1,1,0]
	ds_read_b128 v[72:75], v35 offset:144
	v_pk_fma_f32 v[78:79], v[40:41], v[76:77], v[82:83] op_sel_hi:[1,0,1] neg_lo:[0,0,1] neg_hi:[0,0,1]
	v_pk_fma_f32 v[80:81], v[38:39], v[76:77], v[80:81] op_sel_hi:[1,0,1] neg_lo:[0,0,1] neg_hi:[0,0,1]
	ds_read_b128 v[38:41], v35 offset:160
	v_pk_fma_f32 v[66:67], v[76:77], v[50:51], v[66:67] op_sel_hi:[0,1,1] neg_lo:[0,0,1] neg_hi:[0,0,1]
	v_pk_fma_f32 v[64:65], v[76:77], v[48:49], v[64:65] op_sel_hi:[0,1,1] neg_lo:[0,0,1] neg_hi:[0,0,1]
	ds_read_b128 v[48:51], v35 offset:176
	s_waitcnt lgkmcnt(6)
	v_pk_mul_f32 v[22:23], v[22:23], v[30:31] op_sel_hi:[1,0]
	v_pk_mul_f32 v[20:21], v[20:21], v[30:31] op_sel_hi:[1,0]
	s_waitcnt lgkmcnt(5)
	v_pk_mul_f32 v[58:59], v[30:31], v[58:59] op_sel_hi:[0,1]
	v_pk_mul_f32 v[56:57], v[30:31], v[56:57] op_sel_hi:[0,1]
	s_waitcnt lgkmcnt(4)
	v_pk_mul_f32 v[44:45], v[30:31], v[44:45] op_sel_hi:[0,1]
	v_pk_mul_f32 v[42:43], v[30:31], v[42:43] op_sel_hi:[0,1]
	s_waitcnt lgkmcnt(3)
	v_pk_mul_f32 v[54:55], v[30:31], v[54:55] op_sel_hi:[0,1]
	v_pk_mul_f32 v[30:31], v[30:31], v[52:53] op_sel_hi:[0,1]
	v_pk_fma_f32 v[16:17], v[16:17], v[28:29], v[20:21] op_sel_hi:[1,0,1] neg_lo:[0,0,1] neg_hi:[0,0,1]
	v_pk_fma_f32 v[18:19], v[18:19], v[28:29], v[22:23] op_sel_hi:[1,0,1] neg_lo:[0,0,1] neg_hi:[0,0,1]
	s_waitcnt lgkmcnt(2)
	v_pk_fma_f32 v[20:21], v[72:73], v[28:29], v[56:57] op_sel_hi:[1,0,1] neg_lo:[0,0,1] neg_hi:[0,0,1]
	v_pk_fma_f32 v[22:23], v[74:75], v[28:29], v[58:59] op_sel_hi:[1,0,1] neg_lo:[0,0,1] neg_hi:[0,0,1]
	s_waitcnt lgkmcnt(1)
	v_pk_fma_f32 v[38:39], v[28:29], v[38:39], v[42:43] op_sel_hi:[0,1,1] neg_lo:[0,0,1] neg_hi:[0,0,1]
	v_pk_fma_f32 v[40:41], v[28:29], v[40:41], v[44:45] op_sel_hi:[0,1,1] neg_lo:[0,0,1] neg_hi:[0,0,1]
	s_waitcnt lgkmcnt(0)
	v_pk_fma_f32 v[30:31], v[28:29], v[48:49], v[30:31] op_sel_hi:[0,1,1] neg_lo:[0,0,1] neg_hi:[0,0,1]
	v_pk_fma_f32 v[28:29], v[28:29], v[50:51], v[54:55] op_sel_hi:[0,1,1] neg_lo:[0,0,1] neg_hi:[0,0,1]
	v_pk_add_f32 v[12:13], v[12:13], v[80:81]
	v_pk_add_f32 v[14:15], v[14:15], v[78:79]
	v_pk_add_f32 v[8:9], v[8:9], v[60:61]
	v_pk_add_f32 v[10:11], v[10:11], v[62:63]
	v_pk_add_f32 v[4:5], v[4:5], v[64:65]
	v_pk_add_f32 v[6:7], v[6:7], v[66:67]
	v_pk_add_f32 v[0:1], v[0:1], v[68:69]
	v_pk_add_f32 v[2:3], v[2:3], v[70:71]
	v_add_u32_e32 v35, 0x100, v35
	v_pk_add_f32 v[14:15], v[14:15], v[18:19]
	v_pk_add_f32 v[12:13], v[12:13], v[16:17]
	v_pk_add_f32 v[10:11], v[10:11], v[22:23]
	v_pk_add_f32 v[8:9], v[8:9], v[20:21]
	v_pk_add_f32 v[6:7], v[6:7], v[40:41]
	v_pk_add_f32 v[4:5], v[4:5], v[38:39]
	v_pk_add_f32 v[2:3], v[2:3], v[28:29]
	v_pk_add_f32 v[0:1], v[0:1], v[30:31]
	v_lshl_add_u64 v[16:17], v[24:25], 0, s[0:1]
	v_lshl_add_u64 v[18:19], v[26:27], 0, s[0:1]
	s_waitcnt vmcnt(8)
	v_mov_b32_e32 v72, v128
	v_mov_b32_e32 v73, v129
	v_mov_b32_e32 v74, v220
	v_mov_b32_e32 v75, v221
	ds_read2_b64 v[28:31], v36 offset1:17
	ds_read_b128 v[38:41], v35
	ds_read_b128 v[42:45], v35 offset:16
	ds_read_b128 v[48:51], v35 offset:32
	ds_read_b128 v[52:55], v35 offset:48
	ds_read_b128 v[56:59], v35 offset:64
	ds_read_b128 v[60:63], v35 offset:80
	ds_read_b128 v[64:67], v35 offset:96
	ds_read_b128 v[68:71], v35 offset:112
	ds_read_b128 v[16:19], v35 offset:128
	ds_read_b128 v[20:23], v35 offset:192
	s_add_u32 s0, s0, 8
	s_addc_u32 s1, s1, 0
	v_add_u32_e32 v36, 0x110, v36
	s_cmpk_eq_i32 s0, 0x100
	v_mov_b32_e32 v76, v72
	v_mov_b32_e32 v77, v74
	s_waitcnt lgkmcnt(10)
	v_mul_f32_e32 v78, v74, v29
	v_mov_b32_e32 v80, v74
	v_mov_b32_e32 v81, v72
	v_mul_f32_e32 v72, v72, v29
	v_pk_fma_f32 v[76:77], v[76:77], v[28:29], v[78:79] op_sel_hi:[1,1,0] neg_lo:[0,0,1] neg_hi:[0,0,1]
	v_pk_fma_f32 v[78:79], v[80:81], v[28:29], v[72:73] op_sel_hi:[1,1,0]
	v_mov_b32_e32 v74, v73
	v_mul_f32_e32 v28, v75, v31
	s_waitcnt lgkmcnt(4)
	v_pk_mul_f32 v[60:61], v[78:79], v[60:61] op_sel_hi:[0,1]
	v_pk_mul_f32 v[62:63], v[78:79], v[62:63] op_sel_hi:[0,1]
	s_waitcnt lgkmcnt(2)
	v_pk_mul_f32 v[68:69], v[78:79], v[68:69] op_sel_hi:[0,1]
	v_pk_mul_f32 v[70:71], v[78:79], v[70:71] op_sel_hi:[0,1]
	v_mov_b32_e32 v72, v75
	v_pk_fma_f32 v[28:29], v[74:75], v[30:31], v[28:29] op_sel_hi:[1,1,0] neg_lo:[0,0,1] neg_hi:[0,0,1]
	v_mul_f32_e32 v74, v73, v31
	v_pk_mul_f32 v[80:81], v[56:57], v[78:79] op_sel_hi:[1,0]
	v_pk_mul_f32 v[82:83], v[58:59], v[78:79] op_sel_hi:[1,0]
	v_pk_mul_f32 v[64:65], v[78:79], v[64:65] op_sel_hi:[0,1]
	v_pk_mul_f32 v[66:67], v[78:79], v[66:67] op_sel_hi:[0,1]
	ds_read_b128 v[56:59], v35 offset:208
	v_pk_fma_f32 v[62:63], v[44:45], v[76:77], v[62:63] op_sel_hi:[1,0,1] neg_lo:[0,0,1] neg_hi:[0,0,1]
	v_pk_fma_f32 v[60:61], v[42:43], v[76:77], v[60:61] op_sel_hi:[1,0,1] neg_lo:[0,0,1] neg_hi:[0,0,1]
	ds_read_b128 v[42:45], v35 offset:224
	v_pk_fma_f32 v[70:71], v[76:77], v[54:55], v[70:71] op_sel_hi:[0,1,1] neg_lo:[0,0,1] neg_hi:[0,0,1]
	v_pk_fma_f32 v[68:69], v[76:77], v[52:53], v[68:69] op_sel_hi:[0,1,1] neg_lo:[0,0,1] neg_hi:[0,0,1]
	ds_read_b128 v[52:55], v35 offset:240
	v_pk_fma_f32 v[30:31], v[72:73], v[30:31], v[74:75] op_sel_hi:[1,1,0]
	ds_read_b128 v[72:75], v35 offset:144
	v_pk_fma_f32 v[78:79], v[40:41], v[76:77], v[82:83] op_sel_hi:[1,0,1] neg_lo:[0,0,1] neg_hi:[0,0,1]
	v_pk_fma_f32 v[80:81], v[38:39], v[76:77], v[80:81] op_sel_hi:[1,0,1] neg_lo:[0,0,1] neg_hi:[0,0,1]
	ds_read_b128 v[38:41], v35 offset:160
	v_pk_fma_f32 v[66:67], v[76:77], v[50:51], v[66:67] op_sel_hi:[0,1,1] neg_lo:[0,0,1] neg_hi:[0,0,1]
	v_pk_fma_f32 v[64:65], v[76:77], v[48:49], v[64:65] op_sel_hi:[0,1,1] neg_lo:[0,0,1] neg_hi:[0,0,1]
	ds_read_b128 v[48:51], v35 offset:176
	s_waitcnt lgkmcnt(6)
	v_pk_mul_f32 v[22:23], v[22:23], v[30:31] op_sel_hi:[1,0]
	v_pk_mul_f32 v[20:21], v[20:21], v[30:31] op_sel_hi:[1,0]
	s_waitcnt lgkmcnt(5)
	v_pk_mul_f32 v[58:59], v[30:31], v[58:59] op_sel_hi:[0,1]
	v_pk_mul_f32 v[56:57], v[30:31], v[56:57] op_sel_hi:[0,1]
	s_waitcnt lgkmcnt(4)
	v_pk_mul_f32 v[44:45], v[30:31], v[44:45] op_sel_hi:[0,1]
	v_pk_mul_f32 v[42:43], v[30:31], v[42:43] op_sel_hi:[0,1]
	s_waitcnt lgkmcnt(3)
	v_pk_mul_f32 v[54:55], v[30:31], v[54:55] op_sel_hi:[0,1]
	v_pk_mul_f32 v[30:31], v[30:31], v[52:53] op_sel_hi:[0,1]
	v_pk_fma_f32 v[16:17], v[16:17], v[28:29], v[20:21] op_sel_hi:[1,0,1] neg_lo:[0,0,1] neg_hi:[0,0,1]
	v_pk_fma_f32 v[18:19], v[18:19], v[28:29], v[22:23] op_sel_hi:[1,0,1] neg_lo:[0,0,1] neg_hi:[0,0,1]
	s_waitcnt lgkmcnt(2)
	v_pk_fma_f32 v[20:21], v[72:73], v[28:29], v[56:57] op_sel_hi:[1,0,1] neg_lo:[0,0,1] neg_hi:[0,0,1]
	v_pk_fma_f32 v[22:23], v[74:75], v[28:29], v[58:59] op_sel_hi:[1,0,1] neg_lo:[0,0,1] neg_hi:[0,0,1]
	s_waitcnt lgkmcnt(1)
	v_pk_fma_f32 v[38:39], v[28:29], v[38:39], v[42:43] op_sel_hi:[0,1,1] neg_lo:[0,0,1] neg_hi:[0,0,1]
	v_pk_fma_f32 v[40:41], v[28:29], v[40:41], v[44:45] op_sel_hi:[0,1,1] neg_lo:[0,0,1] neg_hi:[0,0,1]
	s_waitcnt lgkmcnt(0)
	v_pk_fma_f32 v[30:31], v[28:29], v[48:49], v[30:31] op_sel_hi:[0,1,1] neg_lo:[0,0,1] neg_hi:[0,0,1]
	v_pk_fma_f32 v[28:29], v[28:29], v[50:51], v[54:55] op_sel_hi:[0,1,1] neg_lo:[0,0,1] neg_hi:[0,0,1]
	v_pk_add_f32 v[12:13], v[12:13], v[80:81]
	v_pk_add_f32 v[14:15], v[14:15], v[78:79]
	v_pk_add_f32 v[8:9], v[8:9], v[60:61]
	v_pk_add_f32 v[10:11], v[10:11], v[62:63]
	v_pk_add_f32 v[4:5], v[4:5], v[64:65]
	v_pk_add_f32 v[6:7], v[6:7], v[66:67]
	v_pk_add_f32 v[0:1], v[0:1], v[68:69]
	v_pk_add_f32 v[2:3], v[2:3], v[70:71]
	v_add_u32_e32 v35, 0x100, v35
	v_pk_add_f32 v[14:15], v[14:15], v[18:19]
	v_pk_add_f32 v[12:13], v[12:13], v[16:17]
	v_pk_add_f32 v[10:11], v[10:11], v[22:23]
	v_pk_add_f32 v[8:9], v[8:9], v[20:21]
	v_pk_add_f32 v[6:7], v[6:7], v[40:41]
	v_pk_add_f32 v[4:5], v[4:5], v[38:39]
	v_pk_add_f32 v[2:3], v[2:3], v[28:29]
	v_pk_add_f32 v[0:1], v[0:1], v[30:31]
	v_lshl_add_u64 v[16:17], v[24:25], 0, s[0:1]
	v_lshl_add_u64 v[18:19], v[26:27], 0, s[0:1]
	s_waitcnt vmcnt(8)
	v_mov_b32_e32 v72, v130
	v_mov_b32_e32 v73, v131
	v_mov_b32_e32 v74, v222
	v_mov_b32_e32 v75, v223
	ds_read2_b64 v[28:31], v36 offset1:17
	ds_read_b128 v[38:41], v35
	ds_read_b128 v[42:45], v35 offset:16
	ds_read_b128 v[48:51], v35 offset:32
	ds_read_b128 v[52:55], v35 offset:48
	ds_read_b128 v[56:59], v35 offset:64
	ds_read_b128 v[60:63], v35 offset:80
	ds_read_b128 v[64:67], v35 offset:96
	ds_read_b128 v[68:71], v35 offset:112
	ds_read_b128 v[16:19], v35 offset:128
	ds_read_b128 v[20:23], v35 offset:192
	s_add_u32 s0, s0, 8
	s_addc_u32 s1, s1, 0
	v_add_u32_e32 v36, 0x110, v36
	s_cmpk_eq_i32 s0, 0x100
	v_mov_b32_e32 v76, v72
	v_mov_b32_e32 v77, v74
	s_waitcnt lgkmcnt(10)
	v_mul_f32_e32 v78, v74, v29
	v_mov_b32_e32 v80, v74
	v_mov_b32_e32 v81, v72
	v_mul_f32_e32 v72, v72, v29
	v_pk_fma_f32 v[76:77], v[76:77], v[28:29], v[78:79] op_sel_hi:[1,1,0] neg_lo:[0,0,1] neg_hi:[0,0,1]
	v_pk_fma_f32 v[78:79], v[80:81], v[28:29], v[72:73] op_sel_hi:[1,1,0]
	v_mov_b32_e32 v74, v73
	v_mul_f32_e32 v28, v75, v31
	s_waitcnt lgkmcnt(4)
	v_pk_mul_f32 v[60:61], v[78:79], v[60:61] op_sel_hi:[0,1]
	v_pk_mul_f32 v[62:63], v[78:79], v[62:63] op_sel_hi:[0,1]
	s_waitcnt lgkmcnt(2)
	v_pk_mul_f32 v[68:69], v[78:79], v[68:69] op_sel_hi:[0,1]
	v_pk_mul_f32 v[70:71], v[78:79], v[70:71] op_sel_hi:[0,1]
	v_mov_b32_e32 v72, v75
	v_pk_fma_f32 v[28:29], v[74:75], v[30:31], v[28:29] op_sel_hi:[1,1,0] neg_lo:[0,0,1] neg_hi:[0,0,1]
	v_mul_f32_e32 v74, v73, v31
	v_pk_mul_f32 v[80:81], v[56:57], v[78:79] op_sel_hi:[1,0]
	v_pk_mul_f32 v[82:83], v[58:59], v[78:79] op_sel_hi:[1,0]
	v_pk_mul_f32 v[64:65], v[78:79], v[64:65] op_sel_hi:[0,1]
	v_pk_mul_f32 v[66:67], v[78:79], v[66:67] op_sel_hi:[0,1]
	ds_read_b128 v[56:59], v35 offset:208
	v_pk_fma_f32 v[62:63], v[44:45], v[76:77], v[62:63] op_sel_hi:[1,0,1] neg_lo:[0,0,1] neg_hi:[0,0,1]
	v_pk_fma_f32 v[60:61], v[42:43], v[76:77], v[60:61] op_sel_hi:[1,0,1] neg_lo:[0,0,1] neg_hi:[0,0,1]
	ds_read_b128 v[42:45], v35 offset:224
	v_pk_fma_f32 v[70:71], v[76:77], v[54:55], v[70:71] op_sel_hi:[0,1,1] neg_lo:[0,0,1] neg_hi:[0,0,1]
	v_pk_fma_f32 v[68:69], v[76:77], v[52:53], v[68:69] op_sel_hi:[0,1,1] neg_lo:[0,0,1] neg_hi:[0,0,1]
	ds_read_b128 v[52:55], v35 offset:240
	v_pk_fma_f32 v[30:31], v[72:73], v[30:31], v[74:75] op_sel_hi:[1,1,0]
	ds_read_b128 v[72:75], v35 offset:144
	v_pk_fma_f32 v[78:79], v[40:41], v[76:77], v[82:83] op_sel_hi:[1,0,1] neg_lo:[0,0,1] neg_hi:[0,0,1]
	v_pk_fma_f32 v[80:81], v[38:39], v[76:77], v[80:81] op_sel_hi:[1,0,1] neg_lo:[0,0,1] neg_hi:[0,0,1]
	ds_read_b128 v[38:41], v35 offset:160
	v_pk_fma_f32 v[66:67], v[76:77], v[50:51], v[66:67] op_sel_hi:[0,1,1] neg_lo:[0,0,1] neg_hi:[0,0,1]
	v_pk_fma_f32 v[64:65], v[76:77], v[48:49], v[64:65] op_sel_hi:[0,1,1] neg_lo:[0,0,1] neg_hi:[0,0,1]
	ds_read_b128 v[48:51], v35 offset:176
	s_waitcnt lgkmcnt(6)
	v_pk_mul_f32 v[22:23], v[22:23], v[30:31] op_sel_hi:[1,0]
	v_pk_mul_f32 v[20:21], v[20:21], v[30:31] op_sel_hi:[1,0]
	s_waitcnt lgkmcnt(5)
	v_pk_mul_f32 v[58:59], v[30:31], v[58:59] op_sel_hi:[0,1]
	v_pk_mul_f32 v[56:57], v[30:31], v[56:57] op_sel_hi:[0,1]
	s_waitcnt lgkmcnt(4)
	v_pk_mul_f32 v[44:45], v[30:31], v[44:45] op_sel_hi:[0,1]
	v_pk_mul_f32 v[42:43], v[30:31], v[42:43] op_sel_hi:[0,1]
	s_waitcnt lgkmcnt(3)
	v_pk_mul_f32 v[54:55], v[30:31], v[54:55] op_sel_hi:[0,1]
	v_pk_mul_f32 v[30:31], v[30:31], v[52:53] op_sel_hi:[0,1]
	v_pk_fma_f32 v[16:17], v[16:17], v[28:29], v[20:21] op_sel_hi:[1,0,1] neg_lo:[0,0,1] neg_hi:[0,0,1]
	v_pk_fma_f32 v[18:19], v[18:19], v[28:29], v[22:23] op_sel_hi:[1,0,1] neg_lo:[0,0,1] neg_hi:[0,0,1]
	s_waitcnt lgkmcnt(2)
	v_pk_fma_f32 v[20:21], v[72:73], v[28:29], v[56:57] op_sel_hi:[1,0,1] neg_lo:[0,0,1] neg_hi:[0,0,1]
	v_pk_fma_f32 v[22:23], v[74:75], v[28:29], v[58:59] op_sel_hi:[1,0,1] neg_lo:[0,0,1] neg_hi:[0,0,1]
	s_waitcnt lgkmcnt(1)
	v_pk_fma_f32 v[38:39], v[28:29], v[38:39], v[42:43] op_sel_hi:[0,1,1] neg_lo:[0,0,1] neg_hi:[0,0,1]
	v_pk_fma_f32 v[40:41], v[28:29], v[40:41], v[44:45] op_sel_hi:[0,1,1] neg_lo:[0,0,1] neg_hi:[0,0,1]
	s_waitcnt lgkmcnt(0)
	v_pk_fma_f32 v[30:31], v[28:29], v[48:49], v[30:31] op_sel_hi:[0,1,1] neg_lo:[0,0,1] neg_hi:[0,0,1]
	v_pk_fma_f32 v[28:29], v[28:29], v[50:51], v[54:55] op_sel_hi:[0,1,1] neg_lo:[0,0,1] neg_hi:[0,0,1]
	v_pk_add_f32 v[12:13], v[12:13], v[80:81]
	v_pk_add_f32 v[14:15], v[14:15], v[78:79]
	v_pk_add_f32 v[8:9], v[8:9], v[60:61]
	v_pk_add_f32 v[10:11], v[10:11], v[62:63]
	v_pk_add_f32 v[4:5], v[4:5], v[64:65]
	v_pk_add_f32 v[6:7], v[6:7], v[66:67]
	v_pk_add_f32 v[0:1], v[0:1], v[68:69]
	v_pk_add_f32 v[2:3], v[2:3], v[70:71]
	v_add_u32_e32 v35, 0x100, v35
	v_pk_add_f32 v[14:15], v[14:15], v[18:19]
	v_pk_add_f32 v[12:13], v[12:13], v[16:17]
	v_pk_add_f32 v[10:11], v[10:11], v[22:23]
	v_pk_add_f32 v[8:9], v[8:9], v[20:21]
	v_pk_add_f32 v[6:7], v[6:7], v[40:41]
	v_pk_add_f32 v[4:5], v[4:5], v[38:39]
	v_pk_add_f32 v[2:3], v[2:3], v[28:29]
	v_pk_add_f32 v[0:1], v[0:1], v[30:31]
	v_lshl_add_u64 v[16:17], v[24:25], 0, s[0:1]
	v_lshl_add_u64 v[18:19], v[26:27], 0, s[0:1]
	s_waitcnt vmcnt(6)
	v_mov_b32_e32 v72, v132
	v_mov_b32_e32 v73, v133
	v_mov_b32_e32 v74, v224
	v_mov_b32_e32 v75, v225
	ds_read2_b64 v[28:31], v36 offset1:17
	ds_read_b128 v[38:41], v35
	ds_read_b128 v[42:45], v35 offset:16
	ds_read_b128 v[48:51], v35 offset:32
	ds_read_b128 v[52:55], v35 offset:48
	ds_read_b128 v[56:59], v35 offset:64
	ds_read_b128 v[60:63], v35 offset:80
	ds_read_b128 v[64:67], v35 offset:96
	ds_read_b128 v[68:71], v35 offset:112
	ds_read_b128 v[16:19], v35 offset:128
	ds_read_b128 v[20:23], v35 offset:192
	s_add_u32 s0, s0, 8
	s_addc_u32 s1, s1, 0
	v_add_u32_e32 v36, 0x110, v36
	s_cmpk_eq_i32 s0, 0x100
	v_mov_b32_e32 v76, v72
	v_mov_b32_e32 v77, v74
	s_waitcnt lgkmcnt(10)
	v_mul_f32_e32 v78, v74, v29
	v_mov_b32_e32 v80, v74
	v_mov_b32_e32 v81, v72
	v_mul_f32_e32 v72, v72, v29
	v_pk_fma_f32 v[76:77], v[76:77], v[28:29], v[78:79] op_sel_hi:[1,1,0] neg_lo:[0,0,1] neg_hi:[0,0,1]
	v_pk_fma_f32 v[78:79], v[80:81], v[28:29], v[72:73] op_sel_hi:[1,1,0]
	v_mov_b32_e32 v74, v73
	v_mul_f32_e32 v28, v75, v31
	s_waitcnt lgkmcnt(4)
	v_pk_mul_f32 v[60:61], v[78:79], v[60:61] op_sel_hi:[0,1]
	v_pk_mul_f32 v[62:63], v[78:79], v[62:63] op_sel_hi:[0,1]
	s_waitcnt lgkmcnt(2)
	v_pk_mul_f32 v[68:69], v[78:79], v[68:69] op_sel_hi:[0,1]
	v_pk_mul_f32 v[70:71], v[78:79], v[70:71] op_sel_hi:[0,1]
	v_mov_b32_e32 v72, v75
	v_pk_fma_f32 v[28:29], v[74:75], v[30:31], v[28:29] op_sel_hi:[1,1,0] neg_lo:[0,0,1] neg_hi:[0,0,1]
	v_mul_f32_e32 v74, v73, v31
	v_pk_mul_f32 v[80:81], v[56:57], v[78:79] op_sel_hi:[1,0]
	v_pk_mul_f32 v[82:83], v[58:59], v[78:79] op_sel_hi:[1,0]
	v_pk_mul_f32 v[64:65], v[78:79], v[64:65] op_sel_hi:[0,1]
	v_pk_mul_f32 v[66:67], v[78:79], v[66:67] op_sel_hi:[0,1]
	ds_read_b128 v[56:59], v35 offset:208
	v_pk_fma_f32 v[62:63], v[44:45], v[76:77], v[62:63] op_sel_hi:[1,0,1] neg_lo:[0,0,1] neg_hi:[0,0,1]
	v_pk_fma_f32 v[60:61], v[42:43], v[76:77], v[60:61] op_sel_hi:[1,0,1] neg_lo:[0,0,1] neg_hi:[0,0,1]
	ds_read_b128 v[42:45], v35 offset:224
	v_pk_fma_f32 v[70:71], v[76:77], v[54:55], v[70:71] op_sel_hi:[0,1,1] neg_lo:[0,0,1] neg_hi:[0,0,1]
	v_pk_fma_f32 v[68:69], v[76:77], v[52:53], v[68:69] op_sel_hi:[0,1,1] neg_lo:[0,0,1] neg_hi:[0,0,1]
	ds_read_b128 v[52:55], v35 offset:240
	v_pk_fma_f32 v[30:31], v[72:73], v[30:31], v[74:75] op_sel_hi:[1,1,0]
	ds_read_b128 v[72:75], v35 offset:144
	v_pk_fma_f32 v[78:79], v[40:41], v[76:77], v[82:83] op_sel_hi:[1,0,1] neg_lo:[0,0,1] neg_hi:[0,0,1]
	v_pk_fma_f32 v[80:81], v[38:39], v[76:77], v[80:81] op_sel_hi:[1,0,1] neg_lo:[0,0,1] neg_hi:[0,0,1]
	ds_read_b128 v[38:41], v35 offset:160
	v_pk_fma_f32 v[66:67], v[76:77], v[50:51], v[66:67] op_sel_hi:[0,1,1] neg_lo:[0,0,1] neg_hi:[0,0,1]
	v_pk_fma_f32 v[64:65], v[76:77], v[48:49], v[64:65] op_sel_hi:[0,1,1] neg_lo:[0,0,1] neg_hi:[0,0,1]
	ds_read_b128 v[48:51], v35 offset:176
	s_waitcnt lgkmcnt(6)
	v_pk_mul_f32 v[22:23], v[22:23], v[30:31] op_sel_hi:[1,0]
	v_pk_mul_f32 v[20:21], v[20:21], v[30:31] op_sel_hi:[1,0]
	s_waitcnt lgkmcnt(5)
	v_pk_mul_f32 v[58:59], v[30:31], v[58:59] op_sel_hi:[0,1]
	v_pk_mul_f32 v[56:57], v[30:31], v[56:57] op_sel_hi:[0,1]
	s_waitcnt lgkmcnt(4)
	v_pk_mul_f32 v[44:45], v[30:31], v[44:45] op_sel_hi:[0,1]
	v_pk_mul_f32 v[42:43], v[30:31], v[42:43] op_sel_hi:[0,1]
	s_waitcnt lgkmcnt(3)
	v_pk_mul_f32 v[54:55], v[30:31], v[54:55] op_sel_hi:[0,1]
	v_pk_mul_f32 v[30:31], v[30:31], v[52:53] op_sel_hi:[0,1]
	v_pk_fma_f32 v[16:17], v[16:17], v[28:29], v[20:21] op_sel_hi:[1,0,1] neg_lo:[0,0,1] neg_hi:[0,0,1]
	v_pk_fma_f32 v[18:19], v[18:19], v[28:29], v[22:23] op_sel_hi:[1,0,1] neg_lo:[0,0,1] neg_hi:[0,0,1]
	s_waitcnt lgkmcnt(2)
	v_pk_fma_f32 v[20:21], v[72:73], v[28:29], v[56:57] op_sel_hi:[1,0,1] neg_lo:[0,0,1] neg_hi:[0,0,1]
	v_pk_fma_f32 v[22:23], v[74:75], v[28:29], v[58:59] op_sel_hi:[1,0,1] neg_lo:[0,0,1] neg_hi:[0,0,1]
	s_waitcnt lgkmcnt(1)
	v_pk_fma_f32 v[38:39], v[28:29], v[38:39], v[42:43] op_sel_hi:[0,1,1] neg_lo:[0,0,1] neg_hi:[0,0,1]
	v_pk_fma_f32 v[40:41], v[28:29], v[40:41], v[44:45] op_sel_hi:[0,1,1] neg_lo:[0,0,1] neg_hi:[0,0,1]
	s_waitcnt lgkmcnt(0)
	v_pk_fma_f32 v[30:31], v[28:29], v[48:49], v[30:31] op_sel_hi:[0,1,1] neg_lo:[0,0,1] neg_hi:[0,0,1]
	v_pk_fma_f32 v[28:29], v[28:29], v[50:51], v[54:55] op_sel_hi:[0,1,1] neg_lo:[0,0,1] neg_hi:[0,0,1]
	v_pk_add_f32 v[12:13], v[12:13], v[80:81]
	v_pk_add_f32 v[14:15], v[14:15], v[78:79]
	v_pk_add_f32 v[8:9], v[8:9], v[60:61]
	v_pk_add_f32 v[10:11], v[10:11], v[62:63]
	v_pk_add_f32 v[4:5], v[4:5], v[64:65]
	v_pk_add_f32 v[6:7], v[6:7], v[66:67]
	v_pk_add_f32 v[0:1], v[0:1], v[68:69]
	v_pk_add_f32 v[2:3], v[2:3], v[70:71]
	v_add_u32_e32 v35, 0x100, v35
	v_pk_add_f32 v[14:15], v[14:15], v[18:19]
	v_pk_add_f32 v[12:13], v[12:13], v[16:17]
	v_pk_add_f32 v[10:11], v[10:11], v[22:23]
	v_pk_add_f32 v[8:9], v[8:9], v[20:21]
	v_pk_add_f32 v[6:7], v[6:7], v[40:41]
	v_pk_add_f32 v[4:5], v[4:5], v[38:39]
	v_pk_add_f32 v[2:3], v[2:3], v[28:29]
	v_pk_add_f32 v[0:1], v[0:1], v[30:31]
	v_lshl_add_u64 v[16:17], v[24:25], 0, s[0:1]
	v_lshl_add_u64 v[18:19], v[26:27], 0, s[0:1]
	s_waitcnt vmcnt(6)
	v_mov_b32_e32 v72, v134
	v_mov_b32_e32 v73, v135
	v_mov_b32_e32 v74, v226
	v_mov_b32_e32 v75, v227
	ds_read2_b64 v[28:31], v36 offset1:17
	ds_read_b128 v[38:41], v35
	ds_read_b128 v[42:45], v35 offset:16
	ds_read_b128 v[48:51], v35 offset:32
	ds_read_b128 v[52:55], v35 offset:48
	ds_read_b128 v[56:59], v35 offset:64
	ds_read_b128 v[60:63], v35 offset:80
	ds_read_b128 v[64:67], v35 offset:96
	ds_read_b128 v[68:71], v35 offset:112
	ds_read_b128 v[16:19], v35 offset:128
	ds_read_b128 v[20:23], v35 offset:192
	s_add_u32 s0, s0, 8
	s_addc_u32 s1, s1, 0
	v_add_u32_e32 v36, 0x110, v36
	s_cmpk_eq_i32 s0, 0x100
	v_mov_b32_e32 v76, v72
	v_mov_b32_e32 v77, v74
	s_waitcnt lgkmcnt(10)
	v_mul_f32_e32 v78, v74, v29
	v_mov_b32_e32 v80, v74
	v_mov_b32_e32 v81, v72
	v_mul_f32_e32 v72, v72, v29
	v_pk_fma_f32 v[76:77], v[76:77], v[28:29], v[78:79] op_sel_hi:[1,1,0] neg_lo:[0,0,1] neg_hi:[0,0,1]
	v_pk_fma_f32 v[78:79], v[80:81], v[28:29], v[72:73] op_sel_hi:[1,1,0]
	v_mov_b32_e32 v74, v73
	v_mul_f32_e32 v28, v75, v31
	s_waitcnt lgkmcnt(4)
	v_pk_mul_f32 v[60:61], v[78:79], v[60:61] op_sel_hi:[0,1]
	v_pk_mul_f32 v[62:63], v[78:79], v[62:63] op_sel_hi:[0,1]
	s_waitcnt lgkmcnt(2)
	v_pk_mul_f32 v[68:69], v[78:79], v[68:69] op_sel_hi:[0,1]
	v_pk_mul_f32 v[70:71], v[78:79], v[70:71] op_sel_hi:[0,1]
	v_mov_b32_e32 v72, v75
	v_pk_fma_f32 v[28:29], v[74:75], v[30:31], v[28:29] op_sel_hi:[1,1,0] neg_lo:[0,0,1] neg_hi:[0,0,1]
	v_mul_f32_e32 v74, v73, v31
	v_pk_mul_f32 v[80:81], v[56:57], v[78:79] op_sel_hi:[1,0]
	v_pk_mul_f32 v[82:83], v[58:59], v[78:79] op_sel_hi:[1,0]
	v_pk_mul_f32 v[64:65], v[78:79], v[64:65] op_sel_hi:[0,1]
	v_pk_mul_f32 v[66:67], v[78:79], v[66:67] op_sel_hi:[0,1]
	ds_read_b128 v[56:59], v35 offset:208
	v_pk_fma_f32 v[62:63], v[44:45], v[76:77], v[62:63] op_sel_hi:[1,0,1] neg_lo:[0,0,1] neg_hi:[0,0,1]
	v_pk_fma_f32 v[60:61], v[42:43], v[76:77], v[60:61] op_sel_hi:[1,0,1] neg_lo:[0,0,1] neg_hi:[0,0,1]
	ds_read_b128 v[42:45], v35 offset:224
	v_pk_fma_f32 v[70:71], v[76:77], v[54:55], v[70:71] op_sel_hi:[0,1,1] neg_lo:[0,0,1] neg_hi:[0,0,1]
	v_pk_fma_f32 v[68:69], v[76:77], v[52:53], v[68:69] op_sel_hi:[0,1,1] neg_lo:[0,0,1] neg_hi:[0,0,1]
	ds_read_b128 v[52:55], v35 offset:240
	v_pk_fma_f32 v[30:31], v[72:73], v[30:31], v[74:75] op_sel_hi:[1,1,0]
	ds_read_b128 v[72:75], v35 offset:144
	v_pk_fma_f32 v[78:79], v[40:41], v[76:77], v[82:83] op_sel_hi:[1,0,1] neg_lo:[0,0,1] neg_hi:[0,0,1]
	v_pk_fma_f32 v[80:81], v[38:39], v[76:77], v[80:81] op_sel_hi:[1,0,1] neg_lo:[0,0,1] neg_hi:[0,0,1]
	ds_read_b128 v[38:41], v35 offset:160
	v_pk_fma_f32 v[66:67], v[76:77], v[50:51], v[66:67] op_sel_hi:[0,1,1] neg_lo:[0,0,1] neg_hi:[0,0,1]
	v_pk_fma_f32 v[64:65], v[76:77], v[48:49], v[64:65] op_sel_hi:[0,1,1] neg_lo:[0,0,1] neg_hi:[0,0,1]
	ds_read_b128 v[48:51], v35 offset:176
	s_waitcnt lgkmcnt(6)
	v_pk_mul_f32 v[22:23], v[22:23], v[30:31] op_sel_hi:[1,0]
	v_pk_mul_f32 v[20:21], v[20:21], v[30:31] op_sel_hi:[1,0]
	s_waitcnt lgkmcnt(5)
	v_pk_mul_f32 v[58:59], v[30:31], v[58:59] op_sel_hi:[0,1]
	v_pk_mul_f32 v[56:57], v[30:31], v[56:57] op_sel_hi:[0,1]
	s_waitcnt lgkmcnt(4)
	v_pk_mul_f32 v[44:45], v[30:31], v[44:45] op_sel_hi:[0,1]
	v_pk_mul_f32 v[42:43], v[30:31], v[42:43] op_sel_hi:[0,1]
	s_waitcnt lgkmcnt(3)
	v_pk_mul_f32 v[54:55], v[30:31], v[54:55] op_sel_hi:[0,1]
	v_pk_mul_f32 v[30:31], v[30:31], v[52:53] op_sel_hi:[0,1]
	v_pk_fma_f32 v[16:17], v[16:17], v[28:29], v[20:21] op_sel_hi:[1,0,1] neg_lo:[0,0,1] neg_hi:[0,0,1]
	v_pk_fma_f32 v[18:19], v[18:19], v[28:29], v[22:23] op_sel_hi:[1,0,1] neg_lo:[0,0,1] neg_hi:[0,0,1]
	s_waitcnt lgkmcnt(2)
	v_pk_fma_f32 v[20:21], v[72:73], v[28:29], v[56:57] op_sel_hi:[1,0,1] neg_lo:[0,0,1] neg_hi:[0,0,1]
	v_pk_fma_f32 v[22:23], v[74:75], v[28:29], v[58:59] op_sel_hi:[1,0,1] neg_lo:[0,0,1] neg_hi:[0,0,1]
	s_waitcnt lgkmcnt(1)
	v_pk_fma_f32 v[38:39], v[28:29], v[38:39], v[42:43] op_sel_hi:[0,1,1] neg_lo:[0,0,1] neg_hi:[0,0,1]
	v_pk_fma_f32 v[40:41], v[28:29], v[40:41], v[44:45] op_sel_hi:[0,1,1] neg_lo:[0,0,1] neg_hi:[0,0,1]
	s_waitcnt lgkmcnt(0)
	v_pk_fma_f32 v[30:31], v[28:29], v[48:49], v[30:31] op_sel_hi:[0,1,1] neg_lo:[0,0,1] neg_hi:[0,0,1]
	v_pk_fma_f32 v[28:29], v[28:29], v[50:51], v[54:55] op_sel_hi:[0,1,1] neg_lo:[0,0,1] neg_hi:[0,0,1]
	v_pk_add_f32 v[12:13], v[12:13], v[80:81]
	v_pk_add_f32 v[14:15], v[14:15], v[78:79]
	v_pk_add_f32 v[8:9], v[8:9], v[60:61]
	v_pk_add_f32 v[10:11], v[10:11], v[62:63]
	v_pk_add_f32 v[4:5], v[4:5], v[64:65]
	v_pk_add_f32 v[6:7], v[6:7], v[66:67]
	v_pk_add_f32 v[0:1], v[0:1], v[68:69]
	v_pk_add_f32 v[2:3], v[2:3], v[70:71]
	v_add_u32_e32 v35, 0x100, v35
	v_pk_add_f32 v[14:15], v[14:15], v[18:19]
	v_pk_add_f32 v[12:13], v[12:13], v[16:17]
	v_pk_add_f32 v[10:11], v[10:11], v[22:23]
	v_pk_add_f32 v[8:9], v[8:9], v[20:21]
	v_pk_add_f32 v[6:7], v[6:7], v[40:41]
	v_pk_add_f32 v[4:5], v[4:5], v[38:39]
	v_pk_add_f32 v[2:3], v[2:3], v[28:29]
	v_pk_add_f32 v[0:1], v[0:1], v[30:31]
	v_lshl_add_u64 v[16:17], v[24:25], 0, s[0:1]
	v_lshl_add_u64 v[18:19], v[26:27], 0, s[0:1]
	s_waitcnt vmcnt(4)
	v_mov_b32_e32 v72, v136
	v_mov_b32_e32 v73, v137
	v_mov_b32_e32 v74, v228
	v_mov_b32_e32 v75, v229
	ds_read2_b64 v[28:31], v36 offset1:17
	ds_read_b128 v[38:41], v35
	ds_read_b128 v[42:45], v35 offset:16
	ds_read_b128 v[48:51], v35 offset:32
	ds_read_b128 v[52:55], v35 offset:48
	ds_read_b128 v[56:59], v35 offset:64
	ds_read_b128 v[60:63], v35 offset:80
	ds_read_b128 v[64:67], v35 offset:96
	ds_read_b128 v[68:71], v35 offset:112
	ds_read_b128 v[16:19], v35 offset:128
	ds_read_b128 v[20:23], v35 offset:192
	s_add_u32 s0, s0, 8
	s_addc_u32 s1, s1, 0
	v_add_u32_e32 v36, 0x110, v36
	s_cmpk_eq_i32 s0, 0x100
	v_mov_b32_e32 v76, v72
	v_mov_b32_e32 v77, v74
	s_waitcnt lgkmcnt(10)
	v_mul_f32_e32 v78, v74, v29
	v_mov_b32_e32 v80, v74
	v_mov_b32_e32 v81, v72
	v_mul_f32_e32 v72, v72, v29
	v_pk_fma_f32 v[76:77], v[76:77], v[28:29], v[78:79] op_sel_hi:[1,1,0] neg_lo:[0,0,1] neg_hi:[0,0,1]
	v_pk_fma_f32 v[78:79], v[80:81], v[28:29], v[72:73] op_sel_hi:[1,1,0]
	v_mov_b32_e32 v74, v73
	v_mul_f32_e32 v28, v75, v31
	s_waitcnt lgkmcnt(4)
	v_pk_mul_f32 v[60:61], v[78:79], v[60:61] op_sel_hi:[0,1]
	v_pk_mul_f32 v[62:63], v[78:79], v[62:63] op_sel_hi:[0,1]
	s_waitcnt lgkmcnt(2)
	v_pk_mul_f32 v[68:69], v[78:79], v[68:69] op_sel_hi:[0,1]
	v_pk_mul_f32 v[70:71], v[78:79], v[70:71] op_sel_hi:[0,1]
	v_mov_b32_e32 v72, v75
	v_pk_fma_f32 v[28:29], v[74:75], v[30:31], v[28:29] op_sel_hi:[1,1,0] neg_lo:[0,0,1] neg_hi:[0,0,1]
	v_mul_f32_e32 v74, v73, v31
	v_pk_mul_f32 v[80:81], v[56:57], v[78:79] op_sel_hi:[1,0]
	v_pk_mul_f32 v[82:83], v[58:59], v[78:79] op_sel_hi:[1,0]
	v_pk_mul_f32 v[64:65], v[78:79], v[64:65] op_sel_hi:[0,1]
	v_pk_mul_f32 v[66:67], v[78:79], v[66:67] op_sel_hi:[0,1]
	ds_read_b128 v[56:59], v35 offset:208
	v_pk_fma_f32 v[62:63], v[44:45], v[76:77], v[62:63] op_sel_hi:[1,0,1] neg_lo:[0,0,1] neg_hi:[0,0,1]
	v_pk_fma_f32 v[60:61], v[42:43], v[76:77], v[60:61] op_sel_hi:[1,0,1] neg_lo:[0,0,1] neg_hi:[0,0,1]
	ds_read_b128 v[42:45], v35 offset:224
	v_pk_fma_f32 v[70:71], v[76:77], v[54:55], v[70:71] op_sel_hi:[0,1,1] neg_lo:[0,0,1] neg_hi:[0,0,1]
	v_pk_fma_f32 v[68:69], v[76:77], v[52:53], v[68:69] op_sel_hi:[0,1,1] neg_lo:[0,0,1] neg_hi:[0,0,1]
	ds_read_b128 v[52:55], v35 offset:240
	v_pk_fma_f32 v[30:31], v[72:73], v[30:31], v[74:75] op_sel_hi:[1,1,0]
	ds_read_b128 v[72:75], v35 offset:144
	v_pk_fma_f32 v[78:79], v[40:41], v[76:77], v[82:83] op_sel_hi:[1,0,1] neg_lo:[0,0,1] neg_hi:[0,0,1]
	v_pk_fma_f32 v[80:81], v[38:39], v[76:77], v[80:81] op_sel_hi:[1,0,1] neg_lo:[0,0,1] neg_hi:[0,0,1]
	ds_read_b128 v[38:41], v35 offset:160
	v_pk_fma_f32 v[66:67], v[76:77], v[50:51], v[66:67] op_sel_hi:[0,1,1] neg_lo:[0,0,1] neg_hi:[0,0,1]
	v_pk_fma_f32 v[64:65], v[76:77], v[48:49], v[64:65] op_sel_hi:[0,1,1] neg_lo:[0,0,1] neg_hi:[0,0,1]
	ds_read_b128 v[48:51], v35 offset:176
	s_waitcnt lgkmcnt(6)
	v_pk_mul_f32 v[22:23], v[22:23], v[30:31] op_sel_hi:[1,0]
	v_pk_mul_f32 v[20:21], v[20:21], v[30:31] op_sel_hi:[1,0]
	s_waitcnt lgkmcnt(5)
	v_pk_mul_f32 v[58:59], v[30:31], v[58:59] op_sel_hi:[0,1]
	v_pk_mul_f32 v[56:57], v[30:31], v[56:57] op_sel_hi:[0,1]
	s_waitcnt lgkmcnt(4)
	v_pk_mul_f32 v[44:45], v[30:31], v[44:45] op_sel_hi:[0,1]
	v_pk_mul_f32 v[42:43], v[30:31], v[42:43] op_sel_hi:[0,1]
	s_waitcnt lgkmcnt(3)
	v_pk_mul_f32 v[54:55], v[30:31], v[54:55] op_sel_hi:[0,1]
	v_pk_mul_f32 v[30:31], v[30:31], v[52:53] op_sel_hi:[0,1]
	v_pk_fma_f32 v[16:17], v[16:17], v[28:29], v[20:21] op_sel_hi:[1,0,1] neg_lo:[0,0,1] neg_hi:[0,0,1]
	v_pk_fma_f32 v[18:19], v[18:19], v[28:29], v[22:23] op_sel_hi:[1,0,1] neg_lo:[0,0,1] neg_hi:[0,0,1]
	s_waitcnt lgkmcnt(2)
	v_pk_fma_f32 v[20:21], v[72:73], v[28:29], v[56:57] op_sel_hi:[1,0,1] neg_lo:[0,0,1] neg_hi:[0,0,1]
	v_pk_fma_f32 v[22:23], v[74:75], v[28:29], v[58:59] op_sel_hi:[1,0,1] neg_lo:[0,0,1] neg_hi:[0,0,1]
	s_waitcnt lgkmcnt(1)
	v_pk_fma_f32 v[38:39], v[28:29], v[38:39], v[42:43] op_sel_hi:[0,1,1] neg_lo:[0,0,1] neg_hi:[0,0,1]
	v_pk_fma_f32 v[40:41], v[28:29], v[40:41], v[44:45] op_sel_hi:[0,1,1] neg_lo:[0,0,1] neg_hi:[0,0,1]
	s_waitcnt lgkmcnt(0)
	v_pk_fma_f32 v[30:31], v[28:29], v[48:49], v[30:31] op_sel_hi:[0,1,1] neg_lo:[0,0,1] neg_hi:[0,0,1]
	v_pk_fma_f32 v[28:29], v[28:29], v[50:51], v[54:55] op_sel_hi:[0,1,1] neg_lo:[0,0,1] neg_hi:[0,0,1]
	v_pk_add_f32 v[12:13], v[12:13], v[80:81]
	v_pk_add_f32 v[14:15], v[14:15], v[78:79]
	v_pk_add_f32 v[8:9], v[8:9], v[60:61]
	v_pk_add_f32 v[10:11], v[10:11], v[62:63]
	v_pk_add_f32 v[4:5], v[4:5], v[64:65]
	v_pk_add_f32 v[6:7], v[6:7], v[66:67]
	v_pk_add_f32 v[0:1], v[0:1], v[68:69]
	v_pk_add_f32 v[2:3], v[2:3], v[70:71]
	v_add_u32_e32 v35, 0x100, v35
	v_pk_add_f32 v[14:15], v[14:15], v[18:19]
	v_pk_add_f32 v[12:13], v[12:13], v[16:17]
	v_pk_add_f32 v[10:11], v[10:11], v[22:23]
	v_pk_add_f32 v[8:9], v[8:9], v[20:21]
	v_pk_add_f32 v[6:7], v[6:7], v[40:41]
	v_pk_add_f32 v[4:5], v[4:5], v[38:39]
	v_pk_add_f32 v[2:3], v[2:3], v[28:29]
	v_pk_add_f32 v[0:1], v[0:1], v[30:31]
	v_lshl_add_u64 v[16:17], v[24:25], 0, s[0:1]
	v_lshl_add_u64 v[18:19], v[26:27], 0, s[0:1]
	s_waitcnt vmcnt(4)
	v_mov_b32_e32 v72, v138
	v_mov_b32_e32 v73, v139
	v_mov_b32_e32 v74, v230
	v_mov_b32_e32 v75, v231
	ds_read2_b64 v[28:31], v36 offset1:17
	ds_read_b128 v[38:41], v35
	ds_read_b128 v[42:45], v35 offset:16
	ds_read_b128 v[48:51], v35 offset:32
	ds_read_b128 v[52:55], v35 offset:48
	ds_read_b128 v[56:59], v35 offset:64
	ds_read_b128 v[60:63], v35 offset:80
	ds_read_b128 v[64:67], v35 offset:96
	ds_read_b128 v[68:71], v35 offset:112
	ds_read_b128 v[16:19], v35 offset:128
	ds_read_b128 v[20:23], v35 offset:192
	s_add_u32 s0, s0, 8
	s_addc_u32 s1, s1, 0
	v_add_u32_e32 v36, 0x110, v36
	s_cmpk_eq_i32 s0, 0x100
	v_mov_b32_e32 v76, v72
	v_mov_b32_e32 v77, v74
	s_waitcnt lgkmcnt(10)
	v_mul_f32_e32 v78, v74, v29
	v_mov_b32_e32 v80, v74
	v_mov_b32_e32 v81, v72
	v_mul_f32_e32 v72, v72, v29
	v_pk_fma_f32 v[76:77], v[76:77], v[28:29], v[78:79] op_sel_hi:[1,1,0] neg_lo:[0,0,1] neg_hi:[0,0,1]
	v_pk_fma_f32 v[78:79], v[80:81], v[28:29], v[72:73] op_sel_hi:[1,1,0]
	v_mov_b32_e32 v74, v73
	v_mul_f32_e32 v28, v75, v31
	s_waitcnt lgkmcnt(4)
	v_pk_mul_f32 v[60:61], v[78:79], v[60:61] op_sel_hi:[0,1]
	v_pk_mul_f32 v[62:63], v[78:79], v[62:63] op_sel_hi:[0,1]
	s_waitcnt lgkmcnt(2)
	v_pk_mul_f32 v[68:69], v[78:79], v[68:69] op_sel_hi:[0,1]
	v_pk_mul_f32 v[70:71], v[78:79], v[70:71] op_sel_hi:[0,1]
	v_mov_b32_e32 v72, v75
	v_pk_fma_f32 v[28:29], v[74:75], v[30:31], v[28:29] op_sel_hi:[1,1,0] neg_lo:[0,0,1] neg_hi:[0,0,1]
	v_mul_f32_e32 v74, v73, v31
	v_pk_mul_f32 v[80:81], v[56:57], v[78:79] op_sel_hi:[1,0]
	v_pk_mul_f32 v[82:83], v[58:59], v[78:79] op_sel_hi:[1,0]
	v_pk_mul_f32 v[64:65], v[78:79], v[64:65] op_sel_hi:[0,1]
	v_pk_mul_f32 v[66:67], v[78:79], v[66:67] op_sel_hi:[0,1]
	ds_read_b128 v[56:59], v35 offset:208
	v_pk_fma_f32 v[62:63], v[44:45], v[76:77], v[62:63] op_sel_hi:[1,0,1] neg_lo:[0,0,1] neg_hi:[0,0,1]
	v_pk_fma_f32 v[60:61], v[42:43], v[76:77], v[60:61] op_sel_hi:[1,0,1] neg_lo:[0,0,1] neg_hi:[0,0,1]
	ds_read_b128 v[42:45], v35 offset:224
	v_pk_fma_f32 v[70:71], v[76:77], v[54:55], v[70:71] op_sel_hi:[0,1,1] neg_lo:[0,0,1] neg_hi:[0,0,1]
	v_pk_fma_f32 v[68:69], v[76:77], v[52:53], v[68:69] op_sel_hi:[0,1,1] neg_lo:[0,0,1] neg_hi:[0,0,1]
	ds_read_b128 v[52:55], v35 offset:240
	v_pk_fma_f32 v[30:31], v[72:73], v[30:31], v[74:75] op_sel_hi:[1,1,0]
	ds_read_b128 v[72:75], v35 offset:144
	v_pk_fma_f32 v[78:79], v[40:41], v[76:77], v[82:83] op_sel_hi:[1,0,1] neg_lo:[0,0,1] neg_hi:[0,0,1]
	v_pk_fma_f32 v[80:81], v[38:39], v[76:77], v[80:81] op_sel_hi:[1,0,1] neg_lo:[0,0,1] neg_hi:[0,0,1]
	ds_read_b128 v[38:41], v35 offset:160
	v_pk_fma_f32 v[66:67], v[76:77], v[50:51], v[66:67] op_sel_hi:[0,1,1] neg_lo:[0,0,1] neg_hi:[0,0,1]
	v_pk_fma_f32 v[64:65], v[76:77], v[48:49], v[64:65] op_sel_hi:[0,1,1] neg_lo:[0,0,1] neg_hi:[0,0,1]
	ds_read_b128 v[48:51], v35 offset:176
	s_waitcnt lgkmcnt(6)
	v_pk_mul_f32 v[22:23], v[22:23], v[30:31] op_sel_hi:[1,0]
	v_pk_mul_f32 v[20:21], v[20:21], v[30:31] op_sel_hi:[1,0]
	s_waitcnt lgkmcnt(5)
	v_pk_mul_f32 v[58:59], v[30:31], v[58:59] op_sel_hi:[0,1]
	v_pk_mul_f32 v[56:57], v[30:31], v[56:57] op_sel_hi:[0,1]
	s_waitcnt lgkmcnt(4)
	v_pk_mul_f32 v[44:45], v[30:31], v[44:45] op_sel_hi:[0,1]
	v_pk_mul_f32 v[42:43], v[30:31], v[42:43] op_sel_hi:[0,1]
	s_waitcnt lgkmcnt(3)
	v_pk_mul_f32 v[54:55], v[30:31], v[54:55] op_sel_hi:[0,1]
	v_pk_mul_f32 v[30:31], v[30:31], v[52:53] op_sel_hi:[0,1]
	v_pk_fma_f32 v[16:17], v[16:17], v[28:29], v[20:21] op_sel_hi:[1,0,1] neg_lo:[0,0,1] neg_hi:[0,0,1]
	v_pk_fma_f32 v[18:19], v[18:19], v[28:29], v[22:23] op_sel_hi:[1,0,1] neg_lo:[0,0,1] neg_hi:[0,0,1]
	s_waitcnt lgkmcnt(2)
	v_pk_fma_f32 v[20:21], v[72:73], v[28:29], v[56:57] op_sel_hi:[1,0,1] neg_lo:[0,0,1] neg_hi:[0,0,1]
	v_pk_fma_f32 v[22:23], v[74:75], v[28:29], v[58:59] op_sel_hi:[1,0,1] neg_lo:[0,0,1] neg_hi:[0,0,1]
	s_waitcnt lgkmcnt(1)
	v_pk_fma_f32 v[38:39], v[28:29], v[38:39], v[42:43] op_sel_hi:[0,1,1] neg_lo:[0,0,1] neg_hi:[0,0,1]
	v_pk_fma_f32 v[40:41], v[28:29], v[40:41], v[44:45] op_sel_hi:[0,1,1] neg_lo:[0,0,1] neg_hi:[0,0,1]
	s_waitcnt lgkmcnt(0)
	v_pk_fma_f32 v[30:31], v[28:29], v[48:49], v[30:31] op_sel_hi:[0,1,1] neg_lo:[0,0,1] neg_hi:[0,0,1]
	v_pk_fma_f32 v[28:29], v[28:29], v[50:51], v[54:55] op_sel_hi:[0,1,1] neg_lo:[0,0,1] neg_hi:[0,0,1]
	v_pk_add_f32 v[12:13], v[12:13], v[80:81]
	v_pk_add_f32 v[14:15], v[14:15], v[78:79]
	v_pk_add_f32 v[8:9], v[8:9], v[60:61]
	v_pk_add_f32 v[10:11], v[10:11], v[62:63]
	v_pk_add_f32 v[4:5], v[4:5], v[64:65]
	v_pk_add_f32 v[6:7], v[6:7], v[66:67]
	v_pk_add_f32 v[0:1], v[0:1], v[68:69]
	v_pk_add_f32 v[2:3], v[2:3], v[70:71]
	v_add_u32_e32 v35, 0x100, v35
	v_pk_add_f32 v[14:15], v[14:15], v[18:19]
	v_pk_add_f32 v[12:13], v[12:13], v[16:17]
	v_pk_add_f32 v[10:11], v[10:11], v[22:23]
	v_pk_add_f32 v[8:9], v[8:9], v[20:21]
	v_pk_add_f32 v[6:7], v[6:7], v[40:41]
	v_pk_add_f32 v[4:5], v[4:5], v[38:39]
	v_pk_add_f32 v[2:3], v[2:3], v[28:29]
	v_pk_add_f32 v[0:1], v[0:1], v[30:31]
	v_lshl_add_u64 v[16:17], v[24:25], 0, s[0:1]
	v_lshl_add_u64 v[18:19], v[26:27], 0, s[0:1]
	s_waitcnt vmcnt(2)
	v_mov_b32_e32 v72, v140
	v_mov_b32_e32 v73, v141
	v_mov_b32_e32 v74, v232
	v_mov_b32_e32 v75, v233
	ds_read2_b64 v[28:31], v36 offset1:17
	ds_read_b128 v[38:41], v35
	ds_read_b128 v[42:45], v35 offset:16
	ds_read_b128 v[48:51], v35 offset:32
	ds_read_b128 v[52:55], v35 offset:48
	ds_read_b128 v[56:59], v35 offset:64
	ds_read_b128 v[60:63], v35 offset:80
	ds_read_b128 v[64:67], v35 offset:96
	ds_read_b128 v[68:71], v35 offset:112
	ds_read_b128 v[16:19], v35 offset:128
	ds_read_b128 v[20:23], v35 offset:192
	s_add_u32 s0, s0, 8
	s_addc_u32 s1, s1, 0
	v_add_u32_e32 v36, 0x110, v36
	s_cmpk_eq_i32 s0, 0x100
	v_mov_b32_e32 v76, v72
	v_mov_b32_e32 v77, v74
	s_waitcnt lgkmcnt(10)
	v_mul_f32_e32 v78, v74, v29
	v_mov_b32_e32 v80, v74
	v_mov_b32_e32 v81, v72
	v_mul_f32_e32 v72, v72, v29
	v_pk_fma_f32 v[76:77], v[76:77], v[28:29], v[78:79] op_sel_hi:[1,1,0] neg_lo:[0,0,1] neg_hi:[0,0,1]
	v_pk_fma_f32 v[78:79], v[80:81], v[28:29], v[72:73] op_sel_hi:[1,1,0]
	v_mov_b32_e32 v74, v73
	v_mul_f32_e32 v28, v75, v31
	s_waitcnt lgkmcnt(4)
	v_pk_mul_f32 v[60:61], v[78:79], v[60:61] op_sel_hi:[0,1]
	v_pk_mul_f32 v[62:63], v[78:79], v[62:63] op_sel_hi:[0,1]
	s_waitcnt lgkmcnt(2)
	v_pk_mul_f32 v[68:69], v[78:79], v[68:69] op_sel_hi:[0,1]
	v_pk_mul_f32 v[70:71], v[78:79], v[70:71] op_sel_hi:[0,1]
	v_mov_b32_e32 v72, v75
	v_pk_fma_f32 v[28:29], v[74:75], v[30:31], v[28:29] op_sel_hi:[1,1,0] neg_lo:[0,0,1] neg_hi:[0,0,1]
	v_mul_f32_e32 v74, v73, v31
	v_pk_mul_f32 v[80:81], v[56:57], v[78:79] op_sel_hi:[1,0]
	v_pk_mul_f32 v[82:83], v[58:59], v[78:79] op_sel_hi:[1,0]
	v_pk_mul_f32 v[64:65], v[78:79], v[64:65] op_sel_hi:[0,1]
	v_pk_mul_f32 v[66:67], v[78:79], v[66:67] op_sel_hi:[0,1]
	ds_read_b128 v[56:59], v35 offset:208
	v_pk_fma_f32 v[62:63], v[44:45], v[76:77], v[62:63] op_sel_hi:[1,0,1] neg_lo:[0,0,1] neg_hi:[0,0,1]
	v_pk_fma_f32 v[60:61], v[42:43], v[76:77], v[60:61] op_sel_hi:[1,0,1] neg_lo:[0,0,1] neg_hi:[0,0,1]
	ds_read_b128 v[42:45], v35 offset:224
	v_pk_fma_f32 v[70:71], v[76:77], v[54:55], v[70:71] op_sel_hi:[0,1,1] neg_lo:[0,0,1] neg_hi:[0,0,1]
	v_pk_fma_f32 v[68:69], v[76:77], v[52:53], v[68:69] op_sel_hi:[0,1,1] neg_lo:[0,0,1] neg_hi:[0,0,1]
	ds_read_b128 v[52:55], v35 offset:240
	v_pk_fma_f32 v[30:31], v[72:73], v[30:31], v[74:75] op_sel_hi:[1,1,0]
	ds_read_b128 v[72:75], v35 offset:144
	v_pk_fma_f32 v[78:79], v[40:41], v[76:77], v[82:83] op_sel_hi:[1,0,1] neg_lo:[0,0,1] neg_hi:[0,0,1]
	v_pk_fma_f32 v[80:81], v[38:39], v[76:77], v[80:81] op_sel_hi:[1,0,1] neg_lo:[0,0,1] neg_hi:[0,0,1]
	ds_read_b128 v[38:41], v35 offset:160
	v_pk_fma_f32 v[66:67], v[76:77], v[50:51], v[66:67] op_sel_hi:[0,1,1] neg_lo:[0,0,1] neg_hi:[0,0,1]
	v_pk_fma_f32 v[64:65], v[76:77], v[48:49], v[64:65] op_sel_hi:[0,1,1] neg_lo:[0,0,1] neg_hi:[0,0,1]
	ds_read_b128 v[48:51], v35 offset:176
	s_waitcnt lgkmcnt(6)
	v_pk_mul_f32 v[22:23], v[22:23], v[30:31] op_sel_hi:[1,0]
	v_pk_mul_f32 v[20:21], v[20:21], v[30:31] op_sel_hi:[1,0]
	s_waitcnt lgkmcnt(5)
	v_pk_mul_f32 v[58:59], v[30:31], v[58:59] op_sel_hi:[0,1]
	v_pk_mul_f32 v[56:57], v[30:31], v[56:57] op_sel_hi:[0,1]
	s_waitcnt lgkmcnt(4)
	v_pk_mul_f32 v[44:45], v[30:31], v[44:45] op_sel_hi:[0,1]
	v_pk_mul_f32 v[42:43], v[30:31], v[42:43] op_sel_hi:[0,1]
	s_waitcnt lgkmcnt(3)
	v_pk_mul_f32 v[54:55], v[30:31], v[54:55] op_sel_hi:[0,1]
	v_pk_mul_f32 v[30:31], v[30:31], v[52:53] op_sel_hi:[0,1]
	v_pk_fma_f32 v[16:17], v[16:17], v[28:29], v[20:21] op_sel_hi:[1,0,1] neg_lo:[0,0,1] neg_hi:[0,0,1]
	v_pk_fma_f32 v[18:19], v[18:19], v[28:29], v[22:23] op_sel_hi:[1,0,1] neg_lo:[0,0,1] neg_hi:[0,0,1]
	s_waitcnt lgkmcnt(2)
	v_pk_fma_f32 v[20:21], v[72:73], v[28:29], v[56:57] op_sel_hi:[1,0,1] neg_lo:[0,0,1] neg_hi:[0,0,1]
	v_pk_fma_f32 v[22:23], v[74:75], v[28:29], v[58:59] op_sel_hi:[1,0,1] neg_lo:[0,0,1] neg_hi:[0,0,1]
	s_waitcnt lgkmcnt(1)
	v_pk_fma_f32 v[38:39], v[28:29], v[38:39], v[42:43] op_sel_hi:[0,1,1] neg_lo:[0,0,1] neg_hi:[0,0,1]
	v_pk_fma_f32 v[40:41], v[28:29], v[40:41], v[44:45] op_sel_hi:[0,1,1] neg_lo:[0,0,1] neg_hi:[0,0,1]
	s_waitcnt lgkmcnt(0)
	v_pk_fma_f32 v[30:31], v[28:29], v[48:49], v[30:31] op_sel_hi:[0,1,1] neg_lo:[0,0,1] neg_hi:[0,0,1]
	v_pk_fma_f32 v[28:29], v[28:29], v[50:51], v[54:55] op_sel_hi:[0,1,1] neg_lo:[0,0,1] neg_hi:[0,0,1]
	v_pk_add_f32 v[12:13], v[12:13], v[80:81]
	v_pk_add_f32 v[14:15], v[14:15], v[78:79]
	v_pk_add_f32 v[8:9], v[8:9], v[60:61]
	v_pk_add_f32 v[10:11], v[10:11], v[62:63]
	v_pk_add_f32 v[4:5], v[4:5], v[64:65]
	v_pk_add_f32 v[6:7], v[6:7], v[66:67]
	v_pk_add_f32 v[0:1], v[0:1], v[68:69]
	v_pk_add_f32 v[2:3], v[2:3], v[70:71]
	v_add_u32_e32 v35, 0x100, v35
	v_pk_add_f32 v[14:15], v[14:15], v[18:19]
	v_pk_add_f32 v[12:13], v[12:13], v[16:17]
	v_pk_add_f32 v[10:11], v[10:11], v[22:23]
	v_pk_add_f32 v[8:9], v[8:9], v[20:21]
	v_pk_add_f32 v[6:7], v[6:7], v[40:41]
	v_pk_add_f32 v[4:5], v[4:5], v[38:39]
	v_pk_add_f32 v[2:3], v[2:3], v[28:29]
	v_pk_add_f32 v[0:1], v[0:1], v[30:31]
	v_lshl_add_u64 v[16:17], v[24:25], 0, s[0:1]
	v_lshl_add_u64 v[18:19], v[26:27], 0, s[0:1]
	s_waitcnt vmcnt(2)
	v_mov_b32_e32 v72, v142
	v_mov_b32_e32 v73, v143
	v_mov_b32_e32 v74, v234
	v_mov_b32_e32 v75, v235
	ds_read2_b64 v[28:31], v36 offset1:17
	ds_read_b128 v[38:41], v35
	ds_read_b128 v[42:45], v35 offset:16
	ds_read_b128 v[48:51], v35 offset:32
	ds_read_b128 v[52:55], v35 offset:48
	ds_read_b128 v[56:59], v35 offset:64
	ds_read_b128 v[60:63], v35 offset:80
	ds_read_b128 v[64:67], v35 offset:96
	ds_read_b128 v[68:71], v35 offset:112
	ds_read_b128 v[16:19], v35 offset:128
	ds_read_b128 v[20:23], v35 offset:192
	s_add_u32 s0, s0, 8
	s_addc_u32 s1, s1, 0
	v_add_u32_e32 v36, 0x110, v36
	s_cmpk_eq_i32 s0, 0x100
	v_mov_b32_e32 v76, v72
	v_mov_b32_e32 v77, v74
	s_waitcnt lgkmcnt(10)
	v_mul_f32_e32 v78, v74, v29
	v_mov_b32_e32 v80, v74
	v_mov_b32_e32 v81, v72
	v_mul_f32_e32 v72, v72, v29
	v_pk_fma_f32 v[76:77], v[76:77], v[28:29], v[78:79] op_sel_hi:[1,1,0] neg_lo:[0,0,1] neg_hi:[0,0,1]
	v_pk_fma_f32 v[78:79], v[80:81], v[28:29], v[72:73] op_sel_hi:[1,1,0]
	v_mov_b32_e32 v74, v73
	v_mul_f32_e32 v28, v75, v31
	s_waitcnt lgkmcnt(4)
	v_pk_mul_f32 v[60:61], v[78:79], v[60:61] op_sel_hi:[0,1]
	v_pk_mul_f32 v[62:63], v[78:79], v[62:63] op_sel_hi:[0,1]
	s_waitcnt lgkmcnt(2)
	v_pk_mul_f32 v[68:69], v[78:79], v[68:69] op_sel_hi:[0,1]
	v_pk_mul_f32 v[70:71], v[78:79], v[70:71] op_sel_hi:[0,1]
	v_mov_b32_e32 v72, v75
	v_pk_fma_f32 v[28:29], v[74:75], v[30:31], v[28:29] op_sel_hi:[1,1,0] neg_lo:[0,0,1] neg_hi:[0,0,1]
	v_mul_f32_e32 v74, v73, v31
	v_pk_mul_f32 v[80:81], v[56:57], v[78:79] op_sel_hi:[1,0]
	v_pk_mul_f32 v[82:83], v[58:59], v[78:79] op_sel_hi:[1,0]
	v_pk_mul_f32 v[64:65], v[78:79], v[64:65] op_sel_hi:[0,1]
	v_pk_mul_f32 v[66:67], v[78:79], v[66:67] op_sel_hi:[0,1]
	ds_read_b128 v[56:59], v35 offset:208
	v_pk_fma_f32 v[62:63], v[44:45], v[76:77], v[62:63] op_sel_hi:[1,0,1] neg_lo:[0,0,1] neg_hi:[0,0,1]
	v_pk_fma_f32 v[60:61], v[42:43], v[76:77], v[60:61] op_sel_hi:[1,0,1] neg_lo:[0,0,1] neg_hi:[0,0,1]
	ds_read_b128 v[42:45], v35 offset:224
	v_pk_fma_f32 v[70:71], v[76:77], v[54:55], v[70:71] op_sel_hi:[0,1,1] neg_lo:[0,0,1] neg_hi:[0,0,1]
	v_pk_fma_f32 v[68:69], v[76:77], v[52:53], v[68:69] op_sel_hi:[0,1,1] neg_lo:[0,0,1] neg_hi:[0,0,1]
	ds_read_b128 v[52:55], v35 offset:240
	v_pk_fma_f32 v[30:31], v[72:73], v[30:31], v[74:75] op_sel_hi:[1,1,0]
	ds_read_b128 v[72:75], v35 offset:144
	v_pk_fma_f32 v[78:79], v[40:41], v[76:77], v[82:83] op_sel_hi:[1,0,1] neg_lo:[0,0,1] neg_hi:[0,0,1]
	v_pk_fma_f32 v[80:81], v[38:39], v[76:77], v[80:81] op_sel_hi:[1,0,1] neg_lo:[0,0,1] neg_hi:[0,0,1]
	ds_read_b128 v[38:41], v35 offset:160
	v_pk_fma_f32 v[66:67], v[76:77], v[50:51], v[66:67] op_sel_hi:[0,1,1] neg_lo:[0,0,1] neg_hi:[0,0,1]
	v_pk_fma_f32 v[64:65], v[76:77], v[48:49], v[64:65] op_sel_hi:[0,1,1] neg_lo:[0,0,1] neg_hi:[0,0,1]
	ds_read_b128 v[48:51], v35 offset:176
	s_waitcnt lgkmcnt(6)
	v_pk_mul_f32 v[22:23], v[22:23], v[30:31] op_sel_hi:[1,0]
	v_pk_mul_f32 v[20:21], v[20:21], v[30:31] op_sel_hi:[1,0]
	s_waitcnt lgkmcnt(5)
	v_pk_mul_f32 v[58:59], v[30:31], v[58:59] op_sel_hi:[0,1]
	v_pk_mul_f32 v[56:57], v[30:31], v[56:57] op_sel_hi:[0,1]
	s_waitcnt lgkmcnt(4)
	v_pk_mul_f32 v[44:45], v[30:31], v[44:45] op_sel_hi:[0,1]
	v_pk_mul_f32 v[42:43], v[30:31], v[42:43] op_sel_hi:[0,1]
	s_waitcnt lgkmcnt(3)
	v_pk_mul_f32 v[54:55], v[30:31], v[54:55] op_sel_hi:[0,1]
	v_pk_mul_f32 v[30:31], v[30:31], v[52:53] op_sel_hi:[0,1]
	v_pk_fma_f32 v[16:17], v[16:17], v[28:29], v[20:21] op_sel_hi:[1,0,1] neg_lo:[0,0,1] neg_hi:[0,0,1]
	v_pk_fma_f32 v[18:19], v[18:19], v[28:29], v[22:23] op_sel_hi:[1,0,1] neg_lo:[0,0,1] neg_hi:[0,0,1]
	s_waitcnt lgkmcnt(2)
	v_pk_fma_f32 v[20:21], v[72:73], v[28:29], v[56:57] op_sel_hi:[1,0,1] neg_lo:[0,0,1] neg_hi:[0,0,1]
	v_pk_fma_f32 v[22:23], v[74:75], v[28:29], v[58:59] op_sel_hi:[1,0,1] neg_lo:[0,0,1] neg_hi:[0,0,1]
	s_waitcnt lgkmcnt(1)
	v_pk_fma_f32 v[38:39], v[28:29], v[38:39], v[42:43] op_sel_hi:[0,1,1] neg_lo:[0,0,1] neg_hi:[0,0,1]
	v_pk_fma_f32 v[40:41], v[28:29], v[40:41], v[44:45] op_sel_hi:[0,1,1] neg_lo:[0,0,1] neg_hi:[0,0,1]
	s_waitcnt lgkmcnt(0)
	v_pk_fma_f32 v[30:31], v[28:29], v[48:49], v[30:31] op_sel_hi:[0,1,1] neg_lo:[0,0,1] neg_hi:[0,0,1]
	v_pk_fma_f32 v[28:29], v[28:29], v[50:51], v[54:55] op_sel_hi:[0,1,1] neg_lo:[0,0,1] neg_hi:[0,0,1]
	v_pk_add_f32 v[12:13], v[12:13], v[80:81]
	v_pk_add_f32 v[14:15], v[14:15], v[78:79]
	v_pk_add_f32 v[8:9], v[8:9], v[60:61]
	v_pk_add_f32 v[10:11], v[10:11], v[62:63]
	v_pk_add_f32 v[4:5], v[4:5], v[64:65]
	v_pk_add_f32 v[6:7], v[6:7], v[66:67]
	v_pk_add_f32 v[0:1], v[0:1], v[68:69]
	v_pk_add_f32 v[2:3], v[2:3], v[70:71]
	v_add_u32_e32 v35, 0x100, v35
	v_pk_add_f32 v[14:15], v[14:15], v[18:19]
	v_pk_add_f32 v[12:13], v[12:13], v[16:17]
	v_pk_add_f32 v[10:11], v[10:11], v[22:23]
	v_pk_add_f32 v[8:9], v[8:9], v[20:21]
	v_pk_add_f32 v[6:7], v[6:7], v[40:41]
	v_pk_add_f32 v[4:5], v[4:5], v[38:39]
	v_pk_add_f32 v[2:3], v[2:3], v[28:29]
	v_pk_add_f32 v[0:1], v[0:1], v[30:31]
	v_lshl_add_u64 v[16:17], v[24:25], 0, s[0:1]
	v_lshl_add_u64 v[18:19], v[26:27], 0, s[0:1]
	s_waitcnt vmcnt(0)
	v_mov_b32_e32 v72, v148
	v_mov_b32_e32 v73, v149
	v_mov_b32_e32 v74, v236
	v_mov_b32_e32 v75, v237
	ds_read2_b64 v[28:31], v36 offset1:17
	ds_read_b128 v[38:41], v35
	ds_read_b128 v[42:45], v35 offset:16
	ds_read_b128 v[48:51], v35 offset:32
	ds_read_b128 v[52:55], v35 offset:48
	ds_read_b128 v[56:59], v35 offset:64
	ds_read_b128 v[60:63], v35 offset:80
	ds_read_b128 v[64:67], v35 offset:96
	ds_read_b128 v[68:71], v35 offset:112
	ds_read_b128 v[16:19], v35 offset:128
	ds_read_b128 v[20:23], v35 offset:192
	s_add_u32 s0, s0, 8
	s_addc_u32 s1, s1, 0
	v_add_u32_e32 v36, 0x110, v36
	s_cmpk_eq_i32 s0, 0x100
	v_mov_b32_e32 v76, v72
	v_mov_b32_e32 v77, v74
	s_waitcnt lgkmcnt(10)
	v_mul_f32_e32 v78, v74, v29
	v_mov_b32_e32 v80, v74
	v_mov_b32_e32 v81, v72
	v_mul_f32_e32 v72, v72, v29
	v_pk_fma_f32 v[76:77], v[76:77], v[28:29], v[78:79] op_sel_hi:[1,1,0] neg_lo:[0,0,1] neg_hi:[0,0,1]
	v_pk_fma_f32 v[78:79], v[80:81], v[28:29], v[72:73] op_sel_hi:[1,1,0]
	v_mov_b32_e32 v74, v73
	v_mul_f32_e32 v28, v75, v31
	s_waitcnt lgkmcnt(4)
	v_pk_mul_f32 v[60:61], v[78:79], v[60:61] op_sel_hi:[0,1]
	v_pk_mul_f32 v[62:63], v[78:79], v[62:63] op_sel_hi:[0,1]
	s_waitcnt lgkmcnt(2)
	v_pk_mul_f32 v[68:69], v[78:79], v[68:69] op_sel_hi:[0,1]
	v_pk_mul_f32 v[70:71], v[78:79], v[70:71] op_sel_hi:[0,1]
	v_mov_b32_e32 v72, v75
	v_pk_fma_f32 v[28:29], v[74:75], v[30:31], v[28:29] op_sel_hi:[1,1,0] neg_lo:[0,0,1] neg_hi:[0,0,1]
	v_mul_f32_e32 v74, v73, v31
	v_pk_mul_f32 v[80:81], v[56:57], v[78:79] op_sel_hi:[1,0]
	v_pk_mul_f32 v[82:83], v[58:59], v[78:79] op_sel_hi:[1,0]
	v_pk_mul_f32 v[64:65], v[78:79], v[64:65] op_sel_hi:[0,1]
	v_pk_mul_f32 v[66:67], v[78:79], v[66:67] op_sel_hi:[0,1]
	ds_read_b128 v[56:59], v35 offset:208
	v_pk_fma_f32 v[62:63], v[44:45], v[76:77], v[62:63] op_sel_hi:[1,0,1] neg_lo:[0,0,1] neg_hi:[0,0,1]
	v_pk_fma_f32 v[60:61], v[42:43], v[76:77], v[60:61] op_sel_hi:[1,0,1] neg_lo:[0,0,1] neg_hi:[0,0,1]
	ds_read_b128 v[42:45], v35 offset:224
	v_pk_fma_f32 v[70:71], v[76:77], v[54:55], v[70:71] op_sel_hi:[0,1,1] neg_lo:[0,0,1] neg_hi:[0,0,1]
	v_pk_fma_f32 v[68:69], v[76:77], v[52:53], v[68:69] op_sel_hi:[0,1,1] neg_lo:[0,0,1] neg_hi:[0,0,1]
	ds_read_b128 v[52:55], v35 offset:240
	v_pk_fma_f32 v[30:31], v[72:73], v[30:31], v[74:75] op_sel_hi:[1,1,0]
	ds_read_b128 v[72:75], v35 offset:144
	v_pk_fma_f32 v[78:79], v[40:41], v[76:77], v[82:83] op_sel_hi:[1,0,1] neg_lo:[0,0,1] neg_hi:[0,0,1]
	v_pk_fma_f32 v[80:81], v[38:39], v[76:77], v[80:81] op_sel_hi:[1,0,1] neg_lo:[0,0,1] neg_hi:[0,0,1]
	ds_read_b128 v[38:41], v35 offset:160
	v_pk_fma_f32 v[66:67], v[76:77], v[50:51], v[66:67] op_sel_hi:[0,1,1] neg_lo:[0,0,1] neg_hi:[0,0,1]
	v_pk_fma_f32 v[64:65], v[76:77], v[48:49], v[64:65] op_sel_hi:[0,1,1] neg_lo:[0,0,1] neg_hi:[0,0,1]
	ds_read_b128 v[48:51], v35 offset:176
	s_waitcnt lgkmcnt(6)
	v_pk_mul_f32 v[22:23], v[22:23], v[30:31] op_sel_hi:[1,0]
	v_pk_mul_f32 v[20:21], v[20:21], v[30:31] op_sel_hi:[1,0]
	s_waitcnt lgkmcnt(5)
	v_pk_mul_f32 v[58:59], v[30:31], v[58:59] op_sel_hi:[0,1]
	v_pk_mul_f32 v[56:57], v[30:31], v[56:57] op_sel_hi:[0,1]
	s_waitcnt lgkmcnt(4)
	v_pk_mul_f32 v[44:45], v[30:31], v[44:45] op_sel_hi:[0,1]
	v_pk_mul_f32 v[42:43], v[30:31], v[42:43] op_sel_hi:[0,1]
	s_waitcnt lgkmcnt(3)
	v_pk_mul_f32 v[54:55], v[30:31], v[54:55] op_sel_hi:[0,1]
	v_pk_mul_f32 v[30:31], v[30:31], v[52:53] op_sel_hi:[0,1]
	v_pk_fma_f32 v[16:17], v[16:17], v[28:29], v[20:21] op_sel_hi:[1,0,1] neg_lo:[0,0,1] neg_hi:[0,0,1]
	v_pk_fma_f32 v[18:19], v[18:19], v[28:29], v[22:23] op_sel_hi:[1,0,1] neg_lo:[0,0,1] neg_hi:[0,0,1]
	s_waitcnt lgkmcnt(2)
	v_pk_fma_f32 v[20:21], v[72:73], v[28:29], v[56:57] op_sel_hi:[1,0,1] neg_lo:[0,0,1] neg_hi:[0,0,1]
	v_pk_fma_f32 v[22:23], v[74:75], v[28:29], v[58:59] op_sel_hi:[1,0,1] neg_lo:[0,0,1] neg_hi:[0,0,1]
	s_waitcnt lgkmcnt(1)
	v_pk_fma_f32 v[38:39], v[28:29], v[38:39], v[42:43] op_sel_hi:[0,1,1] neg_lo:[0,0,1] neg_hi:[0,0,1]
	v_pk_fma_f32 v[40:41], v[28:29], v[40:41], v[44:45] op_sel_hi:[0,1,1] neg_lo:[0,0,1] neg_hi:[0,0,1]
	s_waitcnt lgkmcnt(0)
	v_pk_fma_f32 v[30:31], v[28:29], v[48:49], v[30:31] op_sel_hi:[0,1,1] neg_lo:[0,0,1] neg_hi:[0,0,1]
	v_pk_fma_f32 v[28:29], v[28:29], v[50:51], v[54:55] op_sel_hi:[0,1,1] neg_lo:[0,0,1] neg_hi:[0,0,1]
	v_pk_add_f32 v[12:13], v[12:13], v[80:81]
	v_pk_add_f32 v[14:15], v[14:15], v[78:79]
	v_pk_add_f32 v[8:9], v[8:9], v[60:61]
	v_pk_add_f32 v[10:11], v[10:11], v[62:63]
	v_pk_add_f32 v[4:5], v[4:5], v[64:65]
	v_pk_add_f32 v[6:7], v[6:7], v[66:67]
	v_pk_add_f32 v[0:1], v[0:1], v[68:69]
	v_pk_add_f32 v[2:3], v[2:3], v[70:71]
	v_add_u32_e32 v35, 0x100, v35
	v_pk_add_f32 v[14:15], v[14:15], v[18:19]
	v_pk_add_f32 v[12:13], v[12:13], v[16:17]
	v_pk_add_f32 v[10:11], v[10:11], v[22:23]
	v_pk_add_f32 v[8:9], v[8:9], v[20:21]
	v_pk_add_f32 v[6:7], v[6:7], v[40:41]
	v_pk_add_f32 v[4:5], v[4:5], v[38:39]
	v_pk_add_f32 v[2:3], v[2:3], v[28:29]
	v_pk_add_f32 v[0:1], v[0:1], v[30:31]
	v_lshl_add_u64 v[16:17], v[24:25], 0, s[0:1]
	v_lshl_add_u64 v[18:19], v[26:27], 0, s[0:1]
	s_waitcnt vmcnt(0)
	v_mov_b32_e32 v72, v150
	v_mov_b32_e32 v73, v151
	v_mov_b32_e32 v74, v238
	v_mov_b32_e32 v75, v239
	ds_read2_b64 v[28:31], v36 offset1:17
	ds_read_b128 v[38:41], v35
	ds_read_b128 v[42:45], v35 offset:16
	ds_read_b128 v[48:51], v35 offset:32
	ds_read_b128 v[52:55], v35 offset:48
	ds_read_b128 v[56:59], v35 offset:64
	ds_read_b128 v[60:63], v35 offset:80
	ds_read_b128 v[64:67], v35 offset:96
	ds_read_b128 v[68:71], v35 offset:112
	ds_read_b128 v[16:19], v35 offset:128
	ds_read_b128 v[20:23], v35 offset:192
	s_add_u32 s0, s0, 8
	s_addc_u32 s1, s1, 0
	v_add_u32_e32 v36, 0x110, v36
	s_cmpk_eq_i32 s0, 0x100
	v_mov_b32_e32 v76, v72
	v_mov_b32_e32 v77, v74
	s_waitcnt lgkmcnt(10)
	v_mul_f32_e32 v78, v74, v29
	v_mov_b32_e32 v80, v74
	v_mov_b32_e32 v81, v72
	v_mul_f32_e32 v72, v72, v29
	v_pk_fma_f32 v[76:77], v[76:77], v[28:29], v[78:79] op_sel_hi:[1,1,0] neg_lo:[0,0,1] neg_hi:[0,0,1]
	v_pk_fma_f32 v[78:79], v[80:81], v[28:29], v[72:73] op_sel_hi:[1,1,0]
	v_mov_b32_e32 v74, v73
	v_mul_f32_e32 v28, v75, v31
	s_waitcnt lgkmcnt(4)
	v_pk_mul_f32 v[60:61], v[78:79], v[60:61] op_sel_hi:[0,1]
	v_pk_mul_f32 v[62:63], v[78:79], v[62:63] op_sel_hi:[0,1]
	s_waitcnt lgkmcnt(2)
	v_pk_mul_f32 v[68:69], v[78:79], v[68:69] op_sel_hi:[0,1]
	v_pk_mul_f32 v[70:71], v[78:79], v[70:71] op_sel_hi:[0,1]
	v_mov_b32_e32 v72, v75
	v_pk_fma_f32 v[28:29], v[74:75], v[30:31], v[28:29] op_sel_hi:[1,1,0] neg_lo:[0,0,1] neg_hi:[0,0,1]
	v_mul_f32_e32 v74, v73, v31
	v_pk_mul_f32 v[80:81], v[56:57], v[78:79] op_sel_hi:[1,0]
	v_pk_mul_f32 v[82:83], v[58:59], v[78:79] op_sel_hi:[1,0]
	v_pk_mul_f32 v[64:65], v[78:79], v[64:65] op_sel_hi:[0,1]
	v_pk_mul_f32 v[66:67], v[78:79], v[66:67] op_sel_hi:[0,1]
	ds_read_b128 v[56:59], v35 offset:208
	v_pk_fma_f32 v[62:63], v[44:45], v[76:77], v[62:63] op_sel_hi:[1,0,1] neg_lo:[0,0,1] neg_hi:[0,0,1]
	v_pk_fma_f32 v[60:61], v[42:43], v[76:77], v[60:61] op_sel_hi:[1,0,1] neg_lo:[0,0,1] neg_hi:[0,0,1]
	ds_read_b128 v[42:45], v35 offset:224
	v_pk_fma_f32 v[70:71], v[76:77], v[54:55], v[70:71] op_sel_hi:[0,1,1] neg_lo:[0,0,1] neg_hi:[0,0,1]
	v_pk_fma_f32 v[68:69], v[76:77], v[52:53], v[68:69] op_sel_hi:[0,1,1] neg_lo:[0,0,1] neg_hi:[0,0,1]
	ds_read_b128 v[52:55], v35 offset:240
	v_pk_fma_f32 v[30:31], v[72:73], v[30:31], v[74:75] op_sel_hi:[1,1,0]
	ds_read_b128 v[72:75], v35 offset:144
	v_pk_fma_f32 v[78:79], v[40:41], v[76:77], v[82:83] op_sel_hi:[1,0,1] neg_lo:[0,0,1] neg_hi:[0,0,1]
	v_pk_fma_f32 v[80:81], v[38:39], v[76:77], v[80:81] op_sel_hi:[1,0,1] neg_lo:[0,0,1] neg_hi:[0,0,1]
	ds_read_b128 v[38:41], v35 offset:160
	v_pk_fma_f32 v[66:67], v[76:77], v[50:51], v[66:67] op_sel_hi:[0,1,1] neg_lo:[0,0,1] neg_hi:[0,0,1]
	v_pk_fma_f32 v[64:65], v[76:77], v[48:49], v[64:65] op_sel_hi:[0,1,1] neg_lo:[0,0,1] neg_hi:[0,0,1]
	ds_read_b128 v[48:51], v35 offset:176
	s_waitcnt lgkmcnt(6)
	v_pk_mul_f32 v[22:23], v[22:23], v[30:31] op_sel_hi:[1,0]
	v_pk_mul_f32 v[20:21], v[20:21], v[30:31] op_sel_hi:[1,0]
	s_waitcnt lgkmcnt(5)
	v_pk_mul_f32 v[58:59], v[30:31], v[58:59] op_sel_hi:[0,1]
	v_pk_mul_f32 v[56:57], v[30:31], v[56:57] op_sel_hi:[0,1]
	s_waitcnt lgkmcnt(4)
	v_pk_mul_f32 v[44:45], v[30:31], v[44:45] op_sel_hi:[0,1]
	v_pk_mul_f32 v[42:43], v[30:31], v[42:43] op_sel_hi:[0,1]
	s_waitcnt lgkmcnt(3)
	v_pk_mul_f32 v[54:55], v[30:31], v[54:55] op_sel_hi:[0,1]
	v_pk_mul_f32 v[30:31], v[30:31], v[52:53] op_sel_hi:[0,1]
	v_pk_fma_f32 v[16:17], v[16:17], v[28:29], v[20:21] op_sel_hi:[1,0,1] neg_lo:[0,0,1] neg_hi:[0,0,1]
	v_pk_fma_f32 v[18:19], v[18:19], v[28:29], v[22:23] op_sel_hi:[1,0,1] neg_lo:[0,0,1] neg_hi:[0,0,1]
	s_waitcnt lgkmcnt(2)
	v_pk_fma_f32 v[20:21], v[72:73], v[28:29], v[56:57] op_sel_hi:[1,0,1] neg_lo:[0,0,1] neg_hi:[0,0,1]
	v_pk_fma_f32 v[22:23], v[74:75], v[28:29], v[58:59] op_sel_hi:[1,0,1] neg_lo:[0,0,1] neg_hi:[0,0,1]
	s_waitcnt lgkmcnt(1)
	v_pk_fma_f32 v[38:39], v[28:29], v[38:39], v[42:43] op_sel_hi:[0,1,1] neg_lo:[0,0,1] neg_hi:[0,0,1]
	v_pk_fma_f32 v[40:41], v[28:29], v[40:41], v[44:45] op_sel_hi:[0,1,1] neg_lo:[0,0,1] neg_hi:[0,0,1]
	s_waitcnt lgkmcnt(0)
	v_pk_fma_f32 v[30:31], v[28:29], v[48:49], v[30:31] op_sel_hi:[0,1,1] neg_lo:[0,0,1] neg_hi:[0,0,1]
	v_pk_fma_f32 v[28:29], v[28:29], v[50:51], v[54:55] op_sel_hi:[0,1,1] neg_lo:[0,0,1] neg_hi:[0,0,1]
	v_pk_add_f32 v[12:13], v[12:13], v[80:81]
	v_pk_add_f32 v[14:15], v[14:15], v[78:79]
	v_pk_add_f32 v[8:9], v[8:9], v[60:61]
	v_pk_add_f32 v[10:11], v[10:11], v[62:63]
	v_pk_add_f32 v[4:5], v[4:5], v[64:65]
	v_pk_add_f32 v[6:7], v[6:7], v[66:67]
	v_pk_add_f32 v[0:1], v[0:1], v[68:69]
	v_pk_add_f32 v[2:3], v[2:3], v[70:71]
	v_add_u32_e32 v35, 0x100, v35
	v_pk_add_f32 v[14:15], v[14:15], v[18:19]
	v_pk_add_f32 v[12:13], v[12:13], v[16:17]
	v_pk_add_f32 v[10:11], v[10:11], v[22:23]
	v_pk_add_f32 v[8:9], v[8:9], v[20:21]
	v_pk_add_f32 v[6:7], v[6:7], v[40:41]
	v_pk_add_f32 v[4:5], v[4:5], v[38:39]
	v_pk_add_f32 v[2:3], v[2:3], v[28:29]
	v_pk_add_f32 v[0:1], v[0:1], v[30:31]
	v_and_b32_e32 v16, 0x3ffff00, v32
	v_lshlrev_b32_e32 v17, 4, v34
	v_or3_b32 v16, v17, v16, v33
	s_movk_i32 s0, 0x2000
	v_lshl_add_u32 v16, v16, 6, 0
	v_cmp_gt_i32_e32 vcc, s0, v32
	ds_write_b128 v16, v[12:15] offset:33792
	ds_write_b128 v16, v[8:11] offset:33808
	ds_write_b128 v16, v[4:7] offset:33824
	ds_write_b128 v16, v[0:3] offset:33840
	s_waitcnt lgkmcnt(0)
	s_barrier
	s_and_saveexec_b64 s[0:1], vcc
	s_cbranch_execz .LBB0_1453
	s_ashr_i32 s81, s80, 31
	s_lshl_b64 s[4:5], s[80:81], 18
	s_add_u32 s4, s93, s4
	v_readlane_b32 s24, v255, 0
	s_addc_u32 s5, s24, s5
	s_lshl_b64 s[24:25], s[80:81], 17
	v_readlane_b32 s29, v255, 2
	s_load_dwordx2 s[30:31], s[72:73], 0x98
	s_add_u32 s24, s29, s24
	v_readlane_b32 s29, v255, 4
	s_addc_u32 s25, s29, s25
	s_lshl_b32 s28, s28, 10
	s_ashr_i32 s29, s28, 31
	s_lshl_b64 s[28:29], s[28:29], 2
	s_waitcnt lgkmcnt(0)
	s_add_u32 s28, s30, s28
	s_addc_u32 s29, s31, s29
	s_lshl_b32 s30, s33, 6
	s_add_u32 s28, s28, s30
	s_movk_i32 s81, 0x600
	s_addc_u32 s29, s29, 0
	v_lshlrev_b32_e32 v4, 3, v32
	s_mov_b64 s[30:31], 0
	s_branch .LBB0_1405
